# phase 10: ds_bpermute xor-1/xor-2 shuffles replaced by DPP quad_perm moves (plus stash layout, dual-tile P1/P9)
# speedup vs baseline: 1.0913x; 1.0062x over previous
.LBB0_729:
	s_waitcnt vmcnt(0)
	s_barrier
	ds_write_b128 v98, v[48:51]
	ds_write_b128 v98, v[44:47] offset:4352
	ds_write_b128 v98, v[36:39] offset:8704
	ds_write_b128 v98, v[40:43] offset:13056
	ds_write_b128 v98, v[28:31] offset:17408
	ds_write_b128 v98, v[32:35] offset:21760
	ds_write_b128 v98, v[20:23] offset:26112
	ds_write_b128 v98, v[24:27] offset:30464
	s_waitcnt lgkmcnt(0)
	s_barrier
	ds_read_b128 v[20:23], v99
	ds_read_b128 v[24:27], v99 offset:4352
	ds_read_b128 v[28:31], v99 offset:8704
	ds_read_b128 v[32:35], v99 offset:13056
	ds_read_b128 v[36:39], v99 offset:17408
	ds_read_b128 v[40:43], v99 offset:21760
	ds_read_b128 v[44:47], v99 offset:26112
	ds_read_b128 v[48:51], v99 offset:30464
	s_waitcnt lgkmcnt(7)
	v_mfma_f32_16x16x32_bf16 v[20:23], v[16:19], v[20:23], 0
	s_and_b32 s24, s59, 7
	s_lshl_b32 s26, s24, 16
	s_add_u32 s26, s18, s26
	s_waitcnt lgkmcnt(6)
	v_mfma_f32_16x16x32_bf16 v[24:27], v[16:19], v[24:27], 0
	s_addc_u32 s27, s19, 0
	s_and_b32 s34, s3, 0xffffffc0
	s_lshl_b32 s24, s24, 9
	s_waitcnt lgkmcnt(5)
	v_mfma_f32_16x16x32_bf16 v[28:31], v[16:19], v[28:31], 0
	s_waitcnt lgkmcnt(4)
	v_mfma_f32_16x16x32_bf16 v[32:35], v[16:19], v[32:35], 0
	s_waitcnt lgkmcnt(3)
	v_mfma_f32_16x16x32_bf16 v[36:39], v[16:19], v[36:39], 0
	s_waitcnt lgkmcnt(2)
	v_mfma_f32_16x16x32_bf16 v[40:43], v[16:19], v[40:43], 0
	s_waitcnt lgkmcnt(1)
	v_mfma_f32_16x16x32_bf16 v[44:47], v[16:19], v[44:47], 0
	s_waitcnt lgkmcnt(0)
	v_mfma_f32_16x16x32_bf16 v[16:19], v[16:19], v[48:51], 0
	ds_read_b128 v[48:51], v88 offset:64
	ds_read_b128 v[62:65], v88 offset:128
	s_waitcnt lgkmcnt(1)
	v_mfma_f32_16x16x32_bf16 v[20:23], v[12:15], v[48:51], v[20:23]
	ds_read_b128 v[48:51], v89 offset:64
	ds_read_b128 v[66:69], v88 offset:192
	s_waitcnt lgkmcnt(2)
	v_mfma_f32_16x16x32_bf16 v[20:23], v[8:11], v[62:65], v[20:23]
	s_waitcnt lgkmcnt(1)
	v_mfma_f32_16x16x32_bf16 v[24:27], v[12:15], v[48:51], v[24:27]
	ds_read_b128 v[48:51], v90 offset:64
	ds_read_b128 v[72:75], v91 offset:64
	ds_read_b128 v[76:79], v90 offset:128
	s_waitcnt lgkmcnt(2)
	v_mfma_f32_16x16x32_bf16 v[28:31], v[12:15], v[48:51], v[28:31]
	ds_read_b128 v[48:51], v92 offset:64
	ds_read_b128 v[102:105], v92 offset:128
	ds_read_b128 v[106:109], v90 offset:192
	v_mfma_f32_16x16x32_bf16 v[20:23], v[4:7], v[66:69], v[20:23]
	s_waitcnt lgkmcnt(4)
	v_mfma_f32_16x16x32_bf16 v[32:35], v[12:15], v[72:75], v[32:35]
	ds_read_b128 v[72:75], v94 offset:64
	ds_read_b128 v[110:113], v94 offset:128
	ds_read_b128 v[114:117], v89 offset:128
	ds_read_b128 v[118:121], v89 offset:192
	s_nop 1
	v_not_b32_e32 v59, v20
	v_or_b32_e32 v61, 0x80000000, v20
	s_waitcnt lgkmcnt(6)
	v_mfma_f32_16x16x32_bf16 v[36:39], v[12:15], v[48:51], v[36:39]
	ds_read_b128 v[48:51], v91 offset:128
	ds_read_b128 v[122:125], v91 offset:192
	ds_read_b128 v[126:129], v93 offset:64
	ds_read_b128 v[130:133], v92 offset:192
	ds_read_b128 v[62:65], v93 offset:128
	ds_read_b128 v[134:137], v93 offset:192
	ds_read_b128 v[138:141], v95 offset:64
	ds_read_b128 v[146:149], v94 offset:192
	v_cmp_gt_i32_e32 vcc, 0, v20
	s_waitcnt lgkmcnt(5)
	v_mfma_f32_16x16x32_bf16 v[40:43], v[12:15], v[126:129], v[40:43]
	v_cndmask_b32_e32 v20, v61, v59, vcc
	v_and_b32_e32 v20, 0xffffff80, v20
	v_bitop3_b32 v59, v71, s44, v20 bitop3:0x36
	v_mfma_f32_16x16x32_bf16 v[44:47], v[12:15], v[72:75], v[44:47]
	v_not_b32_e32 v20, v21
	v_cmp_gt_i32_e32 vcc, 0, v21
	ds_read_b128 v[66:69], v95 offset:128
	ds_read_b128 v[150:153], v95 offset:192
	s_waitcnt lgkmcnt(3)
	v_mfma_f32_16x16x32_bf16 v[12:15], v[12:15], v[138:141], v[16:19]
	s_nop 2
	v_or_b32_e32 v16, 0x80000000, v21
	v_cndmask_b32_e32 v20, v16, v20, vcc
	v_mfma_f32_16x16x32_bf16 v[16:19], v[8:11], v[114:117], v[24:27]
	v_and_b32_e32 v20, 0xffffff80, v20
	v_bitop3_b32 v61, v71, s44, v20 bitop3:0x36
	v_not_b32_e32 v20, v22
	v_or_b32_e32 v21, 0x80000000, v22
	v_cmp_gt_i32_e32 vcc, 0, v22
	v_mfma_f32_16x16x32_bf16 v[16:19], v[4:7], v[118:121], v[16:19]
	s_nop 0
	v_cndmask_b32_e32 v20, v21, v20, vcc
	v_and_b32_e32 v20, 0xffffff80, v20
	v_mfma_f32_16x16x32_bf16 v[24:27], v[8:11], v[76:79], v[28:31]
	v_or_b32_e32 v21, 0x80000000, v23
	v_cmp_gt_i32_e32 vcc, 0, v23
	v_add_u32_e32 v77, 0x8800, v100
	v_mfma_f32_16x16x32_bf16 v[28:31], v[8:11], v[48:51], v[32:35]
	v_bitop3_b32 v48, v71, s44, v20 bitop3:0x36
	v_not_b32_e32 v20, v23
	v_cndmask_b32_e32 v20, v21, v20, vcc
	v_mfma_f32_16x16x32_bf16 v[32:35], v[8:11], v[102:105], v[36:39]
	v_cmp_gt_i32_e32 vcc, 0, v16
	v_and_b32_e32 v20, 0xffffff80, v20
	v_bitop3_b32 v49, v71, s44, v20 bitop3:0x36
	v_not_b32_e32 v36, v16
	v_or_b32_e32 v37, 0x80000000, v16
	v_cndmask_b32_e32 v16, v37, v36, vcc
	v_and_b32_e32 v16, 0xffffff80, v16
	v_bitop3_b32 v16, v71, s45, v16 bitop3:0x36
	v_mfma_f32_16x16x32_bf16 v[20:23], v[8:11], v[62:65], v[40:43]
	ds_write2_b32 v77, v59, v16 offset1:16
	v_not_b32_e32 v16, v17
	v_cmp_gt_i32_e32 vcc, 0, v17
	v_or_b32_e32 v40, 0x80000000, v17
	v_or_b32_e32 v17, 0x80000000, v18
	v_cndmask_b32_e32 v16, v40, v16, vcc
	v_and_b32_e32 v16, 0xffffff80, v16
	v_bitop3_b32 v16, v71, s45, v16 bitop3:0x36
	ds_write2_b32 v77, v61, v16 offset0:132 offset1:148
	v_not_b32_e32 v16, v18
	v_cmp_gt_i32_e32 vcc, 0, v18
	v_mfma_f32_16x16x32_bf16 v[36:39], v[8:11], v[110:113], v[44:47]
	v_add_u32_e32 v78, 0x8c00, v100
	v_cndmask_b32_e32 v16, v17, v16, vcc
	v_and_b32_e32 v16, 0xffffff80, v16
	s_waitcnt lgkmcnt(3)
	v_mfma_f32_16x16x32_bf16 v[8:11], v[8:11], v[66:69], v[12:15]
	v_bitop3_b32 v16, v71, s45, v16 bitop3:0x36
	ds_write2_b32 v78, v48, v16 offset0:8 offset1:24
	v_not_b32_e32 v16, v19
	v_mfma_f32_16x16x32_bf16 v[12:15], v[4:7], v[106:109], v[24:27]
	v_or_b32_e32 v17, 0x80000000, v19
	v_cmp_gt_i32_e32 vcc, 0, v19
	v_mov_b32_e32 v59, v53
	v_mfma_f32_16x16x32_bf16 v[24:27], v[4:7], v[122:125], v[28:31]
	v_mov_b32_e32 v61, v53
	v_mfma_f32_16x16x32_bf16 v[28:31], v[4:7], v[130:133], v[32:35]
	v_mfma_f32_16x16x32_bf16 v[20:23], v[4:7], v[134:137], v[20:23]
	v_mfma_f32_16x16x32_bf16 v[32:35], v[4:7], v[146:149], v[36:39]
	s_waitcnt lgkmcnt(3)
	v_mfma_f32_16x16x32_bf16 v[4:7], v[4:7], v[150:153], v[8:11]
	s_nop 2
	v_cndmask_b32_e32 v8, v17, v16, vcc
	v_and_b32_e32 v8, 0xffffff80, v8
	v_bitop3_b32 v8, v71, s45, v8 bitop3:0x36
	ds_write2_b32 v78, v49, v8 offset0:140 offset1:156
	v_not_b32_e32 v8, v12
	v_or_b32_e32 v9, 0x80000000, v12
	v_cmp_gt_i32_e32 vcc, 0, v12
	v_or_b32_e32 v10, 0x80000000, v13
	v_or_b32_e32 v11, 0x80000000, v14
	v_cndmask_b32_e32 v8, v9, v8, vcc
	v_not_b32_e32 v9, v13
	v_cmp_gt_i32_e32 vcc, 0, v13
	v_or_b32_e32 v12, 0x80000000, v15
	v_or_b32_e32 v13, 0x80000000, v24
	v_cndmask_b32_e32 v9, v10, v9, vcc
	v_not_b32_e32 v10, v14
	v_cmp_gt_i32_e32 vcc, 0, v14
	v_and_b32_e32 v8, 0xffffff80, v8
	v_bitop3_b32 v8, v71, s48, v8 bitop3:0x36
	v_cndmask_b32_e32 v10, v11, v10, vcc
	v_not_b32_e32 v11, v15
	v_cmp_gt_i32_e32 vcc, 0, v15
	v_and_b32_e32 v9, 0xffffff80, v9
	v_bitop3_b32 v9, v71, s48, v9 bitop3:0x36
	v_cndmask_b32_e32 v11, v12, v11, vcc
	v_not_b32_e32 v12, v24
	v_cmp_gt_i32_e32 vcc, 0, v24
	v_and_b32_e32 v10, 0xffffff80, v10
	v_bitop3_b32 v10, v71, s48, v10 bitop3:0x36
	v_cndmask_b32_e32 v12, v13, v12, vcc
	v_and_b32_e32 v12, 0xffffff80, v12
	v_bitop3_b32 v12, v71, s49, v12 bitop3:0x36
	ds_write2_b32 v77, v8, v12 offset0:32 offset1:48
	v_not_b32_e32 v8, v25
	v_or_b32_e32 v12, 0x80000000, v25
	v_cmp_gt_i32_e32 vcc, 0, v25
	v_and_b32_e32 v11, 0xffffff80, v11
	v_bitop3_b32 v11, v71, s48, v11 bitop3:0x36
	v_cndmask_b32_e32 v8, v12, v8, vcc
	v_and_b32_e32 v8, 0xffffff80, v8
	v_bitop3_b32 v8, v71, s49, v8 bitop3:0x36
	ds_write2_b32 v77, v9, v8 offset0:164 offset1:180
	v_not_b32_e32 v8, v26
	v_or_b32_e32 v9, 0x80000000, v26
	v_cmp_gt_i32_e32 vcc, 0, v26
	v_or_b32_e32 v12, 0x80000000, v31
	v_or_b32_e32 v13, 0x80000000, v20
	v_cndmask_b32_e32 v8, v9, v8, vcc
	v_and_b32_e32 v8, 0xffffff80, v8
	v_bitop3_b32 v8, v71, s49, v8 bitop3:0x36
	ds_write2_b32 v78, v10, v8 offset0:40 offset1:56
	v_not_b32_e32 v8, v27
	v_or_b32_e32 v9, 0x80000000, v27
	v_cmp_gt_i32_e32 vcc, 0, v27
	v_or_b32_e32 v10, 0x80000000, v29
	s_nop 0
	v_cndmask_b32_e32 v8, v9, v8, vcc
	v_and_b32_e32 v8, 0xffffff80, v8
	v_bitop3_b32 v8, v71, s49, v8 bitop3:0x36
	ds_write2_b32 v78, v11, v8 offset0:172 offset1:188
	v_not_b32_e32 v8, v28
	v_or_b32_e32 v9, 0x80000000, v28
	v_cmp_gt_i32_e32 vcc, 0, v28
	v_or_b32_e32 v11, 0x80000000, v30
	s_nop 0
	v_cndmask_b32_e32 v8, v9, v8, vcc
	v_not_b32_e32 v9, v29
	v_cmp_gt_i32_e32 vcc, 0, v29
	v_and_b32_e32 v8, 0xffffff80, v8
	v_bitop3_b32 v8, v71, 63, v8 bitop3:0x36
	v_cndmask_b32_e32 v9, v10, v9, vcc
	v_not_b32_e32 v10, v30
	v_cmp_gt_i32_e32 vcc, 0, v30
	v_and_b32_e32 v9, 0xffffff80, v9
	v_bitop3_b32 v9, v71, 63, v9 bitop3:0x36
	v_cndmask_b32_e32 v10, v11, v10, vcc
	v_not_b32_e32 v11, v31
	v_cmp_gt_i32_e32 vcc, 0, v31
	v_and_b32_e32 v10, 0xffffff80, v10
	v_bitop3_b32 v10, v71, 63, v10 bitop3:0x36
	v_cndmask_b32_e32 v11, v12, v11, vcc
	v_not_b32_e32 v12, v20
	v_cmp_gt_i32_e32 vcc, 0, v20
	v_and_b32_e32 v11, 0xffffff80, v11
	v_bitop3_b32 v11, v71, 63, v11 bitop3:0x36
	v_cndmask_b32_e32 v12, v13, v12, vcc
	v_and_b32_e32 v12, 0xffffff80, v12
	v_bitop3_b32 v12, v71, 47, v12 bitop3:0x36
	ds_write2_b32 v77, v8, v12 offset0:64 offset1:80
	v_not_b32_e32 v8, v21
	v_or_b32_e32 v12, 0x80000000, v21
	v_cmp_gt_i32_e32 vcc, 0, v21
	v_or_b32_e32 v13, 0x80000000, v4
	s_nop 0
	v_cndmask_b32_e32 v8, v12, v8, vcc
	v_and_b32_e32 v8, 0xffffff80, v8
	v_bitop3_b32 v8, v71, 47, v8 bitop3:0x36
	ds_write2_b32 v77, v9, v8 offset0:196 offset1:212
	v_not_b32_e32 v8, v22
	v_or_b32_e32 v9, 0x80000000, v22
	v_cmp_gt_i32_e32 vcc, 0, v22
	v_or_b32_e32 v12, 0x80000000, v35
	s_nop 0
	v_cndmask_b32_e32 v8, v9, v8, vcc
	v_and_b32_e32 v8, 0xffffff80, v8
	v_bitop3_b32 v8, v71, 47, v8 bitop3:0x36
	ds_write2_b32 v78, v10, v8 offset0:72 offset1:88
	v_not_b32_e32 v8, v23
	v_or_b32_e32 v9, 0x80000000, v23
	v_cmp_gt_i32_e32 vcc, 0, v23
	v_or_b32_e32 v10, 0x80000000, v33
	s_nop 0
	v_cndmask_b32_e32 v8, v9, v8, vcc
	v_and_b32_e32 v8, 0xffffff80, v8
	v_bitop3_b32 v8, v71, 47, v8 bitop3:0x36
	ds_write2_b32 v78, v11, v8 offset0:204 offset1:220
	v_not_b32_e32 v8, v32
	v_or_b32_e32 v9, 0x80000000, v32
	v_cmp_gt_i32_e32 vcc, 0, v32
	v_or_b32_e32 v11, 0x80000000, v34
	s_nop 0
	v_cndmask_b32_e32 v8, v9, v8, vcc
	v_not_b32_e32 v9, v33
	v_cmp_gt_i32_e32 vcc, 0, v33
	v_and_b32_e32 v8, 0xffffff80, v8
	v_bitop3_b32 v8, v71, 31, v8 bitop3:0x36
	v_cndmask_b32_e32 v9, v10, v9, vcc
	v_not_b32_e32 v10, v34
	v_cmp_gt_i32_e32 vcc, 0, v34
	v_and_b32_e32 v9, 0xffffff80, v9
	v_bitop3_b32 v9, v71, 31, v9 bitop3:0x36
	v_cndmask_b32_e32 v10, v11, v10, vcc
	v_not_b32_e32 v11, v35
	v_cmp_gt_i32_e32 vcc, 0, v35
	v_and_b32_e32 v10, 0xffffff80, v10
	v_bitop3_b32 v10, v71, 31, v10 bitop3:0x36
	v_cndmask_b32_e32 v11, v12, v11, vcc
	v_not_b32_e32 v12, v4
	v_cmp_gt_i32_e32 vcc, 0, v4
	v_and_b32_e32 v11, 0xffffff80, v11
	v_bitop3_b32 v11, v71, 31, v11 bitop3:0x36
	v_cndmask_b32_e32 v4, v13, v12, vcc
	v_and_b32_e32 v4, 0xffffff80, v4
	v_bitop3_b32 v4, v71, 15, v4 bitop3:0x36
	ds_write2_b32 v77, v8, v4 offset0:96 offset1:112
	v_not_b32_e32 v4, v5
	v_or_b32_e32 v8, 0x80000000, v5
	v_cmp_gt_i32_e32 vcc, 0, v5
	v_or_b32_e32 v5, 0x80000000, v6
	s_nop 0
	v_cndmask_b32_e32 v4, v8, v4, vcc
	v_and_b32_e32 v4, 0xffffff80, v4
	v_bitop3_b32 v4, v71, 15, v4 bitop3:0x36
	ds_write2_b32 v77, v9, v4 offset0:228 offset1:244
	v_not_b32_e32 v4, v6
	v_cmp_gt_i32_e32 vcc, 0, v6
	s_nop 1
	v_cndmask_b32_e32 v4, v5, v4, vcc
	v_and_b32_e32 v4, 0xffffff80, v4
	v_bitop3_b32 v4, v71, 15, v4 bitop3:0x36
	ds_write2_b32 v78, v10, v4 offset0:104 offset1:120
	v_not_b32_e32 v4, v7
	v_or_b32_e32 v5, 0x80000000, v7
	v_cmp_gt_i32_e32 vcc, 0, v7
	s_nop 1
	v_cndmask_b32_e32 v4, v5, v4, vcc
	v_and_b32_e32 v4, 0xffffff80, v4
	v_bitop3_b32 v4, v71, 15, v4 bitop3:0x36
	ds_write2_b32 v78, v11, v4 offset0:236 offset1:252
	v_lshl_add_u64 v[4:5], s[26:27], 0, v[52:53]
	v_lshl_add_u64 v[4:5], v[4:5], 0, v[58:59]
	v_add_co_u32_e32 v6, vcc, s50, v4
	s_waitcnt lgkmcnt(0)
	s_nop 0
	v_addc_co_u32_e32 v7, vcc, 0, v5, vcc
	s_barrier
	global_load_dwordx4 v[16:19], v[6:7], off offset:-4096
	global_load_dwordx4 v[20:23], v[6:7], off
	v_add_co_u32_e32 v6, vcc, s51, v4
	s_nop 1
	v_addc_co_u32_e32 v7, vcc, 0, v5, vcc
	global_load_dwordx4 v[24:27], v[6:7], off offset:-4096
	global_load_dwordx4 v[28:31], v[6:7], off
	v_add_co_u32_e32 v6, vcc, s56, v4
	s_nop 1
	v_addc_co_u32_e32 v7, vcc, 0, v5, vcc
	v_add_co_u32_e32 v4, vcc, s57, v4
	global_load_dwordx4 v[36:39], v[6:7], off offset:-4096
	global_load_dwordx4 v[40:43], v[6:7], off
	v_addc_co_u32_e32 v5, vcc, 0, v5, vcc
	global_load_dwordx4 v[44:47], v[4:5], off offset:-4096
	global_load_dwordx4 v[48:51], v[4:5], off
	v_add_u32_e32 v4, s34, v84
	v_ashrrev_i32_e32 v5, 31, v4
	v_lshlrev_b64 v[4:5], 12, v[4:5]
	v_lshl_add_u64 v[4:5], s[16:17], 0, v[4:5]
	v_lshl_add_u64 v[4:5], v[4:5], 0, s[24:25]
	v_lshl_add_u64 v[4:5], v[4:5], 0, v[60:61]
	global_load_dwordx4 v[32:35], v[4:5], off offset:256
	global_load_dwordx4 v[12:15], v[4:5], off offset:320
	global_load_dwordx4 v[8:11], v[4:5], off offset:384
	s_nop 0
	global_load_dwordx4 v[4:7], v[4:5], off offset:448
	s_and_b32 s81, s80, 0x3ff
	s_lshl_b32 s81, s81, 16
	s_cmp_lt_u32 s80, 0x400
	s_cselect_b32 s82, s88, s96
	s_cselect_b32 s83, s89, s97
	s_mov_b32 s86, 0x42800000
	s_cselect_b32 s86, 0x43800000, s86
	s_cselect_b32 s87, 0, 0x400
	s_add_u32 s82, s82, s81
	s_addc_u32 s83, s83, 0
	s_lshr_b32 s81, s81, 1
	s_add_u32 s81, s81, s87
	s_add_u32 s84, s98, s81
	s_addc_u32 s85, s99, 0
	global_load_dwordx4 v[170:173], v234, s[82:83]
	s_add_u32 s82, s82, 0x1000
	s_addc_u32 s83, s83, 0
	global_load_dwordx4 v[174:177], v234, s[82:83]
	s_add_u32 s82, s82, 0x1000
	s_addc_u32 s83, s83, 0
	global_load_dwordx4 v[178:181], v234, s[82:83]
	s_add_u32 s82, s82, 0x1000
	s_addc_u32 s83, s83, 0
	global_load_dwordx4 v[182:185], v234, s[82:83]
	s_add_u32 s82, s82, 0x1000
	s_addc_u32 s83, s83, 0
	global_load_dwordx4 v[186:189], v234, s[82:83]
	s_add_u32 s82, s82, 0x1000
	s_addc_u32 s83, s83, 0
	global_load_dwordx4 v[190:193], v234, s[82:83]
	s_add_u32 s82, s82, 0x1000
	s_addc_u32 s83, s83, 0
	global_load_dwordx4 v[194:197], v234, s[82:83]
	s_add_u32 s82, s82, 0x1000
	s_addc_u32 s83, s83, 0
	global_load_dwordx4 v[198:201], v234, s[82:83]
	s_add_u32 s82, s82, 0x1000
	s_addc_u32 s83, s83, 0
	global_load_dwordx4 v[202:205], v234, s[82:83]
	s_add_u32 s82, s82, 0x1000
	s_addc_u32 s83, s83, 0
	global_load_dwordx4 v[206:209], v234, s[82:83]
	s_add_u32 s82, s82, 0x1000
	s_addc_u32 s83, s83, 0
	global_load_dwordx4 v[210:213], v234, s[82:83]
	s_add_u32 s82, s82, 0x1000
	s_addc_u32 s83, s83, 0
	global_load_dwordx4 v[214:217], v234, s[82:83]
	s_add_u32 s82, s82, 0x1000
	s_addc_u32 s83, s83, 0
	global_load_dwordx4 v[218:221], v234, s[82:83]
	s_add_u32 s82, s82, 0x1000
	s_addc_u32 s83, s83, 0
	global_load_dwordx4 v[222:225], v234, s[82:83]
	s_add_u32 s82, s82, 0x1000
	s_addc_u32 s83, s83, 0
	global_load_dwordx4 v[226:229], v234, s[82:83]
	s_add_u32 s82, s82, 0x1000
	s_addc_u32 s83, s83, 0
	global_load_dwordx4 v[230:233], v234, s[82:83]
	ds_read_b128 v[62:65], v87 offset:34816
	ds_read_b128 v[66:69], v87 offset:34832
	ds_read_b128 v[72:75], v87 offset:34848
	ds_read_b128 v[102:105], v87 offset:34864
	s_waitcnt lgkmcnt(3)
	v_max_u32_e32 v59, v62, v63
	s_waitcnt lgkmcnt(2)
	v_max_u32_e32 v62, v68, v69
	v_max_u32_e32 v61, v64, v65
	v_max3_u32 v62, v66, v67, v62
	v_max3_u32 v59, v59, v61, v62
	ds_read_b128 v[62:65], v87 offset:34880
	s_waitcnt lgkmcnt(2)
	v_max_u32_e32 v61, v74, v75
	s_waitcnt lgkmcnt(1)
	v_max_u32_e32 v66, v104, v105
	v_max3_u32 v61, v72, v73, v61
	v_max3_u32 v70, v102, v103, v66
	ds_read_b128 v[66:69], v87 offset:34896
	v_max3_u32 v59, v59, v61, v70
	s_waitcnt lgkmcnt(1)
	v_max_u32_e32 v61, v64, v65
	v_max3_u32 v61, v62, v63, v61
	ds_read_b128 v[62:65], v87 offset:34912
	ds_read_b128 v[72:75], v87 offset:34928
	s_waitcnt lgkmcnt(2)
	v_max_u32_e32 v68, v68, v69
	v_max3_u32 v66, v66, v67, v68
	v_max3_u32 v59, v59, v61, v66
	s_waitcnt lgkmcnt(1)
	v_max_u32_e32 v61, v64, v65
	v_max3_u32 v61, v62, v63, v61
	s_waitcnt lgkmcnt(0)
	v_max_u32_e32 v62, v74, v75
	v_max3_u32 v62, v72, v73, v62
	v_max3_u32 v61, v59, v61, v62
	s_nop 1
	v_mov_b32_dpp v59, v61 quad_perm:[1,0,3,2] row_mask:0xf bank_mask:0xf
	s_waitcnt lgkmcnt(0)
	v_max_u32_e32 v59, v61, v59
	s_nop 1
	v_mov_b32_dpp v62, v59 quad_perm:[2,3,0,1] row_mask:0xf bank_mask:0xf
	s_waitcnt lgkmcnt(0)
	v_max_u32_e32 v64, v59, v62
	v_not_b32_e32 v59, v64
	v_bfe_u32 v59, v59, 5, 2
	v_cmp_eq_u32_e32 vcc, v59, v83
	s_and_saveexec_b64 s[26:27], vcc
	s_cbranch_execz .LBB0_731
	v_bitop3_b32 v59, v64, s44, v64 bitop3:0xc
	v_lshl_add_u32 v61, v59, 2, v85
	ds_write_b32 v61, v53 offset:34816
	ds_write_b8 v86, v59
	ds_read_b128 v[66:69], v87 offset:34816
	ds_read_b128 v[72:75], v87 offset:34832
	ds_read_b128 v[102:105], v87 offset:34848
	ds_read_b128 v[106:109], v87 offset:34864
	ds_read_b128 v[110:113], v87 offset:34880
	ds_read_b128 v[114:117], v87 offset:34896
	ds_read_b128 v[118:121], v87 offset:34912
	ds_read_b128 v[122:125], v87 offset:34928
	s_waitcnt lgkmcnt(6)
	v_max_u32_e32 v62, v74, v75
	v_max_u32_e32 v59, v66, v67
	v_max_u32_e32 v61, v68, v69
	v_max3_u32 v62, v72, v73, v62
	v_max3_u32 v59, v59, v61, v62
	s_waitcnt lgkmcnt(5)
	v_max_u32_e32 v61, v104, v105
	s_waitcnt lgkmcnt(4)
	v_max_u32_e32 v62, v108, v109
	v_max3_u32 v61, v102, v103, v61
	v_max3_u32 v62, v106, v107, v62
	v_max3_u32 v59, v59, v61, v62
	s_waitcnt lgkmcnt(3)
	v_max_u32_e32 v61, v112, v113
	s_waitcnt lgkmcnt(2)
	v_max_u32_e32 v62, v116, v117
	v_max3_u32 v61, v110, v111, v61
	v_max3_u32 v62, v114, v115, v62
	v_max3_u32 v59, v59, v61, v62
	s_waitcnt lgkmcnt(1)
	v_max_u32_e32 v61, v120, v121
	s_waitcnt lgkmcnt(0)
	v_max_u32_e32 v62, v124, v125
	v_max3_u32 v61, v118, v119, v61
	v_max3_u32 v62, v122, v123, v62
	v_max3_u32 v61, v59, v61, v62
.LBB0_731:
	s_or_b64 exec, exec, s[26:27]
	s_nop 1
	v_mov_b32_dpp v59, v61 quad_perm:[1,0,3,2] row_mask:0xf bank_mask:0xf
	s_waitcnt lgkmcnt(0)
	v_max_u32_e32 v59, v61, v59
	s_nop 1
	v_mov_b32_dpp v62, v59 quad_perm:[2,3,0,1] row_mask:0xf bank_mask:0xf
	s_waitcnt lgkmcnt(0)
	v_max_u32_e32 v62, v59, v62
	v_not_b32_e32 v59, v62
	v_bfe_u32 v59, v59, 5, 2
	v_cmp_eq_u32_e32 vcc, v59, v83
	s_and_saveexec_b64 s[26:27], vcc
	s_cbranch_execz .LBB0_733
	v_bitop3_b32 v59, v62, s44, v62 bitop3:0xc
	v_lshl_add_u32 v61, v59, 2, v85
	ds_write_b32 v61, v53 offset:34816
	ds_write_b8 v86, v59 offset:1
	ds_read_b128 v[66:69], v87 offset:34816
	ds_read_b128 v[72:75], v87 offset:34832
	ds_read_b128 v[102:105], v87 offset:34848
	ds_read_b128 v[106:109], v87 offset:34864
	ds_read_b128 v[110:113], v87 offset:34880
	ds_read_b128 v[114:117], v87 offset:34896
	ds_read_b128 v[118:121], v87 offset:34912
	ds_read_b128 v[122:125], v87 offset:34928
	s_waitcnt lgkmcnt(6)
	v_max_u32_e32 v63, v74, v75
	v_max_u32_e32 v59, v66, v67
	v_max_u32_e32 v61, v68, v69
	v_max3_u32 v63, v72, v73, v63
	v_max3_u32 v59, v59, v61, v63
	s_waitcnt lgkmcnt(5)
	v_max_u32_e32 v61, v104, v105
	s_waitcnt lgkmcnt(4)
	v_max_u32_e32 v63, v108, v109
	v_max3_u32 v61, v102, v103, v61
	v_max3_u32 v63, v106, v107, v63
	v_max3_u32 v59, v59, v61, v63
	s_waitcnt lgkmcnt(3)
	v_max_u32_e32 v61, v112, v113
	s_waitcnt lgkmcnt(2)
	v_max_u32_e32 v63, v116, v117
	v_max3_u32 v61, v110, v111, v61
	v_max3_u32 v63, v114, v115, v63
	v_max3_u32 v59, v59, v61, v63
	s_waitcnt lgkmcnt(1)
	v_max_u32_e32 v61, v120, v121
	s_waitcnt lgkmcnt(0)
	v_max_u32_e32 v63, v124, v125
	v_max3_u32 v61, v118, v119, v61
	v_max3_u32 v63, v122, v123, v63
	v_max3_u32 v61, v59, v61, v63
.LBB0_733:
	s_or_b64 exec, exec, s[26:27]
	s_nop 1
	v_mov_b32_dpp v59, v61 quad_perm:[1,0,3,2] row_mask:0xf bank_mask:0xf
	s_waitcnt lgkmcnt(0)
	v_max_u32_e32 v59, v61, v59
	s_nop 1
	v_mov_b32_dpp v63, v59 quad_perm:[2,3,0,1] row_mask:0xf bank_mask:0xf
	s_waitcnt lgkmcnt(0)
	v_max_u32_e32 v65, v59, v63
	v_not_b32_e32 v59, v65
	v_bfe_u32 v59, v59, 5, 2
	v_cmp_eq_u32_e32 vcc, v59, v83
	s_and_saveexec_b64 s[26:27], vcc
	s_cbranch_execz .LBB0_735
	v_bitop3_b32 v59, v65, s44, v65 bitop3:0xc
	v_lshl_add_u32 v61, v59, 2, v85
	ds_write_b32 v61, v53 offset:34816
	ds_write_b8 v86, v59 offset:2
	ds_read_b128 v[66:69], v87 offset:34816
	ds_read_b128 v[72:75], v87 offset:34832
	ds_read_b128 v[102:105], v87 offset:34848
	ds_read_b128 v[106:109], v87 offset:34864
	ds_read_b128 v[110:113], v87 offset:34880
	ds_read_b128 v[114:117], v87 offset:34896
	ds_read_b128 v[118:121], v87 offset:34912
	ds_read_b128 v[122:125], v87 offset:34928
	s_waitcnt lgkmcnt(6)
	v_max_u32_e32 v63, v74, v75
	v_max_u32_e32 v59, v66, v67
	v_max_u32_e32 v61, v68, v69
	v_max3_u32 v63, v72, v73, v63
	v_max3_u32 v59, v59, v61, v63
	s_waitcnt lgkmcnt(5)
	v_max_u32_e32 v61, v104, v105
	s_waitcnt lgkmcnt(4)
	v_max_u32_e32 v63, v108, v109
	v_max3_u32 v61, v102, v103, v61
	v_max3_u32 v63, v106, v107, v63
	v_max3_u32 v59, v59, v61, v63
	s_waitcnt lgkmcnt(3)
	v_max_u32_e32 v61, v112, v113
	s_waitcnt lgkmcnt(2)
	v_max_u32_e32 v63, v116, v117
	v_max3_u32 v61, v110, v111, v61
	v_max3_u32 v63, v114, v115, v63
	v_max3_u32 v59, v59, v61, v63
	s_waitcnt lgkmcnt(1)
	v_max_u32_e32 v61, v120, v121
	s_waitcnt lgkmcnt(0)
	v_max_u32_e32 v63, v124, v125
	v_max3_u32 v61, v118, v119, v61
	v_max3_u32 v63, v122, v123, v63
	v_max3_u32 v61, v59, v61, v63
.LBB0_735:
	s_or_b64 exec, exec, s[26:27]
	s_nop 1
	v_mov_b32_dpp v59, v61 quad_perm:[1,0,3,2] row_mask:0xf bank_mask:0xf
	s_waitcnt lgkmcnt(0)
	v_max_u32_e32 v59, v61, v59
	s_nop 1
	v_mov_b32_dpp v63, v59 quad_perm:[2,3,0,1] row_mask:0xf bank_mask:0xf
	s_waitcnt lgkmcnt(0)
	v_max_u32_e32 v66, v59, v63
	v_not_b32_e32 v59, v66
	v_bfe_u32 v59, v59, 5, 2
	v_cmp_eq_u32_e32 vcc, v59, v83
	s_and_saveexec_b64 s[26:27], vcc
	s_cbranch_execz .LBB0_737
	v_bitop3_b32 v59, v66, s44, v66 bitop3:0xc
	v_lshl_add_u32 v61, v59, 2, v85
	ds_write_b32 v61, v53 offset:34816
	ds_write_b8 v86, v59 offset:3
	ds_read_b128 v[72:75], v87 offset:34816
	ds_read_b128 v[102:105], v87 offset:34832
	ds_read_b128 v[106:109], v87 offset:34848
	ds_read_b128 v[110:113], v87 offset:34864
	ds_read_b128 v[114:117], v87 offset:34880
	ds_read_b128 v[118:121], v87 offset:34896
	ds_read_b128 v[122:125], v87 offset:34912
	ds_read_b128 v[126:129], v87 offset:34928
	s_waitcnt lgkmcnt(6)
	v_max_u32_e32 v63, v104, v105
	v_max_u32_e32 v59, v72, v73
	v_max_u32_e32 v61, v74, v75
	v_max3_u32 v63, v102, v103, v63
	v_max3_u32 v59, v59, v61, v63
	s_waitcnt lgkmcnt(5)
	v_max_u32_e32 v61, v108, v109
	s_waitcnt lgkmcnt(4)
	v_max_u32_e32 v63, v112, v113
	v_max3_u32 v61, v106, v107, v61
	v_max3_u32 v63, v110, v111, v63
	v_max3_u32 v59, v59, v61, v63
	s_waitcnt lgkmcnt(3)
	v_max_u32_e32 v61, v116, v117
	s_waitcnt lgkmcnt(2)
	v_max_u32_e32 v63, v120, v121
	v_max3_u32 v61, v114, v115, v61
	v_max3_u32 v63, v118, v119, v63
	v_max3_u32 v59, v59, v61, v63
	s_waitcnt lgkmcnt(1)
	v_max_u32_e32 v61, v124, v125
	s_waitcnt lgkmcnt(0)
	v_max_u32_e32 v63, v128, v129
	v_max3_u32 v61, v122, v123, v61
	v_max3_u32 v63, v126, v127, v63
	v_max3_u32 v61, v59, v61, v63
.LBB0_737:
	s_or_b64 exec, exec, s[26:27]
	s_nop 1
	v_mov_b32_dpp v59, v61 quad_perm:[1,0,3,2] row_mask:0xf bank_mask:0xf
	s_waitcnt lgkmcnt(0)
	v_max_u32_e32 v59, v61, v59
	s_nop 1
	v_mov_b32_dpp v63, v59 quad_perm:[2,3,0,1] row_mask:0xf bank_mask:0xf
	s_waitcnt lgkmcnt(0)
	v_max_u32_e32 v67, v59, v63
	v_not_b32_e32 v59, v67
	v_bfe_u32 v59, v59, 5, 2
	v_cmp_eq_u32_e32 vcc, v59, v83
	s_and_saveexec_b64 s[26:27], vcc
	s_cbranch_execz .LBB0_739
	v_bitop3_b32 v59, v67, s44, v67 bitop3:0xc
	v_lshl_add_u32 v61, v59, 2, v85
	ds_write_b32 v61, v53 offset:34816
	ds_write_b8 v86, v59 offset:4
	ds_read_b128 v[72:75], v87 offset:34816
	ds_read_b128 v[102:105], v87 offset:34832
	ds_read_b128 v[106:109], v87 offset:34848
	ds_read_b128 v[110:113], v87 offset:34864
	ds_read_b128 v[114:117], v87 offset:34880
	ds_read_b128 v[118:121], v87 offset:34896
	ds_read_b128 v[122:125], v87 offset:34912
	ds_read_b128 v[126:129], v87 offset:34928
	s_waitcnt lgkmcnt(6)
	v_max_u32_e32 v63, v104, v105
	v_max_u32_e32 v59, v72, v73
	v_max_u32_e32 v61, v74, v75
	v_max3_u32 v63, v102, v103, v63
	v_max3_u32 v59, v59, v61, v63
	s_waitcnt lgkmcnt(5)
	v_max_u32_e32 v61, v108, v109
	s_waitcnt lgkmcnt(4)
	v_max_u32_e32 v63, v112, v113
	v_max3_u32 v61, v106, v107, v61
	v_max3_u32 v63, v110, v111, v63
	v_max3_u32 v59, v59, v61, v63
	s_waitcnt lgkmcnt(3)
	v_max_u32_e32 v61, v116, v117
	s_waitcnt lgkmcnt(2)
	v_max_u32_e32 v63, v120, v121
	v_max3_u32 v61, v114, v115, v61
	v_max3_u32 v63, v118, v119, v63
	v_max3_u32 v59, v59, v61, v63
	s_waitcnt lgkmcnt(1)
	v_max_u32_e32 v61, v124, v125
	s_waitcnt lgkmcnt(0)
	v_max_u32_e32 v63, v128, v129
	v_max3_u32 v61, v122, v123, v61
	v_max3_u32 v63, v126, v127, v63
	v_max3_u32 v61, v59, v61, v63
.LBB0_739:
	s_or_b64 exec, exec, s[26:27]
	s_nop 1
	v_mov_b32_dpp v59, v61 quad_perm:[1,0,3,2] row_mask:0xf bank_mask:0xf
	s_waitcnt lgkmcnt(0)
	v_max_u32_e32 v59, v61, v59
	s_nop 1
	v_mov_b32_dpp v63, v59 quad_perm:[2,3,0,1] row_mask:0xf bank_mask:0xf
	s_waitcnt lgkmcnt(0)
	v_max_u32_e32 v59, v59, v63
	v_not_b32_e32 v63, v59
	v_bfe_u32 v63, v63, 5, 2
	v_cmp_eq_u32_e32 vcc, v63, v83
	s_and_saveexec_b64 s[26:27], vcc
	s_cbranch_execz .LBB0_741
	v_bitop3_b32 v61, v59, s44, v59 bitop3:0xc
	v_lshl_add_u32 v63, v61, 2, v85
	ds_write_b32 v63, v53 offset:34816
	ds_write_b8 v86, v61 offset:5
	ds_read_b128 v[72:75], v87 offset:34816
	ds_read_b128 v[102:105], v87 offset:34832
	ds_read_b128 v[106:109], v87 offset:34848
	ds_read_b128 v[110:113], v87 offset:34864
	ds_read_b128 v[114:117], v87 offset:34880
	ds_read_b128 v[118:121], v87 offset:34896
	ds_read_b128 v[122:125], v87 offset:34912
	ds_read_b128 v[126:129], v87 offset:34928
	s_waitcnt lgkmcnt(6)
	v_max_u32_e32 v68, v104, v105
	v_max_u32_e32 v61, v72, v73
	v_max_u32_e32 v63, v74, v75
	v_max3_u32 v68, v102, v103, v68
	v_max3_u32 v61, v61, v63, v68
	s_waitcnt lgkmcnt(5)
	v_max_u32_e32 v63, v108, v109
	s_waitcnt lgkmcnt(4)
	v_max_u32_e32 v68, v112, v113
	v_max3_u32 v63, v106, v107, v63
	v_max3_u32 v68, v110, v111, v68
	v_max3_u32 v61, v61, v63, v68
	s_waitcnt lgkmcnt(3)
	v_max_u32_e32 v63, v116, v117
	s_waitcnt lgkmcnt(2)
	v_max_u32_e32 v68, v120, v121
	v_max3_u32 v63, v114, v115, v63
	v_max3_u32 v68, v118, v119, v68
	v_max3_u32 v61, v61, v63, v68
	s_waitcnt lgkmcnt(1)
	v_max_u32_e32 v63, v124, v125
	s_waitcnt lgkmcnt(0)
	v_max_u32_e32 v68, v128, v129
	v_max3_u32 v63, v122, v123, v63
	v_max3_u32 v68, v126, v127, v68
	v_max3_u32 v61, v61, v63, v68
.LBB0_741:
	s_or_b64 exec, exec, s[26:27]
	s_nop 1
	v_mov_b32_dpp v63, v61 quad_perm:[1,0,3,2] row_mask:0xf bank_mask:0xf
	s_waitcnt lgkmcnt(0)
	v_max_u32_e32 v63, v61, v63
	s_nop 1
	v_mov_b32_dpp v68, v63 quad_perm:[2,3,0,1] row_mask:0xf bank_mask:0xf
	s_waitcnt lgkmcnt(0)
	v_max_u32_e32 v68, v63, v68
	v_not_b32_e32 v63, v68
	v_bfe_u32 v63, v63, 5, 2
	v_cmp_eq_u32_e32 vcc, v63, v83
	s_and_saveexec_b64 s[26:27], vcc
	s_cbranch_execz .LBB0_743
	v_bitop3_b32 v61, v68, s44, v68 bitop3:0xc
	v_lshl_add_u32 v63, v61, 2, v85
	ds_write_b32 v63, v53 offset:34816
	ds_write_b8 v86, v61 offset:6
	ds_read_b128 v[72:75], v87 offset:34816
	ds_read_b128 v[102:105], v87 offset:34832
	ds_read_b128 v[106:109], v87 offset:34848
	ds_read_b128 v[110:113], v87 offset:34864
	ds_read_b128 v[114:117], v87 offset:34880
	ds_read_b128 v[118:121], v87 offset:34896
	ds_read_b128 v[122:125], v87 offset:34912
	ds_read_b128 v[126:129], v87 offset:34928
	s_waitcnt lgkmcnt(6)
	v_max_u32_e32 v69, v104, v105
	v_max_u32_e32 v61, v72, v73
	v_max_u32_e32 v63, v74, v75
	v_max3_u32 v69, v102, v103, v69
	v_max3_u32 v61, v61, v63, v69
	s_waitcnt lgkmcnt(5)
	v_max_u32_e32 v63, v108, v109
	s_waitcnt lgkmcnt(4)
	v_max_u32_e32 v69, v112, v113
	v_max3_u32 v63, v106, v107, v63
	v_max3_u32 v69, v110, v111, v69
	v_max3_u32 v61, v61, v63, v69
	s_waitcnt lgkmcnt(3)
	v_max_u32_e32 v63, v116, v117
	s_waitcnt lgkmcnt(2)
	v_max_u32_e32 v69, v120, v121
	v_max3_u32 v63, v114, v115, v63
	v_max3_u32 v69, v118, v119, v69
	v_max3_u32 v61, v61, v63, v69
	s_waitcnt lgkmcnt(1)
	v_max_u32_e32 v63, v124, v125
	s_waitcnt lgkmcnt(0)
	v_max_u32_e32 v69, v128, v129
	v_max3_u32 v63, v122, v123, v63
	v_max3_u32 v69, v126, v127, v69
	v_max3_u32 v61, v61, v63, v69
.LBB0_743:
	s_or_b64 exec, exec, s[26:27]
	s_nop 1
	v_mov_b32_dpp v63, v61 quad_perm:[1,0,3,2] row_mask:0xf bank_mask:0xf
	s_waitcnt lgkmcnt(0)
	v_max_u32_e32 v63, v61, v63
	s_nop 1
	v_mov_b32_dpp v69, v63 quad_perm:[2,3,0,1] row_mask:0xf bank_mask:0xf
	s_waitcnt lgkmcnt(0)
	v_max_u32_e32 v70, v63, v69
	v_not_b32_e32 v63, v70
	v_bfe_u32 v63, v63, 5, 2
	v_cmp_eq_u32_e32 vcc, v63, v83
	s_and_saveexec_b64 s[26:27], vcc
	s_cbranch_execz .LBB0_745
	v_bitop3_b32 v61, v70, s44, v70 bitop3:0xc
	v_lshl_add_u32 v63, v61, 2, v85
	ds_write_b32 v63, v53 offset:34816
	ds_write_b8 v86, v61 offset:7
	ds_read_b128 v[72:75], v87 offset:34816
	ds_read_b128 v[102:105], v87 offset:34832
	ds_read_b128 v[106:109], v87 offset:34848
	ds_read_b128 v[110:113], v87 offset:34864
	ds_read_b128 v[114:117], v87 offset:34880
	ds_read_b128 v[118:121], v87 offset:34896
	ds_read_b128 v[122:125], v87 offset:34912
	ds_read_b128 v[126:129], v87 offset:34928
	s_waitcnt lgkmcnt(6)
	v_max_u32_e32 v69, v104, v105
	v_max_u32_e32 v61, v72, v73
	v_max_u32_e32 v63, v74, v75
	v_max3_u32 v69, v102, v103, v69
	v_max3_u32 v61, v61, v63, v69
	s_waitcnt lgkmcnt(5)
	v_max_u32_e32 v63, v108, v109
	s_waitcnt lgkmcnt(4)
	v_max_u32_e32 v69, v112, v113
	v_max3_u32 v63, v106, v107, v63
	v_max3_u32 v69, v110, v111, v69
	v_max3_u32 v61, v61, v63, v69
	s_waitcnt lgkmcnt(3)
	v_max_u32_e32 v63, v116, v117
	s_waitcnt lgkmcnt(2)
	v_max_u32_e32 v69, v120, v121
	v_max3_u32 v63, v114, v115, v63
	v_max3_u32 v69, v118, v119, v69
	v_max3_u32 v61, v61, v63, v69
	s_waitcnt lgkmcnt(1)
	v_max_u32_e32 v63, v124, v125
	s_waitcnt lgkmcnt(0)
	v_max_u32_e32 v69, v128, v129
	v_max3_u32 v63, v122, v123, v63
	v_max3_u32 v69, v126, v127, v69
	v_max3_u32 v61, v61, v63, v69
.LBB0_745:
	s_or_b64 exec, exec, s[26:27]
	s_nop 1
	v_mov_b32_dpp v63, v61 quad_perm:[1,0,3,2] row_mask:0xf bank_mask:0xf
	s_waitcnt lgkmcnt(0)
	v_max_u32_e32 v63, v61, v63
	s_nop 1
	v_mov_b32_dpp v69, v63 quad_perm:[2,3,0,1] row_mask:0xf bank_mask:0xf
	s_waitcnt lgkmcnt(0)
	v_max_u32_e32 v72, v63, v69
	v_not_b32_e32 v63, v72
	v_bfe_u32 v63, v63, 5, 2
	v_cmp_eq_u32_e32 vcc, v63, v83
	s_and_saveexec_b64 s[26:27], vcc
	s_cbranch_execz .LBB0_747
	v_bitop3_b32 v61, v72, s44, v72 bitop3:0xc
	v_lshl_add_u32 v63, v61, 2, v85
	ds_write_b32 v63, v53 offset:34816
	ds_write_b8 v86, v61 offset:8
	ds_read_b128 v[102:105], v87 offset:34816
	ds_read_b128 v[106:109], v87 offset:34832
	ds_read_b128 v[110:113], v87 offset:34848
	ds_read_b128 v[114:117], v87 offset:34864
	ds_read_b128 v[118:121], v87 offset:34880
	ds_read_b128 v[122:125], v87 offset:34896
	ds_read_b128 v[126:129], v87 offset:34912
	ds_read_b128 v[130:133], v87 offset:34928
	s_waitcnt lgkmcnt(6)
	v_max_u32_e32 v69, v108, v109
	v_max_u32_e32 v61, v102, v103
	v_max_u32_e32 v63, v104, v105
	v_max3_u32 v69, v106, v107, v69
	v_max3_u32 v61, v61, v63, v69
	s_waitcnt lgkmcnt(5)
	v_max_u32_e32 v63, v112, v113
	s_waitcnt lgkmcnt(4)
	v_max_u32_e32 v69, v116, v117
	v_max3_u32 v63, v110, v111, v63
	v_max3_u32 v69, v114, v115, v69
	v_max3_u32 v61, v61, v63, v69
	s_waitcnt lgkmcnt(3)
	v_max_u32_e32 v63, v120, v121
	s_waitcnt lgkmcnt(2)
	v_max_u32_e32 v69, v124, v125
	v_max3_u32 v63, v118, v119, v63
	v_max3_u32 v69, v122, v123, v69
	v_max3_u32 v61, v61, v63, v69
	s_waitcnt lgkmcnt(1)
	v_max_u32_e32 v63, v128, v129
	s_waitcnt lgkmcnt(0)
	v_max_u32_e32 v69, v132, v133
	v_max3_u32 v63, v126, v127, v63
	v_max3_u32 v69, v130, v131, v69
	v_max3_u32 v61, v61, v63, v69
.LBB0_747:
	s_or_b64 exec, exec, s[26:27]
	s_nop 1
	v_mov_b32_dpp v63, v61 quad_perm:[1,0,3,2] row_mask:0xf bank_mask:0xf
	s_waitcnt lgkmcnt(0)
	v_max_u32_e32 v63, v61, v63
	s_nop 1
	v_mov_b32_dpp v69, v63 quad_perm:[2,3,0,1] row_mask:0xf bank_mask:0xf
	s_waitcnt lgkmcnt(0)
	v_max_u32_e32 v63, v63, v69
	v_not_b32_e32 v69, v63
	v_bfe_u32 v69, v69, 5, 2
	v_cmp_eq_u32_e32 vcc, v69, v83
	s_and_saveexec_b64 s[26:27], vcc
	s_cbranch_execz .LBB0_749
	v_bitop3_b32 v61, v63, s44, v63 bitop3:0xc
	v_lshl_add_u32 v69, v61, 2, v85
	ds_write_b32 v69, v53 offset:34816
	ds_write_b8 v86, v61 offset:9
	ds_read_b128 v[102:105], v87 offset:34816
	ds_read_b128 v[106:109], v87 offset:34832
	ds_read_b128 v[110:113], v87 offset:34848
	ds_read_b128 v[114:117], v87 offset:34864
	ds_read_b128 v[118:121], v87 offset:34880
	ds_read_b128 v[122:125], v87 offset:34896
	ds_read_b128 v[126:129], v87 offset:34912
	ds_read_b128 v[130:133], v87 offset:34928
	s_waitcnt lgkmcnt(6)
	v_max_u32_e32 v73, v108, v109
	v_max_u32_e32 v61, v102, v103
	v_max_u32_e32 v69, v104, v105
	v_max3_u32 v73, v106, v107, v73
	v_max3_u32 v61, v61, v69, v73
	s_waitcnt lgkmcnt(5)
	v_max_u32_e32 v69, v112, v113
	s_waitcnt lgkmcnt(4)
	v_max_u32_e32 v73, v116, v117
	v_max3_u32 v69, v110, v111, v69
	v_max3_u32 v73, v114, v115, v73
	v_max3_u32 v61, v61, v69, v73
	s_waitcnt lgkmcnt(3)
	v_max_u32_e32 v69, v120, v121
	s_waitcnt lgkmcnt(2)
	v_max_u32_e32 v73, v124, v125
	v_max3_u32 v69, v118, v119, v69
	v_max3_u32 v73, v122, v123, v73
	v_max3_u32 v61, v61, v69, v73
	s_waitcnt lgkmcnt(1)
	v_max_u32_e32 v69, v128, v129
	s_waitcnt lgkmcnt(0)
	v_max_u32_e32 v73, v132, v133
	v_max3_u32 v69, v126, v127, v69
	v_max3_u32 v73, v130, v131, v73
	v_max3_u32 v61, v61, v69, v73
.LBB0_749:
	s_or_b64 exec, exec, s[26:27]
	s_nop 1
	v_mov_b32_dpp v69, v61 quad_perm:[1,0,3,2] row_mask:0xf bank_mask:0xf
	s_waitcnt lgkmcnt(0)
	v_max_u32_e32 v69, v61, v69
	s_nop 1
	v_mov_b32_dpp v73, v69 quad_perm:[2,3,0,1] row_mask:0xf bank_mask:0xf
	s_waitcnt lgkmcnt(0)
	v_max_u32_e32 v73, v69, v73
	v_not_b32_e32 v69, v73
	v_bfe_u32 v69, v69, 5, 2
	v_cmp_eq_u32_e32 vcc, v69, v83
	s_and_saveexec_b64 s[26:27], vcc
	s_cbranch_execz .LBB0_751
	v_bitop3_b32 v61, v73, s44, v73 bitop3:0xc
	v_lshl_add_u32 v69, v61, 2, v85
	ds_write_b32 v69, v53 offset:34816
	ds_write_b8 v86, v61 offset:10
	ds_read_b128 v[102:105], v87 offset:34816
	ds_read_b128 v[106:109], v87 offset:34832
	ds_read_b128 v[110:113], v87 offset:34848
	ds_read_b128 v[114:117], v87 offset:34864
	ds_read_b128 v[118:121], v87 offset:34880
	ds_read_b128 v[122:125], v87 offset:34896
	ds_read_b128 v[126:129], v87 offset:34912
	ds_read_b128 v[130:133], v87 offset:34928
	s_waitcnt lgkmcnt(6)
	v_max_u32_e32 v74, v108, v109
	v_max_u32_e32 v61, v102, v103
	v_max_u32_e32 v69, v104, v105
	v_max3_u32 v74, v106, v107, v74
	v_max3_u32 v61, v61, v69, v74
	s_waitcnt lgkmcnt(5)
	v_max_u32_e32 v69, v112, v113
	s_waitcnt lgkmcnt(4)
	v_max_u32_e32 v74, v116, v117
	v_max3_u32 v69, v110, v111, v69
	v_max3_u32 v74, v114, v115, v74
	v_max3_u32 v61, v61, v69, v74
	s_waitcnt lgkmcnt(3)
	v_max_u32_e32 v69, v120, v121
	s_waitcnt lgkmcnt(2)
	v_max_u32_e32 v74, v124, v125
	v_max3_u32 v69, v118, v119, v69
	v_max3_u32 v74, v122, v123, v74
	v_max3_u32 v61, v61, v69, v74
	s_waitcnt lgkmcnt(1)
	v_max_u32_e32 v69, v128, v129
	s_waitcnt lgkmcnt(0)
	v_max_u32_e32 v74, v132, v133
	v_max3_u32 v69, v126, v127, v69
	v_max3_u32 v74, v130, v131, v74
	v_max3_u32 v61, v61, v69, v74
.LBB0_751:
	s_or_b64 exec, exec, s[26:27]
	s_nop 1
	v_mov_b32_dpp v69, v61 quad_perm:[1,0,3,2] row_mask:0xf bank_mask:0xf
	s_waitcnt lgkmcnt(0)
	v_max_u32_e32 v69, v61, v69
	s_nop 1
	v_mov_b32_dpp v74, v69 quad_perm:[2,3,0,1] row_mask:0xf bank_mask:0xf
	s_waitcnt lgkmcnt(0)
	v_max_u32_e32 v74, v69, v74
	v_not_b32_e32 v69, v74
	v_bfe_u32 v69, v69, 5, 2
	v_cmp_eq_u32_e32 vcc, v69, v83
	s_and_saveexec_b64 s[26:27], vcc
	s_cbranch_execz .LBB0_753
	v_bitop3_b32 v61, v74, s44, v74 bitop3:0xc
	v_lshl_add_u32 v69, v61, 2, v85
	ds_write_b32 v69, v53 offset:34816
	ds_write_b8 v86, v61 offset:11
	ds_read_b128 v[102:105], v87 offset:34816
	ds_read_b128 v[106:109], v87 offset:34832
	ds_read_b128 v[110:113], v87 offset:34848
	ds_read_b128 v[114:117], v87 offset:34864
	ds_read_b128 v[118:121], v87 offset:34880
	ds_read_b128 v[122:125], v87 offset:34896
	ds_read_b128 v[126:129], v87 offset:34912
	ds_read_b128 v[130:133], v87 offset:34928
	s_waitcnt lgkmcnt(6)
	v_max_u32_e32 v75, v108, v109
	v_max_u32_e32 v61, v102, v103
	v_max_u32_e32 v69, v104, v105
	v_max3_u32 v75, v106, v107, v75
	v_max3_u32 v61, v61, v69, v75
	s_waitcnt lgkmcnt(5)
	v_max_u32_e32 v69, v112, v113
	s_waitcnt lgkmcnt(4)
	v_max_u32_e32 v75, v116, v117
	v_max3_u32 v69, v110, v111, v69
	v_max3_u32 v75, v114, v115, v75
	v_max3_u32 v61, v61, v69, v75
	s_waitcnt lgkmcnt(3)
	v_max_u32_e32 v69, v120, v121
	s_waitcnt lgkmcnt(2)
	v_max_u32_e32 v75, v124, v125
	v_max3_u32 v69, v118, v119, v69
	v_max3_u32 v75, v122, v123, v75
	v_max3_u32 v61, v61, v69, v75
	s_waitcnt lgkmcnt(1)
	v_max_u32_e32 v69, v128, v129
	s_waitcnt lgkmcnt(0)
	v_max_u32_e32 v75, v132, v133
	v_max3_u32 v69, v126, v127, v69
	v_max3_u32 v75, v130, v131, v75
	v_max3_u32 v61, v61, v69, v75
.LBB0_753:
	s_or_b64 exec, exec, s[26:27]
	s_nop 1
	v_mov_b32_dpp v69, v61 quad_perm:[1,0,3,2] row_mask:0xf bank_mask:0xf
	s_waitcnt lgkmcnt(0)
	v_max_u32_e32 v69, v61, v69
	s_nop 1
	v_mov_b32_dpp v75, v69 quad_perm:[2,3,0,1] row_mask:0xf bank_mask:0xf
	s_waitcnt lgkmcnt(0)
	v_max_u32_e32 v75, v69, v75
	v_not_b32_e32 v69, v75
	v_bfe_u32 v69, v69, 5, 2
	v_cmp_eq_u32_e32 vcc, v69, v83
	s_and_saveexec_b64 s[26:27], vcc
	s_cbranch_execz .LBB0_755
	v_bitop3_b32 v61, v75, s44, v75 bitop3:0xc
	v_lshl_add_u32 v69, v61, 2, v85
	ds_write_b32 v69, v53 offset:34816
	ds_write_b8 v86, v61 offset:12
	ds_read_b128 v[102:105], v87 offset:34816
	ds_read_b128 v[106:109], v87 offset:34832
	ds_read_b128 v[110:113], v87 offset:34848
	ds_read_b128 v[114:117], v87 offset:34864
	ds_read_b128 v[118:121], v87 offset:34880
	ds_read_b128 v[122:125], v87 offset:34896
	ds_read_b128 v[126:129], v87 offset:34912
	ds_read_b128 v[130:133], v87 offset:34928
	s_waitcnt lgkmcnt(6)
	v_max_u32_e32 v76, v108, v109
	v_max_u32_e32 v61, v102, v103
	v_max_u32_e32 v69, v104, v105
	v_max3_u32 v76, v106, v107, v76
	v_max3_u32 v61, v61, v69, v76
	s_waitcnt lgkmcnt(5)
	v_max_u32_e32 v69, v112, v113
	s_waitcnt lgkmcnt(4)
	v_max_u32_e32 v76, v116, v117
	v_max3_u32 v69, v110, v111, v69
	v_max3_u32 v76, v114, v115, v76
	v_max3_u32 v61, v61, v69, v76
	s_waitcnt lgkmcnt(3)
	v_max_u32_e32 v69, v120, v121
	s_waitcnt lgkmcnt(2)
	v_max_u32_e32 v76, v124, v125
	v_max3_u32 v69, v118, v119, v69
	v_max3_u32 v76, v122, v123, v76
	v_max3_u32 v61, v61, v69, v76
	s_waitcnt lgkmcnt(1)
	v_max_u32_e32 v69, v128, v129
	s_waitcnt lgkmcnt(0)
	v_max_u32_e32 v76, v132, v133
	v_max3_u32 v69, v126, v127, v69
	v_max3_u32 v76, v130, v131, v76
	v_max3_u32 v61, v61, v69, v76
.LBB0_755:
	s_or_b64 exec, exec, s[26:27]
	s_nop 1
	v_mov_b32_dpp v69, v61 quad_perm:[1,0,3,2] row_mask:0xf bank_mask:0xf
	s_waitcnt lgkmcnt(0)
	v_max_u32_e32 v69, v61, v69
	s_nop 1
	v_mov_b32_dpp v76, v69 quad_perm:[2,3,0,1] row_mask:0xf bank_mask:0xf
	s_waitcnt lgkmcnt(0)
	v_max_u32_e32 v69, v69, v76
	v_not_b32_e32 v76, v69
	v_bfe_u32 v76, v76, 5, 2
	v_cmp_eq_u32_e32 vcc, v76, v83
	s_and_saveexec_b64 s[26:27], vcc
	s_cbranch_execz .LBB0_757
	v_bitop3_b32 v61, v69, s44, v69 bitop3:0xc
	v_lshl_add_u32 v76, v61, 2, v85
	ds_write_b32 v76, v53 offset:34816
	ds_write_b8 v86, v61 offset:13
	ds_read_b128 v[102:105], v87 offset:34816
	ds_read_b128 v[106:109], v87 offset:34832
	ds_read_b128 v[110:113], v87 offset:34848
	ds_read_b128 v[114:117], v87 offset:34864
	ds_read_b128 v[118:121], v87 offset:34880
	ds_read_b128 v[122:125], v87 offset:34896
	ds_read_b128 v[126:129], v87 offset:34912
	ds_read_b128 v[130:133], v87 offset:34928
	s_waitcnt lgkmcnt(6)
	v_max_u32_e32 v79, v108, v109
	v_max_u32_e32 v61, v102, v103
	v_max_u32_e32 v76, v104, v105
	v_max3_u32 v79, v106, v107, v79
	v_max3_u32 v61, v61, v76, v79
	s_waitcnt lgkmcnt(5)
	v_max_u32_e32 v76, v112, v113
	s_waitcnt lgkmcnt(4)
	v_max_u32_e32 v79, v116, v117
	v_max3_u32 v76, v110, v111, v76
	v_max3_u32 v79, v114, v115, v79
	v_max3_u32 v61, v61, v76, v79
	s_waitcnt lgkmcnt(3)
	v_max_u32_e32 v76, v120, v121
	s_waitcnt lgkmcnt(2)
	v_max_u32_e32 v79, v124, v125
	v_max3_u32 v76, v118, v119, v76
	v_max3_u32 v79, v122, v123, v79
	v_max3_u32 v61, v61, v76, v79
	s_waitcnt lgkmcnt(1)
	v_max_u32_e32 v76, v128, v129
	s_waitcnt lgkmcnt(0)
	v_max_u32_e32 v79, v132, v133
	v_max3_u32 v76, v126, v127, v76
	v_max3_u32 v79, v130, v131, v79
	v_max3_u32 v61, v61, v76, v79
.LBB0_757:
	s_or_b64 exec, exec, s[26:27]
	s_nop 1
	v_mov_b32_dpp v76, v61 quad_perm:[1,0,3,2] row_mask:0xf bank_mask:0xf
	s_waitcnt lgkmcnt(0)
	v_max_u32_e32 v76, v61, v76
	s_nop 1
	v_mov_b32_dpp v79, v76 quad_perm:[2,3,0,1] row_mask:0xf bank_mask:0xf
	s_waitcnt lgkmcnt(0)
	v_max_u32_e32 v76, v76, v79
	v_not_b32_e32 v79, v76
	v_bfe_u32 v79, v79, 5, 2
	v_cmp_eq_u32_e32 vcc, v79, v83
	s_and_saveexec_b64 s[26:27], vcc
	s_cbranch_execz .LBB0_759
	v_bitop3_b32 v61, v76, s44, v76 bitop3:0xc
	v_lshl_add_u32 v79, v61, 2, v85
	ds_write_b32 v79, v53 offset:34816
	ds_write_b8 v86, v61 offset:14
	ds_read_b128 v[102:105], v87 offset:34816
	ds_read_b128 v[106:109], v87 offset:34832
	ds_read_b128 v[110:113], v87 offset:34848
	ds_read_b128 v[114:117], v87 offset:34864
	ds_read_b128 v[118:121], v87 offset:34880
	ds_read_b128 v[122:125], v87 offset:34896
	ds_read_b128 v[126:129], v87 offset:34912
	ds_read_b128 v[130:133], v87 offset:34928
	s_waitcnt lgkmcnt(6)
	v_max_u32_e32 v80, v108, v109
	v_max_u32_e32 v61, v102, v103
	v_max_u32_e32 v79, v104, v105
	v_max3_u32 v80, v106, v107, v80
	v_max3_u32 v61, v61, v79, v80
	s_waitcnt lgkmcnt(5)
	v_max_u32_e32 v79, v112, v113
	s_waitcnt lgkmcnt(4)
	v_max_u32_e32 v80, v116, v117
	v_max3_u32 v79, v110, v111, v79
	v_max3_u32 v80, v114, v115, v80
	v_max3_u32 v61, v61, v79, v80
	s_waitcnt lgkmcnt(3)
	v_max_u32_e32 v79, v120, v121
	s_waitcnt lgkmcnt(2)
	v_max_u32_e32 v80, v124, v125
	v_max3_u32 v79, v118, v119, v79
	v_max3_u32 v80, v122, v123, v80
	v_max3_u32 v61, v61, v79, v80
	s_waitcnt lgkmcnt(1)
	v_max_u32_e32 v79, v128, v129
	s_waitcnt lgkmcnt(0)
	v_max_u32_e32 v80, v132, v133
	v_max3_u32 v79, v126, v127, v79
	v_max3_u32 v80, v130, v131, v80
	v_max3_u32 v61, v61, v79, v80
.LBB0_759:
	s_or_b64 exec, exec, s[26:27]
	s_nop 1
	v_mov_b32_dpp v79, v61 quad_perm:[1,0,3,2] row_mask:0xf bank_mask:0xf
	s_waitcnt lgkmcnt(0)
	v_max_u32_e32 v61, v61, v79
	s_nop 1
	v_mov_b32_dpp v79, v61 quad_perm:[2,3,0,1] row_mask:0xf bank_mask:0xf
	s_waitcnt lgkmcnt(0)
	v_max_u32_e32 v79, v61, v79
	v_not_b32_e32 v61, v79
	v_bfe_u32 v61, v61, 5, 2
	v_cmp_eq_u32_e32 vcc, v61, v83
	s_and_saveexec_b64 s[26:27], vcc
	s_cbranch_execz .LBB0_761
	v_bitop3_b32 v61, v79, s44, v79 bitop3:0xc
	v_lshl_add_u32 v80, v61, 2, v85
	ds_write_b32 v80, v53 offset:34816
	ds_write_b8 v86, v61 offset:15
.LBB0_761:
	s_or_b64 exec, exec, s[26:27]
	s_waitcnt lgkmcnt(0)
	s_barrier
	s_waitcnt vmcnt(27)
	ds_write_b128 v98, v[16:19]
	s_waitcnt vmcnt(26)
	ds_write_b128 v98, v[20:23] offset:4352
	s_waitcnt vmcnt(25)
	ds_write_b128 v98, v[24:27] offset:8704
	s_waitcnt vmcnt(24)
	ds_write_b128 v98, v[28:31] offset:13056
	s_waitcnt vmcnt(23)
	ds_write_b128 v98, v[36:39] offset:17408
	s_waitcnt vmcnt(22)
	ds_write_b128 v98, v[40:43] offset:21760
	s_waitcnt vmcnt(21)
	ds_write_b128 v98, v[44:47] offset:26112
	s_waitcnt vmcnt(20)
	ds_write_b128 v98, v[48:51] offset:30464
	s_waitcnt lgkmcnt(0)
	s_barrier
	ds_read_b128 v[16:19], v99
	ds_read_b128 v[20:23], v99 offset:4352
	ds_read_b128 v[24:27], v99 offset:8704
	ds_read_b128 v[28:31], v99 offset:13056
	ds_read_b128 v[36:39], v99 offset:17408
	ds_read_b128 v[40:43], v99 offset:21760
	ds_read_b128 v[44:47], v99 offset:26112
	ds_read_b128 v[48:51], v99 offset:30464
	s_waitcnt vmcnt(19) lgkmcnt(7)
	v_mfma_f32_16x16x32_bf16 v[16:19], v[32:35], v[16:19], 0
	s_add_i32 s59, s59, s52
	s_cmpk_gt_i32 s59, 0x7ff
	s_cselect_b64 s[26:27], -1, 0
	s_waitcnt lgkmcnt(6)
	v_mfma_f32_16x16x32_bf16 v[20:23], v[32:35], v[20:23], 0
	s_cmpk_lt_i32 s59, 0x800
	s_cselect_b32 s28, s59, s2
	s_and_b32 s29, s28, 7
	s_waitcnt lgkmcnt(5)
	v_mfma_f32_16x16x32_bf16 v[24:27], v[32:35], v[24:27], 0
	s_lshl_b32 s24, s29, 16
	s_waitcnt lgkmcnt(4)
	v_mfma_f32_16x16x32_bf16 v[28:31], v[32:35], v[28:31], 0
	s_waitcnt lgkmcnt(3)
	v_mfma_f32_16x16x32_bf16 v[36:39], v[32:35], v[36:39], 0
	s_waitcnt lgkmcnt(2)
	v_mfma_f32_16x16x32_bf16 v[40:43], v[32:35], v[40:43], 0
	s_waitcnt lgkmcnt(1)
	v_mfma_f32_16x16x32_bf16 v[44:47], v[32:35], v[44:47], 0
	s_waitcnt lgkmcnt(0)
	v_mfma_f32_16x16x32_bf16 v[32:35], v[32:35], v[48:51], 0
	ds_read_b128 v[48:51], v88 offset:64
	ds_read_b128 v[102:105], v88 offset:128
	s_waitcnt vmcnt(18) lgkmcnt(1)
	v_mfma_f32_16x16x32_bf16 v[16:19], v[12:15], v[48:51], v[16:19]
	ds_read_b128 v[48:51], v89 offset:64
	ds_read_b128 v[106:109], v88 offset:192
	s_waitcnt lgkmcnt(1)
	v_mfma_f32_16x16x32_bf16 v[20:23], v[12:15], v[48:51], v[20:23]
	ds_read_b128 v[48:51], v90 offset:64
	ds_read_b128 v[110:113], v90 offset:128
	s_waitcnt lgkmcnt(1)
	v_mfma_f32_16x16x32_bf16 v[24:27], v[12:15], v[48:51], v[24:27]
	ds_read_b128 v[48:51], v91 offset:64
	ds_read_b128 v[114:117], v90 offset:192
	s_waitcnt vmcnt(17)
	v_mfma_f32_16x16x32_bf16 v[16:19], v[8:11], v[102:105], v[16:19]
	s_waitcnt lgkmcnt(1)
	v_mfma_f32_16x16x32_bf16 v[28:31], v[12:15], v[48:51], v[28:31]
	ds_read_b128 v[48:51], v92 offset:64
	ds_read_b128 v[118:121], v93 offset:64
	ds_read_b128 v[122:125], v92 offset:128
	s_waitcnt vmcnt(16)
	v_mfma_f32_16x16x32_bf16 v[16:19], v[4:7], v[106:109], v[16:19]
	s_waitcnt lgkmcnt(2)
	v_mfma_f32_16x16x32_bf16 v[36:39], v[12:15], v[48:51], v[36:39]
	ds_read_b128 v[48:51], v94 offset:64
	ds_read_b128 v[126:129], v94 offset:128
	ds_read_b128 v[130:133], v92 offset:192
	s_nop 2
	v_not_b32_e32 v61, v16
	v_or_b32_e32 v80, 0x80000000, v16
	s_waitcnt lgkmcnt(4)
	v_mfma_f32_16x16x32_bf16 v[40:43], v[12:15], v[118:121], v[40:43]
	ds_read_b128 v[118:121], v89 offset:128
	ds_read_b128 v[134:137], v89 offset:192
	ds_read_b128 v[138:141], v91 offset:128
	ds_read_b128 v[146:149], v91 offset:192
	ds_read_b128 v[102:105], v93 offset:128
	ds_read_b128 v[150:153], v93 offset:192
	ds_read_b128 v[154:157], v95 offset:64
	ds_read_b128 v[158:161], v94 offset:192
	v_cmp_gt_i32_e32 vcc, 0, v16
	s_waitcnt lgkmcnt(10)
	v_mfma_f32_16x16x32_bf16 v[44:47], v[12:15], v[48:51], v[44:47]
	ds_read_b128 v[106:109], v95 offset:128
	ds_read_b128 v[162:165], v95 offset:192
	v_cndmask_b32_e32 v16, v80, v61, vcc
	v_and_b32_e32 v16, 0xffffff80, v16
	s_waitcnt lgkmcnt(3)
	v_mfma_f32_16x16x32_bf16 v[12:15], v[12:15], v[154:157], v[32:35]
	v_bitop3_b32 v48, v71, s44, v16 bitop3:0x36
	v_not_b32_e32 v16, v17
	v_cmp_gt_i32_e32 vcc, 0, v17
	v_or_b32_e32 v32, 0x80000000, v17
	v_or_b32_e32 v17, 0x80000000, v18
	v_cndmask_b32_e32 v16, v32, v16, vcc
	v_and_b32_e32 v16, 0xffffff80, v16
	v_bitop3_b32 v49, v71, s44, v16 bitop3:0x36
	v_not_b32_e32 v16, v18
	v_cmp_gt_i32_e32 vcc, 0, v18
	v_mfma_f32_16x16x32_bf16 v[20:23], v[8:11], v[118:121], v[20:23]
	v_mov_b32_e32 v61, v53
	v_cndmask_b32_e32 v16, v17, v16, vcc
	v_and_b32_e32 v16, 0xffffff80, v16
	v_bitop3_b32 v50, v71, s44, v16 bitop3:0x36
	v_not_b32_e32 v16, v19
	v_or_b32_e32 v17, 0x80000000, v19
	v_cmp_gt_i32_e32 vcc, 0, v19
	v_mfma_f32_16x16x32_bf16 v[32:35], v[8:11], v[122:125], v[36:39]
	s_nop 0
	v_cndmask_b32_e32 v16, v17, v16, vcc
	v_mfma_f32_16x16x32_bf16 v[36:39], v[8:11], v[102:105], v[40:43]
	s_nop 2
	v_and_b32_e32 v40, 0xffffff80, v16
	v_mfma_f32_16x16x32_bf16 v[16:19], v[4:7], v[134:137], v[20:23]
	v_bitop3_b32 v40, v71, s44, v40 bitop3:0x36
	v_mfma_f32_16x16x32_bf16 v[24:27], v[8:11], v[110:113], v[24:27]
	v_mfma_f32_16x16x32_bf16 v[28:31], v[8:11], v[138:141], v[28:31]
	s_nop 4
	v_not_b32_e32 v41, v16
	v_or_b32_e32 v42, 0x80000000, v16
	v_cmp_gt_i32_e32 vcc, 0, v16
	v_mfma_f32_16x16x32_bf16 v[20:23], v[8:11], v[126:129], v[44:47]
	s_nop 0
	v_cndmask_b32_e32 v16, v42, v41, vcc
	v_and_b32_e32 v16, 0xffffff80, v16
	v_bitop3_b32 v16, v71, s45, v16 bitop3:0x36
	ds_write2_b32 v77, v48, v16 offset1:16
	v_not_b32_e32 v16, v17
	v_or_b32_e32 v41, 0x80000000, v17
	v_cmp_gt_i32_e32 vcc, 0, v17
	v_or_b32_e32 v17, 0x80000000, v18
	s_waitcnt lgkmcnt(2)
	v_mfma_f32_16x16x32_bf16 v[8:11], v[8:11], v[106:109], v[12:15]
	v_cndmask_b32_e32 v16, v41, v16, vcc
	v_and_b32_e32 v16, 0xffffff80, v16
	v_bitop3_b32 v16, v71, s45, v16 bitop3:0x36
	ds_write2_b32 v77, v49, v16 offset0:132 offset1:148
	v_not_b32_e32 v16, v18
	v_cmp_gt_i32_e32 vcc, 0, v18
	v_mfma_f32_16x16x32_bf16 v[12:15], v[4:7], v[114:117], v[24:27]
	s_nop 0
	v_cndmask_b32_e32 v16, v17, v16, vcc
	v_and_b32_e32 v16, 0xffffff80, v16
	v_bitop3_b32 v16, v71, s45, v16 bitop3:0x36
	ds_write2_b32 v78, v50, v16 offset0:8 offset1:24
	v_not_b32_e32 v16, v19
	v_or_b32_e32 v17, 0x80000000, v19
	v_cmp_gt_i32_e32 vcc, 0, v19
	v_mfma_f32_16x16x32_bf16 v[24:27], v[4:7], v[146:149], v[28:31]
	s_nop 0
	v_cndmask_b32_e32 v16, v17, v16, vcc
	v_cmp_gt_i32_e32 vcc, 0, v12
	v_mfma_f32_16x16x32_bf16 v[28:31], v[4:7], v[130:133], v[32:35]
	v_mfma_f32_16x16x32_bf16 v[32:35], v[4:7], v[150:153], v[36:39]
	v_mfma_f32_16x16x32_bf16 v[20:23], v[4:7], v[158:161], v[20:23]
	s_waitcnt lgkmcnt(3)
	v_mfma_f32_16x16x32_bf16 v[4:7], v[4:7], v[162:165], v[8:11]
	s_nop 2
	v_and_b32_e32 v8, 0xffffff80, v16
	v_bitop3_b32 v8, v71, s45, v8 bitop3:0x36
	ds_write2_b32 v78, v40, v8 offset0:140 offset1:156
	v_not_b32_e32 v8, v12
	v_or_b32_e32 v9, 0x80000000, v12
	v_cndmask_b32_e32 v8, v9, v8, vcc
	v_not_b32_e32 v9, v13
	v_or_b32_e32 v10, 0x80000000, v13
	v_cmp_gt_i32_e32 vcc, 0, v13
	v_or_b32_e32 v11, 0x80000000, v14
	v_or_b32_e32 v12, 0x80000000, v15
	v_cndmask_b32_e32 v9, v10, v9, vcc
	v_not_b32_e32 v10, v14
	v_cmp_gt_i32_e32 vcc, 0, v14
	v_or_b32_e32 v13, 0x80000000, v24
	v_and_b32_e32 v8, 0xffffff80, v8
	v_cndmask_b32_e32 v10, v11, v10, vcc
	v_not_b32_e32 v11, v15
	v_cmp_gt_i32_e32 vcc, 0, v15
	v_bitop3_b32 v8, v71, s48, v8 bitop3:0x36
	v_and_b32_e32 v9, 0xffffff80, v9
	v_cndmask_b32_e32 v11, v12, v11, vcc
	v_not_b32_e32 v12, v24
	v_cmp_gt_i32_e32 vcc, 0, v24
	v_bitop3_b32 v9, v71, s48, v9 bitop3:0x36
	v_and_b32_e32 v10, 0xffffff80, v10
	v_cndmask_b32_e32 v12, v13, v12, vcc
	v_and_b32_e32 v12, 0xffffff80, v12
	v_bitop3_b32 v12, v71, s49, v12 bitop3:0x36
	ds_write2_b32 v77, v8, v12 offset0:32 offset1:48
	v_not_b32_e32 v8, v25
	v_or_b32_e32 v12, 0x80000000, v25
	v_cmp_gt_i32_e32 vcc, 0, v25
	v_bitop3_b32 v10, v71, s48, v10 bitop3:0x36
	v_and_b32_e32 v11, 0xffffff80, v11
	v_cndmask_b32_e32 v8, v12, v8, vcc
	v_and_b32_e32 v8, 0xffffff80, v8
	v_bitop3_b32 v8, v71, s49, v8 bitop3:0x36
	ds_write2_b32 v77, v9, v8 offset0:164 offset1:180
	v_not_b32_e32 v8, v26
	v_or_b32_e32 v9, 0x80000000, v26
	v_cmp_gt_i32_e32 vcc, 0, v26
	v_bitop3_b32 v11, v71, s48, v11 bitop3:0x36
	v_or_b32_e32 v12, 0x80000000, v31
	v_cndmask_b32_e32 v8, v9, v8, vcc
	v_and_b32_e32 v8, 0xffffff80, v8
	v_bitop3_b32 v8, v71, s49, v8 bitop3:0x36
	ds_write2_b32 v78, v10, v8 offset0:40 offset1:56
	v_not_b32_e32 v8, v27
	v_or_b32_e32 v9, 0x80000000, v27
	v_cmp_gt_i32_e32 vcc, 0, v27
	v_or_b32_e32 v10, 0x80000000, v29
	v_or_b32_e32 v13, 0x80000000, v32
	v_cndmask_b32_e32 v8, v9, v8, vcc
	v_and_b32_e32 v8, 0xffffff80, v8
	v_bitop3_b32 v8, v71, s49, v8 bitop3:0x36
	ds_write2_b32 v78, v11, v8 offset0:172 offset1:188
	v_not_b32_e32 v8, v28
	v_or_b32_e32 v9, 0x80000000, v28
	v_cmp_gt_i32_e32 vcc, 0, v28
	v_or_b32_e32 v11, 0x80000000, v30
	s_nop 0
	v_cndmask_b32_e32 v8, v9, v8, vcc
	v_not_b32_e32 v9, v29
	v_cmp_gt_i32_e32 vcc, 0, v29
	v_and_b32_e32 v8, 0xffffff80, v8
	v_bitop3_b32 v8, v71, 63, v8 bitop3:0x36
	v_cndmask_b32_e32 v9, v10, v9, vcc
	v_not_b32_e32 v10, v30
	v_cmp_gt_i32_e32 vcc, 0, v30
	v_and_b32_e32 v9, 0xffffff80, v9
	v_bitop3_b32 v9, v71, 63, v9 bitop3:0x36
	v_cndmask_b32_e32 v10, v11, v10, vcc
	v_not_b32_e32 v11, v31
	v_cmp_gt_i32_e32 vcc, 0, v31
	v_and_b32_e32 v10, 0xffffff80, v10
	v_bitop3_b32 v10, v71, 63, v10 bitop3:0x36
	v_cndmask_b32_e32 v11, v12, v11, vcc
	v_not_b32_e32 v12, v32
	v_cmp_gt_i32_e32 vcc, 0, v32
	v_and_b32_e32 v11, 0xffffff80, v11
	v_bitop3_b32 v11, v71, 63, v11 bitop3:0x36
	v_cndmask_b32_e32 v12, v13, v12, vcc
	v_and_b32_e32 v12, 0xffffff80, v12
	v_bitop3_b32 v12, v71, 47, v12 bitop3:0x36
	ds_write2_b32 v77, v8, v12 offset0:64 offset1:80
	v_not_b32_e32 v8, v33
	v_or_b32_e32 v12, 0x80000000, v33
	v_cmp_gt_i32_e32 vcc, 0, v33
	v_or_b32_e32 v13, 0x80000000, v4
	s_nop 0
	v_cndmask_b32_e32 v8, v12, v8, vcc
	v_and_b32_e32 v8, 0xffffff80, v8
	v_bitop3_b32 v8, v71, 47, v8 bitop3:0x36
	ds_write2_b32 v77, v9, v8 offset0:196 offset1:212
	v_not_b32_e32 v8, v34
	v_or_b32_e32 v9, 0x80000000, v34
	v_cmp_gt_i32_e32 vcc, 0, v34
	v_or_b32_e32 v12, 0x80000000, v23
	s_nop 0
	v_cndmask_b32_e32 v8, v9, v8, vcc
	v_and_b32_e32 v8, 0xffffff80, v8
	v_bitop3_b32 v8, v71, 47, v8 bitop3:0x36
	ds_write2_b32 v78, v10, v8 offset0:72 offset1:88
	v_not_b32_e32 v8, v35
	v_or_b32_e32 v9, 0x80000000, v35
	v_cmp_gt_i32_e32 vcc, 0, v35
	v_or_b32_e32 v10, 0x80000000, v21
	s_nop 0
	v_cndmask_b32_e32 v8, v9, v8, vcc
	v_and_b32_e32 v8, 0xffffff80, v8
	v_bitop3_b32 v8, v71, 47, v8 bitop3:0x36
	ds_write2_b32 v78, v11, v8 offset0:204 offset1:220
	v_not_b32_e32 v8, v20
	v_or_b32_e32 v9, 0x80000000, v20
	v_cmp_gt_i32_e32 vcc, 0, v20
	v_or_b32_e32 v11, 0x80000000, v22
	s_nop 0
	v_cndmask_b32_e32 v8, v9, v8, vcc
	v_not_b32_e32 v9, v21
	v_cmp_gt_i32_e32 vcc, 0, v21
	v_and_b32_e32 v8, 0xffffff80, v8
	v_bitop3_b32 v8, v71, 31, v8 bitop3:0x36
	v_cndmask_b32_e32 v9, v10, v9, vcc
	v_not_b32_e32 v10, v22
	v_cmp_gt_i32_e32 vcc, 0, v22
	v_and_b32_e32 v9, 0xffffff80, v9
	v_bitop3_b32 v9, v71, 31, v9 bitop3:0x36
	v_cndmask_b32_e32 v10, v11, v10, vcc
	v_not_b32_e32 v11, v23
	v_cmp_gt_i32_e32 vcc, 0, v23
	v_and_b32_e32 v10, 0xffffff80, v10
	v_bitop3_b32 v10, v71, 31, v10 bitop3:0x36
	v_cndmask_b32_e32 v11, v12, v11, vcc
	v_not_b32_e32 v12, v4
	v_cmp_gt_i32_e32 vcc, 0, v4
	v_and_b32_e32 v11, 0xffffff80, v11
	v_bitop3_b32 v11, v71, 31, v11 bitop3:0x36
	v_cndmask_b32_e32 v4, v13, v12, vcc
	v_and_b32_e32 v4, 0xffffff80, v4
	v_bitop3_b32 v4, v71, 15, v4 bitop3:0x36
	ds_write2_b32 v77, v8, v4 offset0:96 offset1:112
	v_not_b32_e32 v4, v5
	v_or_b32_e32 v8, 0x80000000, v5
	v_cmp_gt_i32_e32 vcc, 0, v5
	v_or_b32_e32 v5, 0x80000000, v6
	s_nop 0
	v_cndmask_b32_e32 v4, v8, v4, vcc
	v_and_b32_e32 v4, 0xffffff80, v4
	v_bitop3_b32 v4, v71, 15, v4 bitop3:0x36
	ds_write2_b32 v77, v9, v4 offset0:228 offset1:244
	v_not_b32_e32 v4, v6
	v_cmp_gt_i32_e32 vcc, 0, v6
	s_nop 1
	v_cndmask_b32_e32 v4, v5, v4, vcc
	v_and_b32_e32 v4, 0xffffff80, v4
	v_bitop3_b32 v4, v71, 15, v4 bitop3:0x36
	ds_write2_b32 v78, v10, v4 offset0:104 offset1:120
	v_not_b32_e32 v4, v7
	v_or_b32_e32 v5, 0x80000000, v7
	v_cmp_gt_i32_e32 vcc, 0, v7
	s_nop 1
	v_cndmask_b32_e32 v4, v5, v4, vcc
	v_and_b32_e32 v4, 0xffffff80, v4
	v_bitop3_b32 v4, v71, 15, v4 bitop3:0x36
	ds_write2_b32 v78, v11, v4 offset0:236 offset1:252
	v_lshl_add_u64 v[4:5], v[54:55], 0, s[24:25]
	v_add_co_u32_e32 v6, vcc, s39, v4
	s_waitcnt lgkmcnt(0)
	s_nop 0
	v_addc_co_u32_e32 v7, vcc, 0, v5, vcc
	s_waitcnt vmcnt(0)
	v_mul_f32_e32 v170, s86, v170
	v_mul_f32_e32 v171, s86, v171
	v_mul_f32_e32 v172, s86, v172
	v_mul_f32_e32 v173, s86, v173
	v_mul_f32_e32 v174, s86, v174
	v_mul_f32_e32 v175, s86, v175
	v_mul_f32_e32 v176, s86, v176
	v_mul_f32_e32 v177, s86, v177
	v_mul_f32_e32 v178, s86, v178
	v_mul_f32_e32 v179, s86, v179
	v_mul_f32_e32 v180, s86, v180
	v_mul_f32_e32 v181, s86, v181
	v_mul_f32_e32 v182, s86, v182
	v_mul_f32_e32 v183, s86, v183
	v_mul_f32_e32 v184, s86, v184
	v_mul_f32_e32 v185, s86, v185
	v_mul_f32_e32 v186, s86, v186
	v_mul_f32_e32 v187, s86, v187
	v_mul_f32_e32 v188, s86, v188
	v_mul_f32_e32 v189, s86, v189
	v_mul_f32_e32 v190, s86, v190
	v_mul_f32_e32 v191, s86, v191
	v_mul_f32_e32 v192, s86, v192
	v_mul_f32_e32 v193, s86, v193
	v_mul_f32_e32 v194, s86, v194
	v_mul_f32_e32 v195, s86, v195
	v_mul_f32_e32 v196, s86, v196
	v_mul_f32_e32 v197, s86, v197
	v_mul_f32_e32 v198, s86, v198
	v_mul_f32_e32 v199, s86, v199
	v_mul_f32_e32 v200, s86, v200
	v_mul_f32_e32 v201, s86, v201
	v_mul_f32_e32 v202, s86, v202
	v_mul_f32_e32 v203, s86, v203
	v_mul_f32_e32 v204, s86, v204
	v_mul_f32_e32 v205, s86, v205
	v_mul_f32_e32 v206, s86, v206
	v_mul_f32_e32 v207, s86, v207
	v_mul_f32_e32 v208, s86, v208
	v_mul_f32_e32 v209, s86, v209
	v_mul_f32_e32 v210, s86, v210
	v_mul_f32_e32 v211, s86, v211
	v_mul_f32_e32 v212, s86, v212
	v_mul_f32_e32 v213, s86, v213
	v_mul_f32_e32 v214, s86, v214
	v_mul_f32_e32 v215, s86, v215
	v_mul_f32_e32 v216, s86, v216
	v_mul_f32_e32 v217, s86, v217
	v_mul_f32_e32 v218, s86, v218
	v_mul_f32_e32 v219, s86, v219
	v_mul_f32_e32 v220, s86, v220
	v_mul_f32_e32 v221, s86, v221
	v_mul_f32_e32 v222, s86, v222
	v_mul_f32_e32 v223, s86, v223
	v_mul_f32_e32 v224, s86, v224
	v_mul_f32_e32 v225, s86, v225
	v_mul_f32_e32 v226, s86, v226
	v_mul_f32_e32 v227, s86, v227
	v_mul_f32_e32 v228, s86, v228
	v_mul_f32_e32 v229, s86, v229
	v_mul_f32_e32 v230, s86, v230
	v_mul_f32_e32 v231, s86, v231
	v_mul_f32_e32 v232, s86, v232
	v_mul_f32_e32 v233, s86, v233
	v_cvt_pk_fp8_f32 v236, v170, v171
	v_cvt_pk_fp8_f32 v237, v174, v175
	v_cvt_pk_fp8_f32 v238, v178, v179
	v_cvt_pk_fp8_f32 v239, v182, v183
	v_cvt_pk_fp8_f32 v240, v186, v187
	v_cvt_pk_fp8_f32 v241, v190, v191
	v_cvt_pk_fp8_f32 v242, v194, v195
	v_cvt_pk_fp8_f32 v243, v198, v199
	v_cvt_pk_fp8_f32 v244, v202, v203
	v_cvt_pk_fp8_f32 v245, v206, v207
	v_cvt_pk_fp8_f32 v246, v210, v211
	v_cvt_pk_fp8_f32 v247, v214, v215
	v_cvt_pk_fp8_f32 v248, v218, v219
	v_cvt_pk_fp8_f32 v249, v222, v223
	v_cvt_pk_fp8_f32 v250, v226, v227
	v_cvt_pk_fp8_f32 v251, v230, v231
	v_cvt_pk_fp8_f32 v236, v172, v173 op_sel:[0,0,1]
	v_cvt_pk_fp8_f32 v237, v176, v177 op_sel:[0,0,1]
	v_cvt_pk_fp8_f32 v238, v180, v181 op_sel:[0,0,1]
	v_cvt_pk_fp8_f32 v239, v184, v185 op_sel:[0,0,1]
	v_cvt_pk_fp8_f32 v240, v188, v189 op_sel:[0,0,1]
	v_cvt_pk_fp8_f32 v241, v192, v193 op_sel:[0,0,1]
	v_cvt_pk_fp8_f32 v242, v196, v197 op_sel:[0,0,1]
	v_cvt_pk_fp8_f32 v243, v200, v201 op_sel:[0,0,1]
	v_cvt_pk_fp8_f32 v244, v204, v205 op_sel:[0,0,1]
	v_cvt_pk_fp8_f32 v245, v208, v209 op_sel:[0,0,1]
	v_cvt_pk_fp8_f32 v246, v212, v213 op_sel:[0,0,1]
	v_cvt_pk_fp8_f32 v247, v216, v217 op_sel:[0,0,1]
	v_cvt_pk_fp8_f32 v248, v220, v221 op_sel:[0,0,1]
	v_cvt_pk_fp8_f32 v249, v224, v225 op_sel:[0,0,1]
	v_cvt_pk_fp8_f32 v250, v228, v229 op_sel:[0,0,1]
	v_cvt_pk_fp8_f32 v251, v232, v233 op_sel:[0,0,1]
	s_nop 0
	global_store_dword v235, v236, s[84:85]
	s_add_u32 s84, s84, 0x800
	s_addc_u32 s85, s85, 0
	global_store_dword v235, v237, s[84:85]
	s_add_u32 s84, s84, 0x800
	s_addc_u32 s85, s85, 0
	global_store_dword v235, v238, s[84:85]
	s_add_u32 s84, s84, 0x800
	s_addc_u32 s85, s85, 0
	global_store_dword v235, v239, s[84:85]
	s_add_u32 s84, s84, 0x800
	s_addc_u32 s85, s85, 0
	global_store_dword v235, v240, s[84:85]
	s_add_u32 s84, s84, 0x800
	s_addc_u32 s85, s85, 0
	global_store_dword v235, v241, s[84:85]
	s_add_u32 s84, s84, 0x800
	s_addc_u32 s85, s85, 0
	global_store_dword v235, v242, s[84:85]
	s_add_u32 s84, s84, 0x800
	s_addc_u32 s85, s85, 0
	global_store_dword v235, v243, s[84:85]
	s_add_u32 s84, s84, 0x800
	s_addc_u32 s85, s85, 0
	global_store_dword v235, v244, s[84:85]
	s_add_u32 s84, s84, 0x800
	s_addc_u32 s85, s85, 0
	global_store_dword v235, v245, s[84:85]
	s_add_u32 s84, s84, 0x800
	s_addc_u32 s85, s85, 0
	global_store_dword v235, v246, s[84:85]
	s_add_u32 s84, s84, 0x800
	s_addc_u32 s85, s85, 0
	global_store_dword v235, v247, s[84:85]
	s_add_u32 s84, s84, 0x800
	s_addc_u32 s85, s85, 0
	global_store_dword v235, v248, s[84:85]
	s_add_u32 s84, s84, 0x800
	s_addc_u32 s85, s85, 0
	global_store_dword v235, v249, s[84:85]
	s_add_u32 s84, s84, 0x800
	s_addc_u32 s85, s85, 0
	global_store_dword v235, v250, s[84:85]
	s_add_u32 s84, s84, 0x800
	s_addc_u32 s85, s85, 0
	global_store_dword v235, v251, s[84:85]
	s_barrier
	global_load_dwordx4 v[44:47], v[6:7], off offset:-4096
	global_load_dwordx4 v[36:39], v[6:7], off
	v_add_co_u32_e32 v6, vcc, s38, v4
	s_lshl_b32 s24, s28, 3
	s_nop 0
	v_addc_co_u32_e32 v7, vcc, 0, v5, vcc
	global_load_dwordx4 v[40:43], v[6:7], off offset:-4096
	global_load_dwordx4 v[28:31], v[6:7], off
	v_add_co_u32_e32 v6, vcc, s37, v4
	s_andn2_b32 s24, s24, 63
	s_nop 0
	v_addc_co_u32_e32 v7, vcc, 0, v5, vcc
	global_load_dwordx4 v[32:35], v[6:7], off offset:-4096
	global_load_dwordx4 v[20:23], v[6:7], off
	v_add_co_u32_e32 v6, vcc, s36, v4
	s_nop 1
	v_addc_co_u32_e32 v7, vcc, 0, v5, vcc
	global_load_dwordx4 v[48:51], v[4:5], off
	global_load_dwordx4 v[24:27], v[6:7], off
	v_add_u32_e32 v4, s24, v84
	v_ashrrev_i32_e32 v5, 31, v4
	v_lshlrev_b64 v[4:5], 12, v[4:5]
	v_lshl_add_u64 v[4:5], s[16:17], 0, v[4:5]
	s_lshl_b32 s24, s29, 9
	v_lshl_add_u64 v[4:5], v[4:5], 0, s[24:25]
	v_lshl_add_u64 v[4:5], v[4:5], 0, v[60:61]
	global_load_dwordx4 v[16:19], v[4:5], off
	global_load_dwordx4 v[12:15], v[4:5], off offset:64
	global_load_dwordx4 v[8:11], v[4:5], off offset:128
	s_nop 0
	global_load_dwordx4 v[4:7], v[4:5], off offset:192
	ds_read_b128 v[102:105], v87 offset:34816
	ds_read_b128 v[106:109], v87 offset:34832
	ds_read_b128 v[110:113], v87 offset:34848
	ds_read_b128 v[114:117], v87 offset:34864
	s_waitcnt lgkmcnt(3)
	v_max_u32_e32 v61, v102, v103
	v_max_u32_e32 v77, v104, v105
	s_waitcnt lgkmcnt(2)
	v_max_u32_e32 v78, v108, v109
	ds_read_b128 v[102:105], v87 offset:34880
	v_max3_u32 v78, v106, v107, v78
	ds_read_b128 v[106:109], v87 offset:34896
	v_max3_u32 v61, v61, v77, v78
	s_waitcnt lgkmcnt(3)
	v_max_u32_e32 v77, v112, v113
	s_waitcnt lgkmcnt(2)
	v_max_u32_e32 v78, v116, v117
	v_max3_u32 v77, v110, v111, v77
	v_max3_u32 v78, v114, v115, v78
	v_max3_u32 v61, v61, v77, v78
	s_waitcnt lgkmcnt(1)
	v_max_u32_e32 v77, v104, v105
	v_max3_u32 v77, v102, v103, v77
	ds_read_b128 v[102:105], v87 offset:34912
	s_waitcnt lgkmcnt(1)
	v_max_u32_e32 v78, v108, v109
	ds_read_b128 v[108:111], v87 offset:34928
	v_max3_u32 v78, v106, v107, v78
	v_max3_u32 v61, v61, v77, v78
	s_waitcnt lgkmcnt(1)
	v_max_u32_e32 v77, v104, v105
	v_max3_u32 v77, v102, v103, v77
	s_waitcnt lgkmcnt(0)
	v_max_u32_e32 v78, v110, v111
	v_max3_u32 v78, v108, v109, v78
	v_max3_u32 v112, v61, v77, v78
	s_nop 1
	v_mov_b32_dpp v61, v112 quad_perm:[1,0,3,2] row_mask:0xf bank_mask:0xf
	s_waitcnt lgkmcnt(0)
	v_max_u32_e32 v61, v112, v61
	s_nop 1
	v_mov_b32_dpp v77, v61 quad_perm:[2,3,0,1] row_mask:0xf bank_mask:0xf
	s_waitcnt lgkmcnt(0)
	v_max_u32_e32 v61, v61, v77
	v_not_b32_e32 v77, v61
	v_bfe_u32 v77, v77, 5, 2
	v_cmp_eq_u32_e32 vcc, v77, v83
	s_and_saveexec_b64 s[28:29], vcc
	s_cbranch_execz .LBB0_763
	v_bitop3_b32 v77, v61, s44, v61 bitop3:0xc
	v_lshl_add_u32 v78, v77, 2, v85
	ds_write_b32 v78, v53 offset:34816
	ds_write_b8 v86, v77 offset:16
	ds_read_b128 v[102:105], v87 offset:34816
	ds_read_b128 v[106:109], v87 offset:34832
	ds_read_b128 v[110:113], v87 offset:34848
	ds_read_b128 v[114:117], v87 offset:34864
	ds_read_b128 v[118:121], v87 offset:34880
	ds_read_b128 v[122:125], v87 offset:34896
	ds_read_b128 v[126:129], v87 offset:34912
	ds_read_b128 v[130:133], v87 offset:34928
	s_waitcnt lgkmcnt(6)
	v_max_u32_e32 v80, v108, v109
	v_max_u32_e32 v77, v102, v103
	v_max_u32_e32 v78, v104, v105
	v_max3_u32 v80, v106, v107, v80
	v_max3_u32 v77, v77, v78, v80
	s_waitcnt lgkmcnt(5)
	v_max_u32_e32 v78, v112, v113
	s_waitcnt lgkmcnt(4)
	v_max_u32_e32 v80, v116, v117
	v_max3_u32 v78, v110, v111, v78
	v_max3_u32 v80, v114, v115, v80
	v_max3_u32 v77, v77, v78, v80
	s_waitcnt lgkmcnt(3)
	v_max_u32_e32 v78, v120, v121
	s_waitcnt lgkmcnt(2)
	v_max_u32_e32 v80, v124, v125
	v_max3_u32 v78, v118, v119, v78
	v_max3_u32 v80, v122, v123, v80
	v_max3_u32 v77, v77, v78, v80
	s_waitcnt lgkmcnt(1)
	v_max_u32_e32 v78, v128, v129
	s_waitcnt lgkmcnt(0)
	v_max_u32_e32 v80, v132, v133
	v_max3_u32 v78, v126, v127, v78
	v_max3_u32 v80, v130, v131, v80
	v_max3_u32 v112, v77, v78, v80
.LBB0_763:
	s_or_b64 exec, exec, s[28:29]
	s_nop 1
	v_mov_b32_dpp v77, v112 quad_perm:[1,0,3,2] row_mask:0xf bank_mask:0xf
	s_waitcnt lgkmcnt(0)
	v_max_u32_e32 v77, v112, v77
	s_nop 1
	v_mov_b32_dpp v78, v77 quad_perm:[2,3,0,1] row_mask:0xf bank_mask:0xf
	s_waitcnt lgkmcnt(0)
	v_max_u32_e32 v77, v77, v78
	v_not_b32_e32 v78, v77
	v_bfe_u32 v78, v78, 5, 2
	v_cmp_eq_u32_e32 vcc, v78, v83
	s_and_saveexec_b64 s[28:29], vcc
	s_cbranch_execz .LBB0_765
	v_bitop3_b32 v78, v77, s44, v77 bitop3:0xc
	v_lshl_add_u32 v80, v78, 2, v85
	ds_write_b32 v80, v53 offset:34816
	ds_write_b8 v86, v78 offset:17
	ds_read_b128 v[102:105], v87 offset:34816
	ds_read_b128 v[106:109], v87 offset:34832
	ds_read_b128 v[110:113], v87 offset:34848
	ds_read_b128 v[114:117], v87 offset:34864
	ds_read_b128 v[118:121], v87 offset:34880
	ds_read_b128 v[122:125], v87 offset:34896
	ds_read_b128 v[126:129], v87 offset:34912
	ds_read_b128 v[130:133], v87 offset:34928
	s_waitcnt lgkmcnt(6)
	v_max_u32_e32 v81, v108, v109
	v_max_u32_e32 v78, v102, v103
	v_max_u32_e32 v80, v104, v105
	v_max3_u32 v81, v106, v107, v81
	v_max3_u32 v78, v78, v80, v81
	s_waitcnt lgkmcnt(5)
	v_max_u32_e32 v80, v112, v113
	s_waitcnt lgkmcnt(4)
	v_max_u32_e32 v81, v116, v117
	v_max3_u32 v80, v110, v111, v80
	v_max3_u32 v81, v114, v115, v81
	v_max3_u32 v78, v78, v80, v81
	s_waitcnt lgkmcnt(3)
	v_max_u32_e32 v80, v120, v121
	s_waitcnt lgkmcnt(2)
	v_max_u32_e32 v81, v124, v125
	v_max3_u32 v80, v118, v119, v80
	v_max3_u32 v81, v122, v123, v81
	v_max3_u32 v78, v78, v80, v81
	s_waitcnt lgkmcnt(1)
	v_max_u32_e32 v80, v128, v129
	s_waitcnt lgkmcnt(0)
	v_max_u32_e32 v81, v132, v133
	v_max3_u32 v80, v126, v127, v80
	v_max3_u32 v81, v130, v131, v81
	v_max3_u32 v112, v78, v80, v81
.LBB0_765:
	s_or_b64 exec, exec, s[28:29]
	s_nop 1
	v_mov_b32_dpp v78, v112 quad_perm:[1,0,3,2] row_mask:0xf bank_mask:0xf
	s_waitcnt lgkmcnt(0)
	v_max_u32_e32 v78, v112, v78
	s_nop 1
	v_mov_b32_dpp v80, v78 quad_perm:[2,3,0,1] row_mask:0xf bank_mask:0xf
	s_waitcnt lgkmcnt(0)
	v_max_u32_e32 v78, v78, v80
	v_not_b32_e32 v80, v78
	v_bfe_u32 v80, v80, 5, 2
	v_cmp_eq_u32_e32 vcc, v80, v83
	s_and_saveexec_b64 s[28:29], vcc
	s_cbranch_execz .LBB0_767
	v_bitop3_b32 v80, v78, s44, v78 bitop3:0xc
	v_lshl_add_u32 v81, v80, 2, v85
	ds_write_b32 v81, v53 offset:34816
	ds_write_b8 v86, v80 offset:18
	ds_read_b128 v[102:105], v87 offset:34816
	ds_read_b128 v[106:109], v87 offset:34832
	ds_read_b128 v[110:113], v87 offset:34848
	ds_read_b128 v[114:117], v87 offset:34864
	ds_read_b128 v[118:121], v87 offset:34880
	ds_read_b128 v[122:125], v87 offset:34896
	ds_read_b128 v[126:129], v87 offset:34912
	ds_read_b128 v[130:133], v87 offset:34928
	s_waitcnt lgkmcnt(7)
	v_max_u32_e32 v80, v102, v103
	s_waitcnt lgkmcnt(6)
	v_max_u32_e32 v102, v108, v109
	v_max_u32_e32 v81, v104, v105
	v_max3_u32 v102, v106, v107, v102
	v_max3_u32 v80, v80, v81, v102
	s_waitcnt lgkmcnt(5)
	v_max_u32_e32 v81, v112, v113
	s_waitcnt lgkmcnt(4)
	v_max_u32_e32 v102, v116, v117
	v_max3_u32 v81, v110, v111, v81
	v_max3_u32 v102, v114, v115, v102
	v_max3_u32 v80, v80, v81, v102
	s_waitcnt lgkmcnt(3)
	v_max_u32_e32 v81, v120, v121
	s_waitcnt lgkmcnt(2)
	v_max_u32_e32 v102, v124, v125
	v_max3_u32 v81, v118, v119, v81
	v_max3_u32 v102, v122, v123, v102
	v_max3_u32 v80, v80, v81, v102
	s_waitcnt lgkmcnt(1)
	v_max_u32_e32 v81, v128, v129
	s_waitcnt lgkmcnt(0)
	v_max_u32_e32 v102, v132, v133
	v_max3_u32 v81, v126, v127, v81
	v_max3_u32 v102, v130, v131, v102
	v_max3_u32 v112, v80, v81, v102
.LBB0_767:
	s_or_b64 exec, exec, s[28:29]
	s_nop 1
	v_mov_b32_dpp v80, v112 quad_perm:[1,0,3,2] row_mask:0xf bank_mask:0xf
	s_waitcnt lgkmcnt(0)
	v_max_u32_e32 v80, v112, v80
	s_nop 1
	v_mov_b32_dpp v81, v80 quad_perm:[2,3,0,1] row_mask:0xf bank_mask:0xf
	s_waitcnt lgkmcnt(0)
	v_max_u32_e32 v80, v80, v81
	v_not_b32_e32 v81, v80
	v_bfe_u32 v81, v81, 5, 2
	v_cmp_eq_u32_e32 vcc, v81, v83
	s_and_saveexec_b64 s[28:29], vcc
	s_cbranch_execz .LBB0_769
	v_bitop3_b32 v81, v80, s44, v80 bitop3:0xc
	v_lshl_add_u32 v102, v81, 2, v85
	ds_write_b32 v102, v53 offset:34816
	ds_write_b8 v86, v81 offset:19
	ds_read_b128 v[102:105], v87 offset:34816
	ds_read_b128 v[106:109], v87 offset:34832
	ds_read_b128 v[110:113], v87 offset:34848
	ds_read_b128 v[114:117], v87 offset:34864
	ds_read_b128 v[118:121], v87 offset:34880
	ds_read_b128 v[122:125], v87 offset:34896
	ds_read_b128 v[126:129], v87 offset:34912
	ds_read_b128 v[130:133], v87 offset:34928
	s_waitcnt lgkmcnt(7)
	v_max_u32_e32 v81, v102, v103
	s_waitcnt lgkmcnt(6)
	v_max_u32_e32 v103, v108, v109
	v_max_u32_e32 v102, v104, v105
	v_max3_u32 v103, v106, v107, v103
	v_max3_u32 v81, v81, v102, v103
	s_waitcnt lgkmcnt(5)
	v_max_u32_e32 v102, v112, v113
	s_waitcnt lgkmcnt(4)
	v_max_u32_e32 v103, v116, v117
	v_max3_u32 v102, v110, v111, v102
	v_max3_u32 v103, v114, v115, v103
	v_max3_u32 v81, v81, v102, v103
	s_waitcnt lgkmcnt(3)
	v_max_u32_e32 v102, v120, v121
	s_waitcnt lgkmcnt(2)
	v_max_u32_e32 v103, v124, v125
	v_max3_u32 v102, v118, v119, v102
	v_max3_u32 v103, v122, v123, v103
	v_max3_u32 v81, v81, v102, v103
	s_waitcnt lgkmcnt(1)
	v_max_u32_e32 v102, v128, v129
	s_waitcnt lgkmcnt(0)
	v_max_u32_e32 v103, v132, v133
	v_max3_u32 v102, v126, v127, v102
	v_max3_u32 v103, v130, v131, v103
	v_max3_u32 v112, v81, v102, v103
.LBB0_769:
	s_or_b64 exec, exec, s[28:29]
	s_nop 1
	v_mov_b32_dpp v81, v112 quad_perm:[1,0,3,2] row_mask:0xf bank_mask:0xf
	s_waitcnt lgkmcnt(0)
	v_max_u32_e32 v81, v112, v81
	s_nop 1
	v_mov_b32_dpp v102, v81 quad_perm:[2,3,0,1] row_mask:0xf bank_mask:0xf
	s_waitcnt lgkmcnt(0)
	v_max_u32_e32 v81, v81, v102
	v_not_b32_e32 v102, v81
	v_bfe_u32 v102, v102, 5, 2
	v_cmp_eq_u32_e32 vcc, v102, v83
	s_and_saveexec_b64 s[28:29], vcc
	s_cbranch_execz .LBB0_771
	v_bitop3_b32 v102, v81, s44, v81 bitop3:0xc
	v_lshl_add_u32 v103, v102, 2, v85
	ds_write_b32 v103, v53 offset:34816
	ds_write_b8 v86, v102 offset:20
	ds_read_b128 v[102:105], v87 offset:34816
	ds_read_b128 v[106:109], v87 offset:34832
	ds_read_b128 v[110:113], v87 offset:34848
	ds_read_b128 v[114:117], v87 offset:34864
	ds_read_b128 v[118:121], v87 offset:34880
	ds_read_b128 v[122:125], v87 offset:34896
	ds_read_b128 v[126:129], v87 offset:34912
	ds_read_b128 v[130:133], v87 offset:34928
	s_waitcnt lgkmcnt(7)
	v_max_u32_e32 v102, v102, v103
	v_max_u32_e32 v103, v104, v105
	s_waitcnt lgkmcnt(6)
	v_max_u32_e32 v104, v108, v109
	v_max3_u32 v104, v106, v107, v104
	v_max3_u32 v102, v102, v103, v104
	s_waitcnt lgkmcnt(5)
	v_max_u32_e32 v103, v112, v113
	s_waitcnt lgkmcnt(4)
	v_max_u32_e32 v104, v116, v117
	v_max3_u32 v103, v110, v111, v103
	v_max3_u32 v104, v114, v115, v104
	v_max3_u32 v102, v102, v103, v104
	s_waitcnt lgkmcnt(3)
	v_max_u32_e32 v103, v120, v121
	s_waitcnt lgkmcnt(2)
	v_max_u32_e32 v104, v124, v125
	v_max3_u32 v103, v118, v119, v103
	v_max3_u32 v104, v122, v123, v104
	v_max3_u32 v102, v102, v103, v104
	s_waitcnt lgkmcnt(1)
	v_max_u32_e32 v103, v128, v129
	s_waitcnt lgkmcnt(0)
	v_max_u32_e32 v104, v132, v133
	v_max3_u32 v103, v126, v127, v103
	v_max3_u32 v104, v130, v131, v104
	v_max3_u32 v112, v102, v103, v104
.LBB0_771:
	s_or_b64 exec, exec, s[28:29]
	s_nop 1
	v_mov_b32_dpp v102, v112 quad_perm:[1,0,3,2] row_mask:0xf bank_mask:0xf
	s_waitcnt lgkmcnt(0)
	v_max_u32_e32 v102, v112, v102
	s_nop 1
	v_mov_b32_dpp v103, v102 quad_perm:[2,3,0,1] row_mask:0xf bank_mask:0xf
	s_waitcnt lgkmcnt(0)
	v_max_u32_e32 v102, v102, v103
	v_not_b32_e32 v103, v102
	v_bfe_u32 v103, v103, 5, 2
	v_cmp_eq_u32_e32 vcc, v103, v83
	s_and_saveexec_b64 s[28:29], vcc
	s_cbranch_execz .LBB0_773
	v_bitop3_b32 v103, v102, s44, v102 bitop3:0xc
	v_lshl_add_u32 v104, v103, 2, v85
	ds_write_b32 v104, v53 offset:34816
	ds_write_b8 v86, v103 offset:21
	ds_read_b128 v[104:107], v87 offset:34816
	ds_read_b128 v[108:111], v87 offset:34832
	ds_read_b128 v[112:115], v87 offset:34848
	ds_read_b128 v[116:119], v87 offset:34864
	ds_read_b128 v[120:123], v87 offset:34880
	ds_read_b128 v[124:127], v87 offset:34896
	ds_read_b128 v[128:131], v87 offset:34912
	ds_read_b128 v[132:135], v87 offset:34928
	s_waitcnt lgkmcnt(7)
	v_max_u32_e32 v103, v104, v105
	s_waitcnt lgkmcnt(6)
	v_max_u32_e32 v105, v110, v111
	v_max_u32_e32 v104, v106, v107
	v_max3_u32 v105, v108, v109, v105
	v_max3_u32 v103, v103, v104, v105
	s_waitcnt lgkmcnt(5)
	v_max_u32_e32 v104, v114, v115
	s_waitcnt lgkmcnt(4)
	v_max_u32_e32 v105, v118, v119
	v_max3_u32 v104, v112, v113, v104
	v_max3_u32 v105, v116, v117, v105
	v_max3_u32 v103, v103, v104, v105
	s_waitcnt lgkmcnt(3)
	v_max_u32_e32 v104, v122, v123
	s_waitcnt lgkmcnt(2)
	v_max_u32_e32 v105, v126, v127
	v_max3_u32 v104, v120, v121, v104
	v_max3_u32 v105, v124, v125, v105
	v_max3_u32 v103, v103, v104, v105
	s_waitcnt lgkmcnt(1)
	v_max_u32_e32 v104, v130, v131
	s_waitcnt lgkmcnt(0)
	v_max_u32_e32 v105, v134, v135
	v_max3_u32 v104, v128, v129, v104
	v_max3_u32 v105, v132, v133, v105
	v_max3_u32 v112, v103, v104, v105
.LBB0_773:
	s_or_b64 exec, exec, s[28:29]
	s_nop 1
	v_mov_b32_dpp v103, v112 quad_perm:[1,0,3,2] row_mask:0xf bank_mask:0xf
	s_waitcnt lgkmcnt(0)
	v_max_u32_e32 v103, v112, v103
	s_nop 1
	v_mov_b32_dpp v104, v103 quad_perm:[2,3,0,1] row_mask:0xf bank_mask:0xf
	s_waitcnt lgkmcnt(0)
	v_max_u32_e32 v103, v103, v104
	v_not_b32_e32 v104, v103
	v_bfe_u32 v104, v104, 5, 2
	v_cmp_eq_u32_e32 vcc, v104, v83
	s_and_saveexec_b64 s[28:29], vcc
	s_cbranch_execz .LBB0_775
	v_bitop3_b32 v104, v103, s44, v103 bitop3:0xc
	v_lshl_add_u32 v105, v104, 2, v85
	ds_write_b32 v105, v53 offset:34816
	ds_write_b8 v86, v104 offset:22
	ds_read_b128 v[104:107], v87 offset:34816
	ds_read_b128 v[108:111], v87 offset:34832
	ds_read_b128 v[112:115], v87 offset:34848
	ds_read_b128 v[116:119], v87 offset:34864
	ds_read_b128 v[120:123], v87 offset:34880
	ds_read_b128 v[124:127], v87 offset:34896
	ds_read_b128 v[128:131], v87 offset:34912
	ds_read_b128 v[132:135], v87 offset:34928
	s_waitcnt lgkmcnt(7)
	v_max_u32_e32 v104, v104, v105
	v_max_u32_e32 v105, v106, v107
	s_waitcnt lgkmcnt(6)
	v_max_u32_e32 v106, v110, v111
	v_max3_u32 v106, v108, v109, v106
	v_max3_u32 v104, v104, v105, v106
	s_waitcnt lgkmcnt(5)
	v_max_u32_e32 v105, v114, v115
	s_waitcnt lgkmcnt(4)
	v_max_u32_e32 v106, v118, v119
	v_max3_u32 v105, v112, v113, v105
	v_max3_u32 v106, v116, v117, v106
	v_max3_u32 v104, v104, v105, v106
	s_waitcnt lgkmcnt(3)
	v_max_u32_e32 v105, v122, v123
	s_waitcnt lgkmcnt(2)
	v_max_u32_e32 v106, v126, v127
	v_max3_u32 v105, v120, v121, v105
	v_max3_u32 v106, v124, v125, v106
	v_max3_u32 v104, v104, v105, v106
	s_waitcnt lgkmcnt(1)
	v_max_u32_e32 v105, v130, v131
	s_waitcnt lgkmcnt(0)
	v_max_u32_e32 v106, v134, v135
	v_max3_u32 v105, v128, v129, v105
	v_max3_u32 v106, v132, v133, v106
	v_max3_u32 v112, v104, v105, v106
.LBB0_775:
	s_or_b64 exec, exec, s[28:29]
	s_nop 1
	v_mov_b32_dpp v104, v112 quad_perm:[1,0,3,2] row_mask:0xf bank_mask:0xf
	s_waitcnt lgkmcnt(0)
	v_max_u32_e32 v104, v112, v104
	s_nop 1
	v_mov_b32_dpp v105, v104 quad_perm:[2,3,0,1] row_mask:0xf bank_mask:0xf
	s_waitcnt lgkmcnt(0)
	v_max_u32_e32 v104, v104, v105
	v_not_b32_e32 v105, v104
	v_bfe_u32 v105, v105, 5, 2
	v_cmp_eq_u32_e32 vcc, v105, v83
	s_and_saveexec_b64 s[28:29], vcc
	s_cbranch_execz .LBB0_777
	v_bitop3_b32 v105, v104, s44, v104 bitop3:0xc
	v_lshl_add_u32 v106, v105, 2, v85
	ds_write_b32 v106, v53 offset:34816
	ds_write_b8 v86, v105 offset:23
	ds_read_b128 v[106:109], v87 offset:34816
	ds_read_b128 v[110:113], v87 offset:34832
	ds_read_b128 v[114:117], v87 offset:34848
	ds_read_b128 v[118:121], v87 offset:34864
	ds_read_b128 v[122:125], v87 offset:34880
	ds_read_b128 v[126:129], v87 offset:34896
	ds_read_b128 v[130:133], v87 offset:34912
	ds_read_b128 v[134:137], v87 offset:34928
	s_waitcnt lgkmcnt(7)
	v_max_u32_e32 v105, v106, v107
	s_waitcnt lgkmcnt(6)
	v_max_u32_e32 v107, v112, v113
	v_max_u32_e32 v106, v108, v109
	v_max3_u32 v107, v110, v111, v107
	v_max3_u32 v105, v105, v106, v107
	s_waitcnt lgkmcnt(5)
	v_max_u32_e32 v106, v116, v117
	s_waitcnt lgkmcnt(4)
	v_max_u32_e32 v107, v120, v121
	v_max3_u32 v106, v114, v115, v106
	v_max3_u32 v107, v118, v119, v107
	v_max3_u32 v105, v105, v106, v107
	s_waitcnt lgkmcnt(3)
	v_max_u32_e32 v106, v124, v125
	s_waitcnt lgkmcnt(2)
	v_max_u32_e32 v107, v128, v129
	v_max3_u32 v106, v122, v123, v106
	v_max3_u32 v107, v126, v127, v107
	v_max3_u32 v105, v105, v106, v107
	s_waitcnt lgkmcnt(1)
	v_max_u32_e32 v106, v132, v133
	s_waitcnt lgkmcnt(0)
	v_max_u32_e32 v107, v136, v137
	v_max3_u32 v106, v130, v131, v106
	v_max3_u32 v107, v134, v135, v107
	v_max3_u32 v112, v105, v106, v107
.LBB0_777:
	s_or_b64 exec, exec, s[28:29]
	s_nop 1
	v_mov_b32_dpp v105, v112 quad_perm:[1,0,3,2] row_mask:0xf bank_mask:0xf
	s_waitcnt lgkmcnt(0)
	v_max_u32_e32 v105, v112, v105
	s_nop 1
	v_mov_b32_dpp v106, v105 quad_perm:[2,3,0,1] row_mask:0xf bank_mask:0xf
	s_waitcnt lgkmcnt(0)
	v_max_u32_e32 v105, v105, v106
	v_not_b32_e32 v106, v105
	v_bfe_u32 v106, v106, 5, 2
	v_cmp_eq_u32_e32 vcc, v106, v83
	s_and_saveexec_b64 s[28:29], vcc
	s_cbranch_execz .LBB0_779
	v_bitop3_b32 v106, v105, s44, v105 bitop3:0xc
	v_lshl_add_u32 v107, v106, 2, v85
	ds_write_b32 v107, v53 offset:34816
	ds_write_b8 v86, v106 offset:24
	ds_read_b128 v[106:109], v87 offset:34816
	ds_read_b128 v[110:113], v87 offset:34832
	ds_read_b128 v[114:117], v87 offset:34848
	ds_read_b128 v[118:121], v87 offset:34864
	ds_read_b128 v[122:125], v87 offset:34880
	ds_read_b128 v[126:129], v87 offset:34896
	ds_read_b128 v[130:133], v87 offset:34912
	ds_read_b128 v[134:137], v87 offset:34928
	s_waitcnt lgkmcnt(7)
	v_max_u32_e32 v106, v106, v107
	v_max_u32_e32 v107, v108, v109
	s_waitcnt lgkmcnt(6)
	v_max_u32_e32 v108, v112, v113
	v_max3_u32 v108, v110, v111, v108
	v_max3_u32 v106, v106, v107, v108
	s_waitcnt lgkmcnt(5)
	v_max_u32_e32 v107, v116, v117
	s_waitcnt lgkmcnt(4)
	v_max_u32_e32 v108, v120, v121
	v_max3_u32 v107, v114, v115, v107
	v_max3_u32 v108, v118, v119, v108
	v_max3_u32 v106, v106, v107, v108
	s_waitcnt lgkmcnt(3)
	v_max_u32_e32 v107, v124, v125
	s_waitcnt lgkmcnt(2)
	v_max_u32_e32 v108, v128, v129
	v_max3_u32 v107, v122, v123, v107
	v_max3_u32 v108, v126, v127, v108
	v_max3_u32 v106, v106, v107, v108
	s_waitcnt lgkmcnt(1)
	v_max_u32_e32 v107, v132, v133
	s_waitcnt lgkmcnt(0)
	v_max_u32_e32 v108, v136, v137
	v_max3_u32 v107, v130, v131, v107
	v_max3_u32 v108, v134, v135, v108
	v_max3_u32 v112, v106, v107, v108
.LBB0_779:
	s_or_b64 exec, exec, s[28:29]
	s_nop 1
	v_mov_b32_dpp v106, v112 quad_perm:[1,0,3,2] row_mask:0xf bank_mask:0xf
	s_waitcnt lgkmcnt(0)
	v_max_u32_e32 v106, v112, v106
	s_nop 1
	v_mov_b32_dpp v107, v106 quad_perm:[2,3,0,1] row_mask:0xf bank_mask:0xf
	s_waitcnt lgkmcnt(0)
	v_max_u32_e32 v106, v106, v107
	v_not_b32_e32 v107, v106
	v_bfe_u32 v107, v107, 5, 2
	v_cmp_eq_u32_e32 vcc, v107, v83
	s_and_saveexec_b64 s[28:29], vcc
	s_cbranch_execz .LBB0_781
	v_bitop3_b32 v107, v106, s44, v106 bitop3:0xc
	v_lshl_add_u32 v108, v107, 2, v85
	ds_write_b32 v108, v53 offset:34816
	ds_write_b8 v86, v107 offset:25
	ds_read_b128 v[108:111], v87 offset:34816
	ds_read_b128 v[112:115], v87 offset:34832
	ds_read_b128 v[116:119], v87 offset:34848
	ds_read_b128 v[120:123], v87 offset:34864
	ds_read_b128 v[124:127], v87 offset:34880
	ds_read_b128 v[128:131], v87 offset:34896
	ds_read_b128 v[132:135], v87 offset:34912
	ds_read_b128 v[136:139], v87 offset:34928
	s_waitcnt lgkmcnt(7)
	v_max_u32_e32 v107, v108, v109
	s_waitcnt lgkmcnt(6)
	v_max_u32_e32 v109, v114, v115
	v_max_u32_e32 v108, v110, v111
	v_max3_u32 v109, v112, v113, v109
	v_max3_u32 v107, v107, v108, v109
	s_waitcnt lgkmcnt(5)
	v_max_u32_e32 v108, v118, v119
	s_waitcnt lgkmcnt(4)
	v_max_u32_e32 v109, v122, v123
	v_max3_u32 v108, v116, v117, v108
	v_max3_u32 v109, v120, v121, v109
	v_max3_u32 v107, v107, v108, v109
	s_waitcnt lgkmcnt(3)
	v_max_u32_e32 v108, v126, v127
	s_waitcnt lgkmcnt(2)
	v_max_u32_e32 v109, v130, v131
	v_max3_u32 v108, v124, v125, v108
	v_max3_u32 v109, v128, v129, v109
	v_max3_u32 v107, v107, v108, v109
	s_waitcnt lgkmcnt(1)
	v_max_u32_e32 v108, v134, v135
	s_waitcnt lgkmcnt(0)
	v_max_u32_e32 v109, v138, v139
	v_max3_u32 v108, v132, v133, v108
	v_max3_u32 v109, v136, v137, v109
	v_max3_u32 v112, v107, v108, v109
.LBB0_781:
	s_or_b64 exec, exec, s[28:29]
	s_nop 1
	v_mov_b32_dpp v107, v112 quad_perm:[1,0,3,2] row_mask:0xf bank_mask:0xf
	s_waitcnt lgkmcnt(0)
	v_max_u32_e32 v107, v112, v107
	s_nop 1
	v_mov_b32_dpp v108, v107 quad_perm:[2,3,0,1] row_mask:0xf bank_mask:0xf
	s_waitcnt lgkmcnt(0)
	v_max_u32_e32 v107, v107, v108
	v_not_b32_e32 v108, v107
	v_bfe_u32 v108, v108, 5, 2
	v_cmp_eq_u32_e32 vcc, v108, v83
	s_and_saveexec_b64 s[28:29], vcc
	s_cbranch_execz .LBB0_783
	v_bitop3_b32 v108, v107, s44, v107 bitop3:0xc
	v_lshl_add_u32 v109, v108, 2, v85
	ds_write_b32 v109, v53 offset:34816
	ds_write_b8 v86, v108 offset:26
	ds_read_b128 v[108:111], v87 offset:34816
	ds_read_b128 v[112:115], v87 offset:34832
	ds_read_b128 v[116:119], v87 offset:34848
	ds_read_b128 v[120:123], v87 offset:34864
	ds_read_b128 v[124:127], v87 offset:34880
	ds_read_b128 v[128:131], v87 offset:34896
	ds_read_b128 v[132:135], v87 offset:34912
	ds_read_b128 v[136:139], v87 offset:34928
	s_waitcnt lgkmcnt(7)
	v_max_u32_e32 v108, v108, v109
	v_max_u32_e32 v109, v110, v111
	s_waitcnt lgkmcnt(6)
	v_max_u32_e32 v110, v114, v115
	v_max3_u32 v110, v112, v113, v110
	v_max3_u32 v108, v108, v109, v110
	s_waitcnt lgkmcnt(5)
	v_max_u32_e32 v109, v118, v119
	s_waitcnt lgkmcnt(4)
	v_max_u32_e32 v110, v122, v123
	v_max3_u32 v109, v116, v117, v109
	v_max3_u32 v110, v120, v121, v110
	v_max3_u32 v108, v108, v109, v110
	s_waitcnt lgkmcnt(3)
	v_max_u32_e32 v109, v126, v127
	s_waitcnt lgkmcnt(2)
	v_max_u32_e32 v110, v130, v131
	v_max3_u32 v109, v124, v125, v109
	v_max3_u32 v110, v128, v129, v110
	v_max3_u32 v108, v108, v109, v110
	s_waitcnt lgkmcnt(1)
	v_max_u32_e32 v109, v134, v135
	s_waitcnt lgkmcnt(0)
	v_max_u32_e32 v110, v138, v139
	v_max3_u32 v109, v132, v133, v109
	v_max3_u32 v110, v136, v137, v110
	v_max3_u32 v112, v108, v109, v110
.LBB0_783:
	s_or_b64 exec, exec, s[28:29]
	s_nop 1
	v_mov_b32_dpp v108, v112 quad_perm:[1,0,3,2] row_mask:0xf bank_mask:0xf
	s_waitcnt lgkmcnt(0)
	v_max_u32_e32 v108, v112, v108
	s_nop 1
	v_mov_b32_dpp v109, v108 quad_perm:[2,3,0,1] row_mask:0xf bank_mask:0xf
	s_waitcnt lgkmcnt(0)
	v_max_u32_e32 v108, v108, v109
	v_not_b32_e32 v109, v108
	v_bfe_u32 v109, v109, 5, 2
	v_cmp_eq_u32_e32 vcc, v109, v83
	s_and_saveexec_b64 s[28:29], vcc
	s_cbranch_execz .LBB0_785
	v_bitop3_b32 v109, v108, s44, v108 bitop3:0xc
	v_lshl_add_u32 v110, v109, 2, v85
	ds_write_b32 v110, v53 offset:34816
	ds_write_b8 v86, v109 offset:27
	ds_read_b128 v[110:113], v87 offset:34816
	ds_read_b128 v[114:117], v87 offset:34832
	ds_read_b128 v[118:121], v87 offset:34848
	ds_read_b128 v[122:125], v87 offset:34864
	ds_read_b128 v[126:129], v87 offset:34880
	ds_read_b128 v[130:133], v87 offset:34896
	ds_read_b128 v[134:137], v87 offset:34912
	ds_read_b128 v[138:141], v87 offset:34928
	s_waitcnt lgkmcnt(7)
	v_max_u32_e32 v109, v110, v111
	s_waitcnt lgkmcnt(6)
	v_max_u32_e32 v111, v116, v117
	v_max_u32_e32 v110, v112, v113
	v_max3_u32 v111, v114, v115, v111
	v_max3_u32 v109, v109, v110, v111
	s_waitcnt lgkmcnt(5)
	v_max_u32_e32 v110, v120, v121
	s_waitcnt lgkmcnt(4)
	v_max_u32_e32 v111, v124, v125
	v_max3_u32 v110, v118, v119, v110
	v_max3_u32 v111, v122, v123, v111
	v_max3_u32 v109, v109, v110, v111
	s_waitcnt lgkmcnt(3)
	v_max_u32_e32 v110, v128, v129
	s_waitcnt lgkmcnt(2)
	v_max_u32_e32 v111, v132, v133
	v_max3_u32 v110, v126, v127, v110
	v_max3_u32 v111, v130, v131, v111
	v_max3_u32 v109, v109, v110, v111
	s_waitcnt lgkmcnt(1)
	v_max_u32_e32 v110, v136, v137
	s_waitcnt lgkmcnt(0)
	v_max_u32_e32 v111, v140, v141
	v_max3_u32 v110, v134, v135, v110
	v_max3_u32 v111, v138, v139, v111
	v_max3_u32 v112, v109, v110, v111
.LBB0_785:
	s_or_b64 exec, exec, s[28:29]
	s_nop 1
	v_mov_b32_dpp v109, v112 quad_perm:[1,0,3,2] row_mask:0xf bank_mask:0xf
	s_waitcnt lgkmcnt(0)
	v_max_u32_e32 v109, v112, v109
	s_nop 1
	v_mov_b32_dpp v110, v109 quad_perm:[2,3,0,1] row_mask:0xf bank_mask:0xf
	s_waitcnt lgkmcnt(0)
	v_max_u32_e32 v109, v109, v110
	v_not_b32_e32 v110, v109
	v_bfe_u32 v110, v110, 5, 2
	v_cmp_eq_u32_e32 vcc, v110, v83
	s_and_saveexec_b64 s[28:29], vcc
	s_cbranch_execz .LBB0_787
	v_bitop3_b32 v110, v109, s44, v109 bitop3:0xc
	v_lshl_add_u32 v111, v110, 2, v85
	ds_write_b32 v111, v53 offset:34816
	ds_write_b8 v86, v110 offset:28
	ds_read_b128 v[110:113], v87 offset:34816
	ds_read_b128 v[114:117], v87 offset:34832
	ds_read_b128 v[118:121], v87 offset:34848
	ds_read_b128 v[122:125], v87 offset:34864
	ds_read_b128 v[126:129], v87 offset:34880
	ds_read_b128 v[130:133], v87 offset:34896
	ds_read_b128 v[134:137], v87 offset:34912
	ds_read_b128 v[138:141], v87 offset:34928
	s_waitcnt lgkmcnt(7)
	v_max_u32_e32 v110, v110, v111
	v_max_u32_e32 v111, v112, v113
	s_waitcnt lgkmcnt(6)
	v_max_u32_e32 v112, v116, v117
	v_max3_u32 v112, v114, v115, v112
	v_max3_u32 v110, v110, v111, v112
	s_waitcnt lgkmcnt(5)
	v_max_u32_e32 v111, v120, v121
	s_waitcnt lgkmcnt(4)
	v_max_u32_e32 v112, v124, v125
	v_max3_u32 v111, v118, v119, v111
	v_max3_u32 v112, v122, v123, v112
	v_max3_u32 v110, v110, v111, v112
	s_waitcnt lgkmcnt(3)
	v_max_u32_e32 v111, v128, v129
	s_waitcnt lgkmcnt(2)
	v_max_u32_e32 v112, v132, v133
	v_max3_u32 v111, v126, v127, v111
	v_max3_u32 v112, v130, v131, v112
	v_max3_u32 v110, v110, v111, v112
	s_waitcnt lgkmcnt(1)
	v_max_u32_e32 v111, v136, v137
	s_waitcnt lgkmcnt(0)
	v_max_u32_e32 v112, v140, v141
	v_max3_u32 v111, v134, v135, v111
	v_max3_u32 v112, v138, v139, v112
	v_max3_u32 v112, v110, v111, v112
.LBB0_787:
	s_or_b64 exec, exec, s[28:29]
	s_nop 1
	v_mov_b32_dpp v110, v112 quad_perm:[1,0,3,2] row_mask:0xf bank_mask:0xf
	s_waitcnt lgkmcnt(0)
	v_max_u32_e32 v110, v112, v110
	s_nop 1
	v_mov_b32_dpp v111, v110 quad_perm:[2,3,0,1] row_mask:0xf bank_mask:0xf
	s_waitcnt lgkmcnt(0)
	v_max_u32_e32 v110, v110, v111
	v_not_b32_e32 v111, v110
	v_bfe_u32 v111, v111, 5, 2
	v_cmp_eq_u32_e32 vcc, v111, v83
	s_and_saveexec_b64 s[28:29], vcc
	s_cbranch_execz .LBB0_789
	v_bitop3_b32 v111, v110, s44, v110 bitop3:0xc
	v_lshl_add_u32 v112, v111, 2, v85
	ds_write_b32 v112, v53 offset:34816
	ds_write_b8 v86, v111 offset:29
	ds_read_b128 v[112:115], v87 offset:34816
	ds_read_b128 v[116:119], v87 offset:34832
	ds_read_b128 v[120:123], v87 offset:34848
	ds_read_b128 v[124:127], v87 offset:34864
	ds_read_b128 v[128:131], v87 offset:34880
	ds_read_b128 v[132:135], v87 offset:34896
	ds_read_b128 v[136:139], v87 offset:34912
	ds_read_b128 v[140:143], v87 offset:34928
	s_waitcnt lgkmcnt(7)
	v_max_u32_e32 v111, v112, v113
	s_waitcnt lgkmcnt(6)
	v_max_u32_e32 v113, v118, v119
	v_max_u32_e32 v112, v114, v115
	v_max3_u32 v113, v116, v117, v113
	v_max3_u32 v111, v111, v112, v113
	s_waitcnt lgkmcnt(5)
	v_max_u32_e32 v112, v122, v123
	s_waitcnt lgkmcnt(4)
	v_max_u32_e32 v113, v126, v127
	v_max3_u32 v112, v120, v121, v112
	v_max3_u32 v113, v124, v125, v113
	v_max3_u32 v111, v111, v112, v113
	s_waitcnt lgkmcnt(3)
	v_max_u32_e32 v112, v130, v131
	s_waitcnt lgkmcnt(2)
	v_max_u32_e32 v113, v134, v135
	v_max3_u32 v112, v128, v129, v112
	v_max3_u32 v113, v132, v133, v113
	v_max3_u32 v111, v111, v112, v113
	s_waitcnt lgkmcnt(1)
	v_max_u32_e32 v112, v138, v139
	s_waitcnt lgkmcnt(0)
	v_max_u32_e32 v113, v142, v143
	v_max3_u32 v112, v136, v137, v112
	v_max3_u32 v113, v140, v141, v113
	v_max3_u32 v112, v111, v112, v113
.LBB0_789:
	s_or_b64 exec, exec, s[28:29]
	s_nop 1
	v_mov_b32_dpp v111, v112 quad_perm:[1,0,3,2] row_mask:0xf bank_mask:0xf
	s_waitcnt lgkmcnt(0)
	v_max_u32_e32 v111, v112, v111
	s_nop 1
	v_mov_b32_dpp v113, v111 quad_perm:[2,3,0,1] row_mask:0xf bank_mask:0xf
	s_waitcnt lgkmcnt(0)
	v_max_u32_e32 v111, v111, v113
	v_not_b32_e32 v113, v111
	v_bfe_u32 v113, v113, 5, 2
	v_cmp_eq_u32_e32 vcc, v113, v83
	s_and_saveexec_b64 s[28:29], vcc
	s_cbranch_execz .LBB0_791
	v_bitop3_b32 v112, v111, s44, v111 bitop3:0xc
	v_lshl_add_u32 v113, v112, 2, v85
	ds_write_b32 v113, v53 offset:34816
	ds_write_b8 v86, v112 offset:30
	ds_read_b128 v[112:115], v87 offset:34816
	ds_read_b128 v[116:119], v87 offset:34832
	ds_read_b128 v[120:123], v87 offset:34848
	ds_read_b128 v[124:127], v87 offset:34864
	ds_read_b128 v[128:131], v87 offset:34880
	ds_read_b128 v[132:135], v87 offset:34896
	ds_read_b128 v[136:139], v87 offset:34912
	ds_read_b128 v[140:143], v87 offset:34928
	s_waitcnt lgkmcnt(7)
	v_max_u32_e32 v112, v112, v113
	v_max_u32_e32 v113, v114, v115
	s_waitcnt lgkmcnt(6)
	v_max_u32_e32 v114, v118, v119
	v_max3_u32 v114, v116, v117, v114
	v_max3_u32 v112, v112, v113, v114
	s_waitcnt lgkmcnt(5)
	v_max_u32_e32 v113, v122, v123
	s_waitcnt lgkmcnt(4)
	v_max_u32_e32 v114, v126, v127
	v_max3_u32 v113, v120, v121, v113
	v_max3_u32 v114, v124, v125, v114
	v_max3_u32 v112, v112, v113, v114
	s_waitcnt lgkmcnt(3)
	v_max_u32_e32 v113, v130, v131
	s_waitcnt lgkmcnt(2)
	v_max_u32_e32 v114, v134, v135
	v_max3_u32 v113, v128, v129, v113
	v_max3_u32 v114, v132, v133, v114
	v_max3_u32 v112, v112, v113, v114
	s_waitcnt lgkmcnt(1)
	v_max_u32_e32 v113, v138, v139
	s_waitcnt lgkmcnt(0)
	v_max_u32_e32 v114, v142, v143
	v_max3_u32 v113, v136, v137, v113
	v_max3_u32 v114, v140, v141, v114
	v_max3_u32 v112, v112, v113, v114
.LBB0_791:
	s_or_b64 exec, exec, s[28:29]
	s_nop 1
	v_mov_b32_dpp v113, v112 quad_perm:[1,0,3,2] row_mask:0xf bank_mask:0xf
	s_waitcnt lgkmcnt(0)
	v_max_u32_e32 v112, v112, v113
	s_nop 1
	v_mov_b32_dpp v113, v112 quad_perm:[2,3,0,1] row_mask:0xf bank_mask:0xf
	s_waitcnt lgkmcnt(0)
	v_max_u32_e32 v112, v112, v113
	v_not_b32_e32 v113, v112
	v_bfe_u32 v113, v113, 5, 2
	v_cmp_eq_u32_e32 vcc, v113, v83
	s_and_saveexec_b64 s[28:29], vcc
	s_cbranch_execz .LBB0_793
	v_bitop3_b32 v113, v112, s44, v112 bitop3:0xc
	v_lshl_add_u32 v114, v113, 2, v85
	ds_write_b32 v114, v53 offset:34816
	ds_write_b8 v86, v113 offset:31

.LBB0_841:
	s_or_b64 exec, exec, s[28:29]
	v_cmp_gt_i32_e32 vcc, 0, v61
	v_mov_b32_e32 v106, 0
	s_nop 0
	v_cndmask_b32_e32 v64, -1, v101, vcc
	v_cmp_gt_i32_e32 vcc, 0, v77
	v_bitop3_b32 v64, v64, v61, s43 bitop3:0x78
	s_nop 0
	v_cndmask_b32_e32 v65, -1, v101, vcc
	v_cmp_lt_i32_e32 vcc, -1, v78
	v_bitop3_b32 v65, v65, v77, s43 bitop3:0x78
	s_nop 0
	v_cndmask_b32_e64 v66, v101, -1, vcc
	v_cmp_lt_i32_e32 vcc, -1, v80
	v_bitop3_b32 v66, v66, v78, s43 bitop3:0x78
	s_nop 0
	v_cndmask_b32_e64 v67, v101, -1, vcc
	v_cmp_lt_i32_e32 vcc, -1, v59
	v_bitop3_b32 v67, v67, v80, s43 bitop3:0x78
	s_nop 0
	v_cndmask_b32_e64 v61, v101, -1, vcc
	v_bitop3_b32 v68, v61, v59, s43 bitop3:0x78
	s_and_saveexec_b64 s[28:29], s[14:15]
	v_add_f32_e32 v59, v66, v68
	v_not_b32_e32 v61, v59
	v_or_b32_e32 v77, 0x80000000, v59
	v_cmp_gt_i32_e32 vcc, 0, v59
	s_nop 1
	v_cndmask_b32_e32 v59, v77, v61, vcc
	v_and_b32_e32 v59, 0xffffff00, v59
	v_or_b32_e32 v106, 0xbd, v59
	s_or_b64 exec, exec, s[28:29]
	v_pk_add_f32 v[108:109], v[64:65], v[68:69] op_sel_hi:[1,0]
	v_pk_add_f32 v[66:67], v[62:63], v[66:67] op_sel_hi:[0,1]
	v_and_b32_e32 v111, 0x7fffffff, v109
	v_and_b32_e32 v110, 0x7fffffff, v108
	v_xor_b32_e32 v59, -1, v109
	v_pk_add_f32 v[110:111], v[110:111], 0 neg_lo:[1,1] neg_hi:[1,1]
	v_cmp_gt_i32_e32 vcc, 0, v109
	v_xor_b32_e32 v61, -1, v108
	v_or_b32_e32 v107, 0x80000000, v67
	v_cndmask_b32_e32 v59, v111, v59, vcc
	v_cmp_gt_i32_e32 vcc, 0, v108
	v_and_b32_e32 v59, 0xffffff00, v59
	v_sub_u32_e32 v59, v59, v57
	v_cndmask_b32_e32 v61, v110, v61, vcc
	v_cmp_lt_i32_e32 vcc, -1, v69
	v_add_u32_e32 v77, 0xbe, v59
	v_pk_add_f32 v[108:109], v[62:63], v[64:65] op_sel_hi:[0,1]
	v_cndmask_b32_e64 v59, v101, -1, vcc
	v_not_b32_e32 v62, v67
	v_cmp_gt_i32_e32 vcc, 0, v67
	v_bitop3_b32 v68, v59, v69, s43 bitop3:0x78
	v_not_b32_e32 v59, v66
	v_or_b32_e32 v80, 0x80000000, v66
	v_cndmask_b32_e32 v62, v107, v62, vcc
	v_cmp_gt_i32_e32 vcc, 0, v66
	v_not_b32_e32 v78, v109
	v_or_b32_e32 v111, 0x80000000, v109
	v_cndmask_b32_e32 v59, v80, v59, vcc
	v_cmp_gt_i32_e32 vcc, 0, v109
	v_not_b32_e32 v69, v108
	v_or_b32_e32 v110, 0x80000000, v108
	v_cndmask_b32_e32 v66, v111, v78, vcc
	v_cmp_gt_i32_e32 vcc, 0, v108
	v_and_b32_e32 v59, 0xffffff00, v59
	v_sub_u32_e32 v59, v59, v2
	v_cndmask_b32_e32 v67, v110, v69, vcc
	v_cmp_lt_i32_e32 vcc, -1, v63
	v_and_b32_e32 v62, 0xffffff00, v62
	v_add_u32_e32 v78, 0xfd, v59
	v_cndmask_b32_e64 v59, v101, -1, vcc
	v_sub_u32_e32 v62, v62, v3
	v_bitop3_b32 v69, v59, v63, s43 bitop3:0x78
	v_add_u32_e32 v80, 0xfc, v62
	v_pk_add_f32 v[62:63], v[64:65], v[68:69] op_sel_hi:[0,1]
	v_not_b32_e32 v59, v63
	v_or_b32_e32 v64, 0x80000000, v63
	v_cmp_gt_i32_e32 vcc, 0, v63
	v_and_b32_e32 v67, 0xffffff00, v67
	v_and_b32_e32 v66, 0xffffff00, v66
	v_cndmask_b32_e32 v59, v64, v59, vcc
	v_and_b32_e32 v59, 0xffffff00, v59
	v_bitop3_b32 v63, v0, s44, v59 bitop3:0x36
	v_not_b32_e32 v59, v62
	v_or_b32_e32 v64, 0x80000000, v62
	v_cmp_gt_i32_e32 vcc, 0, v62
	v_and_b32_e32 v61, 0xffffff00, v61
	v_sub_u32_e32 v66, v66, v1
	v_sub_u32_e32 v67, v67, v0
	v_cndmask_b32_e32 v59, v64, v59, vcc
	v_sub_u32_e32 v61, v61, v56
	v_add_u32_e32 v67, 0xff, v67
	v_add_u32_e32 v66, 0xfe, v66
	v_and_b32_e32 v59, 0xffffff00, v59
	v_add_u32_e32 v61, 0xbf, v61
	v_bitop3_b32 v62, v0, 63, v59 bitop3:0x36
	v_max_u32_e32 v59, v66, v80
	v_max_u32_e32 v64, v67, v78
	v_max_u32_e32 v65, v104, v105
	v_max_u32_e32 v107, v73, v74
	v_max3_u32 v59, v64, v59, v63
	v_max_u32_e32 v64, v62, v61
	v_max_u32_e32 v68, v102, v103
	v_max_u32_e32 v69, v79, v81
	v_max3_u32 v65, v77, v106, v65
	v_max3_u32 v107, v75, v76, v107
	v_max_u32_e32 v108, v70, v72
	v_max3_u32 v59, v59, v64, v65
	v_max3_u32 v64, v68, v69, v107
	v_max3_u32 v59, v59, v64, v108
	s_nop 1
	v_mov_b32_dpp v64, v59 quad_perm:[1,0,3,2] row_mask:0xf bank_mask:0xf
	s_and_b32 s24, s40, 0x70
	s_lshl_b32 s24, s24, 2
	s_waitcnt lgkmcnt(0)
	v_max_u32_e32 v59, v59, v64
	s_nop 1
	v_mov_b32_dpp v64, v59 quad_perm:[2,3,0,1] row_mask:0xf bank_mask:0xf
	s_waitcnt lgkmcnt(0)
	v_max_u32_e32 v59, v59, v64
	v_cmp_ne_u32_e32 vcc, v67, v59
	s_nop 1
	v_cndmask_b32_e32 v64, 0, v67, vcc
	v_cmp_ne_u32_e32 vcc, v66, v59
	s_nop 1
	v_cndmask_b32_e32 v65, 0, v66, vcc
	v_cmp_ne_u32_e32 vcc, v78, v59
	s_nop 1
	v_cndmask_b32_e32 v66, 0, v78, vcc
	v_cmp_ne_u32_e32 vcc, v80, v59
	s_nop 1
	v_cndmask_b32_e32 v67, 0, v80, vcc
	v_cmp_ne_u32_e32 vcc, v72, v59
	s_nop 1
	v_cndmask_b32_e32 v68, 0, v72, vcc
	v_cmp_ne_u32_e32 vcc, v70, v59
	s_nop 1
	v_cndmask_b32_e32 v69, 0, v70, vcc
	v_cmp_ne_u32_e32 vcc, v74, v59
	s_nop 1
	v_cndmask_b32_e32 v70, 0, v74, vcc
	v_cmp_ne_u32_e32 vcc, v73, v59
	s_nop 1
	v_cndmask_b32_e32 v72, 0, v73, vcc
	v_cmp_ne_u32_e32 vcc, v76, v59
	s_nop 1
	v_cndmask_b32_e32 v73, 0, v76, vcc
	v_cmp_ne_u32_e32 vcc, v75, v59
	s_nop 1
	v_cndmask_b32_e32 v74, 0, v75, vcc
	v_cmp_ne_u32_e32 vcc, v81, v59
	s_nop 1
	v_cndmask_b32_e32 v75, 0, v81, vcc
	v_cmp_ne_u32_e32 vcc, v79, v59
	s_nop 1
	v_cndmask_b32_e32 v76, 0, v79, vcc
	v_cmp_ne_u32_e32 vcc, v103, v59
	s_nop 1
	v_cndmask_b32_e32 v78, 0, v103, vcc
	v_cmp_ne_u32_e32 vcc, v102, v59
	s_nop 1
	v_cndmask_b32_e32 v79, 0, v102, vcc
	v_cmp_ne_u32_e32 vcc, v105, v59
	s_nop 1
	v_cndmask_b32_e32 v80, 0, v105, vcc
	v_cmp_ne_u32_e32 vcc, v104, v59
	s_nop 1
	v_cndmask_b32_e32 v81, 0, v104, vcc
	v_cmp_ne_u32_e32 vcc, v61, v59
	s_nop 1
	v_cndmask_b32_e32 v102, 0, v61, vcc
	v_max3_u32 v61, v64, v65, v66
	v_max3_u32 v61, v61, v67, v68
	v_max3_u32 v61, v61, v69, v70
	v_max3_u32 v61, v61, v72, v73
	v_cmp_ne_u32_e32 vcc, v77, v59
	v_max3_u32 v61, v61, v74, v75
	v_max3_u32 v61, v61, v76, v78
	v_cndmask_b32_e32 v77, 0, v77, vcc
	v_cmp_ne_u32_e32 vcc, v106, v59
	v_max3_u32 v61, v61, v79, v80
	v_max3_u32 v61, v61, v81, v102
	v_cndmask_b32_e32 v103, 0, v106, vcc
	v_cmp_ne_u32_e32 vcc, v63, v59
	v_max3_u32 v61, v61, v77, v103
	s_nop 0
	v_cndmask_b32_e32 v63, 0, v63, vcc
	v_cmp_ne_u32_e32 vcc, v62, v59
	s_nop 1
	v_cndmask_b32_e32 v62, 0, v62, vcc
	v_max3_u32 v61, v61, v63, v62
	s_nop 1
	v_mov_b32_dpp v104, v61 quad_perm:[1,0,3,2] row_mask:0xf bank_mask:0xf
	s_waitcnt lgkmcnt(0)
	v_max_u32_e32 v61, v61, v104
	s_nop 1
	v_mov_b32_dpp v104, v61 quad_perm:[2,3,0,1] row_mask:0xf bank_mask:0xf
	s_waitcnt lgkmcnt(0)
	v_max_u32_e32 v61, v61, v104
	v_cmp_ne_u32_e32 vcc, v64, v61
	s_nop 1
	v_cndmask_b32_e32 v64, 0, v64, vcc
	v_cmp_ne_u32_e32 vcc, v65, v61
	s_nop 1
	v_cndmask_b32_e32 v65, 0, v65, vcc
	v_cmp_ne_u32_e32 vcc, v66, v61
	s_nop 1
	v_cndmask_b32_e32 v66, 0, v66, vcc
	v_cmp_ne_u32_e32 vcc, v67, v61
	s_nop 1
	v_cndmask_b32_e32 v67, 0, v67, vcc
	v_cmp_ne_u32_e32 vcc, v68, v61
	s_nop 1
	v_cndmask_b32_e32 v68, 0, v68, vcc
	v_cmp_ne_u32_e32 vcc, v69, v61
	s_nop 1
	v_cndmask_b32_e32 v69, 0, v69, vcc
	v_cmp_ne_u32_e32 vcc, v70, v61
	s_nop 1
	v_cndmask_b32_e32 v70, 0, v70, vcc
	v_cmp_ne_u32_e32 vcc, v72, v61
	s_nop 1
	v_cndmask_b32_e32 v72, 0, v72, vcc
	v_cmp_ne_u32_e32 vcc, v73, v61
	s_nop 1
	v_cndmask_b32_e32 v73, 0, v73, vcc
	v_cmp_ne_u32_e32 vcc, v74, v61
	s_nop 1
	v_cndmask_b32_e32 v74, 0, v74, vcc
	v_cmp_ne_u32_e32 vcc, v75, v61
	s_nop 1
	v_cndmask_b32_e32 v75, 0, v75, vcc
	v_cmp_ne_u32_e32 vcc, v76, v61
	s_nop 1
	v_cndmask_b32_e32 v76, 0, v76, vcc
	v_cmp_ne_u32_e32 vcc, v78, v61
	s_nop 1
	v_cndmask_b32_e32 v78, 0, v78, vcc
	v_cmp_ne_u32_e32 vcc, v79, v61
	s_nop 1
	v_cndmask_b32_e32 v79, 0, v79, vcc
	v_cmp_ne_u32_e32 vcc, v80, v61
	s_nop 1
	v_cndmask_b32_e32 v80, 0, v80, vcc
	v_cmp_ne_u32_e32 vcc, v81, v61
	s_nop 1
	v_cndmask_b32_e32 v81, 0, v81, vcc
	v_cmp_ne_u32_e32 vcc, v102, v61
	s_nop 1
	v_cndmask_b32_e32 v104, 0, v102, vcc
	v_max3_u32 v102, v64, v65, v66
	v_max3_u32 v102, v102, v67, v68
	v_max3_u32 v102, v102, v69, v70
	v_max3_u32 v102, v102, v72, v73
	v_cmp_ne_u32_e32 vcc, v77, v61
	v_max3_u32 v102, v102, v74, v75
	v_max3_u32 v102, v102, v76, v78
	v_cndmask_b32_e32 v77, 0, v77, vcc
	v_cmp_ne_u32_e32 vcc, v103, v61
	v_max3_u32 v102, v102, v79, v80
	v_max3_u32 v102, v102, v81, v104
	v_cndmask_b32_e32 v103, 0, v103, vcc
	v_cmp_ne_u32_e32 vcc, v63, v61
	v_max3_u32 v102, v102, v77, v103
	s_nop 0
	v_cndmask_b32_e32 v63, 0, v63, vcc
	v_cmp_ne_u32_e32 vcc, v62, v61
	s_nop 1
	v_cndmask_b32_e32 v62, 0, v62, vcc
	v_max3_u32 v102, v102, v63, v62
	s_nop 1
	v_mov_b32_dpp v105, v102 quad_perm:[1,0,3,2] row_mask:0xf bank_mask:0xf
	s_waitcnt lgkmcnt(0)
	v_max_u32_e32 v102, v102, v105
	s_nop 1
	v_mov_b32_dpp v105, v102 quad_perm:[2,3,0,1] row_mask:0xf bank_mask:0xf
	s_waitcnt lgkmcnt(0)
	v_max_u32_e32 v102, v102, v105
	v_cmp_ne_u32_e32 vcc, v64, v102
	s_nop 1
	v_cndmask_b32_e32 v64, 0, v64, vcc
	v_cmp_ne_u32_e32 vcc, v65, v102
	s_nop 1
	v_cndmask_b32_e32 v65, 0, v65, vcc
	v_cmp_ne_u32_e32 vcc, v66, v102
	s_nop 1
	v_cndmask_b32_e32 v66, 0, v66, vcc
	v_cmp_ne_u32_e32 vcc, v67, v102
	s_nop 1
	v_cndmask_b32_e32 v67, 0, v67, vcc
	v_cmp_ne_u32_e32 vcc, v68, v102
	s_nop 1
	v_cndmask_b32_e32 v68, 0, v68, vcc
	v_cmp_ne_u32_e32 vcc, v69, v102
	s_nop 1
	v_cndmask_b32_e32 v69, 0, v69, vcc
	v_cmp_ne_u32_e32 vcc, v70, v102
	s_nop 1
	v_cndmask_b32_e32 v70, 0, v70, vcc
	v_cmp_ne_u32_e32 vcc, v72, v102
	s_nop 1
	v_cndmask_b32_e32 v72, 0, v72, vcc
	v_cmp_ne_u32_e32 vcc, v73, v102
	s_nop 1
	v_cndmask_b32_e32 v73, 0, v73, vcc
	v_cmp_ne_u32_e32 vcc, v74, v102
	s_nop 1
	v_cndmask_b32_e32 v74, 0, v74, vcc
	v_cmp_ne_u32_e32 vcc, v75, v102
	s_nop 1
	v_cndmask_b32_e32 v75, 0, v75, vcc
	v_cmp_ne_u32_e32 vcc, v76, v102
	s_nop 1
	v_cndmask_b32_e32 v76, 0, v76, vcc
	v_cmp_ne_u32_e32 vcc, v78, v102
	s_nop 1
	v_cndmask_b32_e32 v78, 0, v78, vcc
	v_cmp_ne_u32_e32 vcc, v79, v102
	s_nop 1
	v_cndmask_b32_e32 v79, 0, v79, vcc
	v_cmp_ne_u32_e32 vcc, v80, v102
	s_nop 1
	v_cndmask_b32_e32 v80, 0, v80, vcc
	v_cmp_ne_u32_e32 vcc, v81, v102
	s_nop 1
	v_cndmask_b32_e32 v81, 0, v81, vcc
	v_cmp_ne_u32_e32 vcc, v104, v102
	s_nop 1
	v_cndmask_b32_e32 v104, 0, v104, vcc
	v_cmp_ne_u32_e32 vcc, v77, v102
	s_nop 1
	v_cndmask_b32_e32 v77, 0, v77, vcc
	v_cmp_ne_u32_e32 vcc, v103, v102
	s_nop 1
	v_cndmask_b32_e32 v105, 0, v103, vcc
	v_max3_u32 v103, v64, v65, v66
	v_max3_u32 v103, v103, v67, v68
	v_max3_u32 v103, v103, v69, v70
	v_max3_u32 v103, v103, v72, v73
	v_max3_u32 v103, v103, v74, v75
	v_max3_u32 v103, v103, v76, v78
	v_cmp_ne_u32_e32 vcc, v63, v102
	v_max3_u32 v103, v103, v79, v80
	v_max3_u32 v103, v103, v81, v104
	v_cndmask_b32_e32 v63, 0, v63, vcc
	v_cmp_ne_u32_e32 vcc, v62, v102
	v_max3_u32 v103, v103, v77, v105
	s_nop 0
	v_cndmask_b32_e32 v62, 0, v62, vcc
	v_max3_u32 v103, v103, v63, v62
	s_nop 1
	v_mov_b32_dpp v106, v103 quad_perm:[1,0,3,2] row_mask:0xf bank_mask:0xf
	s_waitcnt lgkmcnt(0)
	v_max_u32_e32 v103, v103, v106
	s_nop 1
	v_mov_b32_dpp v106, v103 quad_perm:[2,3,0,1] row_mask:0xf bank_mask:0xf
	s_waitcnt lgkmcnt(0)
	v_max_u32_e32 v103, v103, v106
	v_cmp_ne_u32_e32 vcc, v64, v103
	s_nop 1
	v_cndmask_b32_e32 v64, 0, v64, vcc
	v_cmp_ne_u32_e32 vcc, v65, v103
	s_nop 1
	v_cndmask_b32_e32 v65, 0, v65, vcc
	v_cmp_ne_u32_e32 vcc, v66, v103
	s_nop 1
	v_cndmask_b32_e32 v66, 0, v66, vcc
	v_cmp_ne_u32_e32 vcc, v67, v103
	s_nop 1
	v_cndmask_b32_e32 v67, 0, v67, vcc
	v_cmp_ne_u32_e32 vcc, v68, v103
	s_nop 1
	v_cndmask_b32_e32 v68, 0, v68, vcc
	v_cmp_ne_u32_e32 vcc, v69, v103
	s_nop 1
	v_cndmask_b32_e32 v69, 0, v69, vcc
	v_cmp_ne_u32_e32 vcc, v70, v103
	s_nop 1
	v_cndmask_b32_e32 v70, 0, v70, vcc
	v_cmp_ne_u32_e32 vcc, v72, v103
	s_nop 1
	v_cndmask_b32_e32 v72, 0, v72, vcc
	v_cmp_ne_u32_e32 vcc, v73, v103
	s_nop 1
	v_cndmask_b32_e32 v73, 0, v73, vcc
	v_cmp_ne_u32_e32 vcc, v74, v103
	s_nop 1
	v_cndmask_b32_e32 v74, 0, v74, vcc
	v_cmp_ne_u32_e32 vcc, v75, v103
	s_nop 1
	v_cndmask_b32_e32 v75, 0, v75, vcc
	v_cmp_ne_u32_e32 vcc, v76, v103
	s_nop 1
	v_cndmask_b32_e32 v106, 0, v76, vcc
	v_cmp_ne_u32_e32 vcc, v78, v103
	v_max3_u32 v76, v64, v65, v66
	v_max3_u32 v76, v76, v67, v68
	v_cndmask_b32_e32 v78, 0, v78, vcc
	v_cmp_ne_u32_e32 vcc, v79, v103
	v_max3_u32 v76, v76, v69, v70
	v_max3_u32 v76, v76, v72, v73
	v_cndmask_b32_e32 v79, 0, v79, vcc
	v_cmp_ne_u32_e32 vcc, v80, v103
	v_max3_u32 v76, v76, v74, v75
	v_max3_u32 v76, v76, v106, v78
	v_cndmask_b32_e32 v80, 0, v80, vcc
	v_cmp_ne_u32_e32 vcc, v81, v103
	v_max3_u32 v76, v76, v79, v80
	s_nop 0
	v_cndmask_b32_e32 v81, 0, v81, vcc
	v_cmp_ne_u32_e32 vcc, v104, v103
	s_nop 1
	v_cndmask_b32_e32 v104, 0, v104, vcc
	v_cmp_ne_u32_e32 vcc, v77, v103
	v_max3_u32 v76, v76, v81, v104
	s_nop 0
	v_cndmask_b32_e32 v77, 0, v77, vcc
	v_cmp_ne_u32_e32 vcc, v105, v103
	s_nop 1
	v_cndmask_b32_e32 v105, 0, v105, vcc
	v_cmp_ne_u32_e32 vcc, v63, v103
	v_max3_u32 v76, v76, v77, v105
	s_nop 0
	v_cndmask_b32_e32 v63, 0, v63, vcc
	v_cmp_ne_u32_e32 vcc, v62, v103
	s_nop 1
	v_cndmask_b32_e32 v62, 0, v62, vcc
	v_max3_u32 v76, v76, v63, v62
	s_nop 1
	v_mov_b32_dpp v107, v76 quad_perm:[1,0,3,2] row_mask:0xf bank_mask:0xf
	s_waitcnt lgkmcnt(0)
	v_max_u32_e32 v76, v76, v107
	s_nop 1
	v_mov_b32_dpp v107, v76 quad_perm:[2,3,0,1] row_mask:0xf bank_mask:0xf
	s_waitcnt lgkmcnt(0)
	v_max_u32_e32 v76, v76, v107
	v_cmp_ne_u32_e32 vcc, v64, v76
	s_nop 1
	v_cndmask_b32_e32 v64, 0, v64, vcc
	v_cmp_ne_u32_e32 vcc, v65, v76
	s_nop 1
	v_cndmask_b32_e32 v65, 0, v65, vcc
	v_cmp_ne_u32_e32 vcc, v66, v76
	s_nop 1
	v_cndmask_b32_e32 v66, 0, v66, vcc
	v_cmp_ne_u32_e32 vcc, v67, v76
	s_nop 1
	v_cndmask_b32_e32 v67, 0, v67, vcc
	v_cmp_ne_u32_e32 vcc, v68, v76
	s_nop 1
	v_cndmask_b32_e32 v68, 0, v68, vcc
	v_cmp_ne_u32_e32 vcc, v69, v76
	s_nop 1
	v_cndmask_b32_e32 v69, 0, v69, vcc
	v_cmp_ne_u32_e32 vcc, v70, v76
	s_nop 1
	v_cndmask_b32_e32 v70, 0, v70, vcc
	v_cmp_ne_u32_e32 vcc, v72, v76
	s_nop 1
	v_cndmask_b32_e32 v72, 0, v72, vcc
	v_cmp_ne_u32_e32 vcc, v73, v76
	s_nop 1
	v_cndmask_b32_e32 v73, 0, v73, vcc
	v_cmp_ne_u32_e32 vcc, v74, v76
	s_nop 1
	v_cndmask_b32_e32 v74, 0, v74, vcc
	v_cmp_ne_u32_e32 vcc, v75, v76
	s_nop 1
	v_cndmask_b32_e32 v75, 0, v75, vcc
	v_cmp_ne_u32_e32 vcc, v106, v76
	s_nop 1
	v_cndmask_b32_e32 v106, 0, v106, vcc
	v_cmp_ne_u32_e32 vcc, v78, v76
	s_nop 1
	v_cndmask_b32_e32 v78, 0, v78, vcc
	v_cmp_ne_u32_e32 vcc, v79, v76
	s_nop 1
	v_cndmask_b32_e32 v79, 0, v79, vcc
	v_cmp_ne_u32_e32 vcc, v80, v76
	s_nop 1
	v_cndmask_b32_e32 v80, 0, v80, vcc
	v_cmp_ne_u32_e32 vcc, v81, v76
	s_nop 1
	v_cndmask_b32_e32 v81, 0, v81, vcc
	v_cmp_ne_u32_e32 vcc, v104, v76
	s_nop 1
	v_cndmask_b32_e32 v104, 0, v104, vcc
	v_cmp_ne_u32_e32 vcc, v77, v76
	s_nop 1
	v_cndmask_b32_e32 v107, 0, v77, vcc
	v_max3_u32 v77, v64, v65, v66
	v_max3_u32 v77, v77, v67, v68
	v_max3_u32 v77, v77, v69, v70
	v_max3_u32 v77, v77, v72, v73
	v_max3_u32 v77, v77, v74, v75
	v_cmp_ne_u32_e32 vcc, v105, v76
	v_max3_u32 v77, v77, v106, v78
	v_max3_u32 v77, v77, v79, v80
	v_cndmask_b32_e32 v105, 0, v105, vcc
	v_cmp_ne_u32_e32 vcc, v63, v76
	v_max3_u32 v77, v77, v81, v104
	v_max3_u32 v77, v77, v107, v105
	v_cndmask_b32_e32 v63, 0, v63, vcc
	v_cmp_ne_u32_e32 vcc, v62, v76
	s_nop 1
	v_cndmask_b32_e32 v62, 0, v62, vcc
	v_max3_u32 v77, v77, v63, v62
	s_nop 1
	v_mov_b32_dpp v108, v77 quad_perm:[1,0,3,2] row_mask:0xf bank_mask:0xf
	s_waitcnt lgkmcnt(0)
	v_max_u32_e32 v77, v77, v108
	s_nop 1
	v_mov_b32_dpp v108, v77 quad_perm:[2,3,0,1] row_mask:0xf bank_mask:0xf
	s_waitcnt lgkmcnt(0)
	v_max_u32_e32 v77, v77, v108
	v_cmp_ne_u32_e32 vcc, v64, v77
	s_nop 1
	v_cndmask_b32_e32 v64, 0, v64, vcc
	v_cmp_ne_u32_e32 vcc, v65, v77
	s_nop 1
	v_cndmask_b32_e32 v65, 0, v65, vcc
	v_cmp_ne_u32_e32 vcc, v66, v77
	s_nop 1
	v_cndmask_b32_e32 v66, 0, v66, vcc
	v_cmp_ne_u32_e32 vcc, v67, v77
	s_nop 1
	v_cndmask_b32_e32 v67, 0, v67, vcc
	v_cmp_ne_u32_e32 vcc, v68, v77
	s_nop 1
	v_cndmask_b32_e32 v68, 0, v68, vcc
	v_cmp_ne_u32_e32 vcc, v69, v77
	s_nop 1
	v_cndmask_b32_e32 v69, 0, v69, vcc
	v_cmp_ne_u32_e32 vcc, v70, v77
	s_nop 1
	v_cndmask_b32_e32 v70, 0, v70, vcc
	v_cmp_ne_u32_e32 vcc, v72, v77
	s_nop 1
	v_cndmask_b32_e32 v72, 0, v72, vcc
	v_cmp_ne_u32_e32 vcc, v73, v77
	s_nop 1
	v_cndmask_b32_e32 v73, 0, v73, vcc
	v_cmp_ne_u32_e32 vcc, v74, v77
	s_nop 1
	v_cndmask_b32_e32 v74, 0, v74, vcc
	v_cmp_ne_u32_e32 vcc, v75, v77
	s_nop 1
	v_cndmask_b32_e32 v75, 0, v75, vcc
	v_cmp_ne_u32_e32 vcc, v106, v77
	s_nop 1
	v_cndmask_b32_e32 v106, 0, v106, vcc
	v_cmp_ne_u32_e32 vcc, v78, v77
	s_nop 1
	v_cndmask_b32_e32 v108, 0, v78, vcc
	v_cmp_ne_u32_e32 vcc, v79, v77
	v_max3_u32 v78, v64, v65, v66
	v_max3_u32 v78, v78, v67, v68
	v_cndmask_b32_e32 v79, 0, v79, vcc
	v_cmp_ne_u32_e32 vcc, v80, v77
	v_max3_u32 v78, v78, v69, v70
	v_max3_u32 v78, v78, v72, v73
	v_cndmask_b32_e32 v80, 0, v80, vcc
	v_cmp_ne_u32_e32 vcc, v81, v77
	v_max3_u32 v78, v78, v74, v75
	v_max3_u32 v78, v78, v106, v108
	v_cndmask_b32_e32 v81, 0, v81, vcc
	v_cmp_ne_u32_e32 vcc, v104, v77
	v_max3_u32 v78, v78, v79, v80
	s_nop 0
	v_cndmask_b32_e32 v104, 0, v104, vcc
	v_cmp_ne_u32_e32 vcc, v107, v77
	v_max3_u32 v78, v78, v81, v104
	s_nop 0
	v_cndmask_b32_e32 v107, 0, v107, vcc
	v_cmp_ne_u32_e32 vcc, v105, v77
	s_nop 1
	v_cndmask_b32_e32 v105, 0, v105, vcc
	v_cmp_ne_u32_e32 vcc, v63, v77
	v_max3_u32 v78, v78, v107, v105
	s_nop 0
	v_cndmask_b32_e32 v63, 0, v63, vcc
	v_cmp_ne_u32_e32 vcc, v62, v77
	s_nop 1
	v_cndmask_b32_e32 v62, 0, v62, vcc
	v_max3_u32 v78, v78, v63, v62
	s_nop 1
	v_mov_b32_dpp v109, v78 quad_perm:[1,0,3,2] row_mask:0xf bank_mask:0xf
	s_waitcnt lgkmcnt(0)
	v_max_u32_e32 v78, v78, v109
	s_nop 1
	v_mov_b32_dpp v109, v78 quad_perm:[2,3,0,1] row_mask:0xf bank_mask:0xf
	s_waitcnt lgkmcnt(0)
	v_max_u32_e32 v78, v78, v109
	v_cmp_ne_u32_e32 vcc, v64, v78
	s_nop 1
	v_cndmask_b32_e32 v64, 0, v64, vcc
	v_cmp_ne_u32_e32 vcc, v65, v78
	s_nop 1
	v_cndmask_b32_e32 v65, 0, v65, vcc
	v_cmp_ne_u32_e32 vcc, v66, v78
	s_nop 1
	v_cndmask_b32_e32 v66, 0, v66, vcc
	v_cmp_ne_u32_e32 vcc, v67, v78
	s_nop 1
	v_cndmask_b32_e32 v67, 0, v67, vcc
	v_cmp_ne_u32_e32 vcc, v68, v78
	s_nop 1
	v_cndmask_b32_e32 v68, 0, v68, vcc
	v_cmp_ne_u32_e32 vcc, v69, v78
	s_nop 1
	v_cndmask_b32_e32 v69, 0, v69, vcc
	v_cmp_ne_u32_e32 vcc, v70, v78
	s_nop 1
	v_cndmask_b32_e32 v70, 0, v70, vcc
	v_cmp_ne_u32_e32 vcc, v72, v78
	s_nop 1
	v_cndmask_b32_e32 v72, 0, v72, vcc
	v_cmp_ne_u32_e32 vcc, v73, v78
	s_nop 1
	v_cndmask_b32_e32 v73, 0, v73, vcc
	v_cmp_ne_u32_e32 vcc, v74, v78
	s_nop 1
	v_cndmask_b32_e32 v74, 0, v74, vcc
	v_cmp_ne_u32_e32 vcc, v75, v78
	s_nop 1
	v_cndmask_b32_e32 v75, 0, v75, vcc
	v_cmp_ne_u32_e32 vcc, v106, v78
	s_nop 1
	v_cndmask_b32_e32 v106, 0, v106, vcc
	v_cmp_ne_u32_e32 vcc, v108, v78
	s_nop 1
	v_cndmask_b32_e32 v108, 0, v108, vcc
	v_cmp_ne_u32_e32 vcc, v79, v78
	s_nop 1
	v_cndmask_b32_e32 v109, 0, v79, vcc
	v_max3_u32 v79, v64, v65, v66
	v_cmp_ne_u32_e32 vcc, v80, v78
	v_max3_u32 v79, v79, v67, v68
	v_max3_u32 v79, v79, v69, v70
	v_cndmask_b32_e32 v80, 0, v80, vcc
	v_cmp_ne_u32_e32 vcc, v81, v78
	v_max3_u32 v79, v79, v72, v73
	v_max3_u32 v79, v79, v74, v75
	v_cndmask_b32_e32 v81, 0, v81, vcc
	v_cmp_ne_u32_e32 vcc, v104, v78
	v_max3_u32 v79, v79, v106, v108
	v_max3_u32 v79, v79, v109, v80
	v_cndmask_b32_e32 v104, 0, v104, vcc
	v_cmp_ne_u32_e32 vcc, v107, v78
	v_max3_u32 v79, v79, v81, v104
	s_nop 0
	v_cndmask_b32_e32 v107, 0, v107, vcc
	v_cmp_ne_u32_e32 vcc, v105, v78
	s_nop 1
	v_cndmask_b32_e32 v105, 0, v105, vcc
	v_cmp_ne_u32_e32 vcc, v63, v78
	v_max3_u32 v79, v79, v107, v105
	s_nop 0
	v_cndmask_b32_e32 v63, 0, v63, vcc
	v_cmp_ne_u32_e32 vcc, v62, v78
	s_nop 1
	v_cndmask_b32_e32 v62, 0, v62, vcc
	v_max3_u32 v79, v79, v63, v62
	s_nop 1
	v_mov_b32_dpp v110, v79 quad_perm:[1,0,3,2] row_mask:0xf bank_mask:0xf
	s_waitcnt lgkmcnt(0)
	v_max_u32_e32 v79, v79, v110
	s_nop 1
	v_mov_b32_dpp v110, v79 quad_perm:[2,3,0,1] row_mask:0xf bank_mask:0xf
	s_waitcnt lgkmcnt(0)
	v_max_u32_e32 v79, v79, v110
	v_cmp_ne_u32_e32 vcc, v64, v79
	s_nop 1
	v_cndmask_b32_e32 v64, 0, v64, vcc
	v_cmp_ne_u32_e32 vcc, v65, v79
	s_nop 1
	v_cndmask_b32_e32 v65, 0, v65, vcc
	v_cmp_ne_u32_e32 vcc, v66, v79
	s_nop 1
	v_cndmask_b32_e32 v66, 0, v66, vcc
	v_cmp_ne_u32_e32 vcc, v67, v79
	s_nop 1
	v_cndmask_b32_e32 v67, 0, v67, vcc
	v_cmp_ne_u32_e32 vcc, v68, v79
	s_nop 1
	v_cndmask_b32_e32 v68, 0, v68, vcc
	v_cmp_ne_u32_e32 vcc, v69, v79
	s_nop 1
	v_cndmask_b32_e32 v69, 0, v69, vcc
	v_cmp_ne_u32_e32 vcc, v70, v79
	s_nop 1
	v_cndmask_b32_e32 v70, 0, v70, vcc
	v_cmp_ne_u32_e32 vcc, v72, v79
	s_nop 1
	v_cndmask_b32_e32 v72, 0, v72, vcc
	v_cmp_ne_u32_e32 vcc, v73, v79
	s_nop 1
	v_cndmask_b32_e32 v73, 0, v73, vcc
	v_cmp_ne_u32_e32 vcc, v74, v79
	s_nop 1
	v_cndmask_b32_e32 v74, 0, v74, vcc
	v_cmp_ne_u32_e32 vcc, v75, v79
	s_nop 1
	v_cndmask_b32_e32 v75, 0, v75, vcc
	v_cmp_ne_u32_e32 vcc, v106, v79
	s_nop 1
	v_cndmask_b32_e32 v106, 0, v106, vcc
	v_cmp_ne_u32_e32 vcc, v108, v79
	s_nop 1
	v_cndmask_b32_e32 v108, 0, v108, vcc
	v_cmp_ne_u32_e32 vcc, v109, v79
	s_nop 1
	v_cndmask_b32_e32 v109, 0, v109, vcc
	v_cmp_ne_u32_e32 vcc, v80, v79
	s_nop 1
	v_cndmask_b32_e32 v80, 0, v80, vcc
	v_cmp_ne_u32_e32 vcc, v81, v79
	s_nop 1
	v_cndmask_b32_e32 v81, 0, v81, vcc
	v_cmp_ne_u32_e32 vcc, v104, v79
	s_nop 1
	v_cndmask_b32_e32 v104, 0, v104, vcc
	v_cmp_ne_u32_e32 vcc, v107, v79
	s_nop 1
	v_cndmask_b32_e32 v107, 0, v107, vcc
	v_cmp_ne_u32_e32 vcc, v105, v79
	s_nop 1
	v_cndmask_b32_e32 v105, 0, v105, vcc
	v_cmp_ne_u32_e32 vcc, v63, v79
	s_nop 1
	v_cndmask_b32_e32 v63, 0, v63, vcc
	v_cmp_ne_u32_e32 vcc, v62, v79
	s_nop 1
	v_cndmask_b32_e32 v110, 0, v62, vcc
	v_max3_u32 v62, v64, v65, v66
	v_max3_u32 v62, v62, v67, v68
	v_max3_u32 v62, v62, v69, v70
	v_max3_u32 v62, v62, v72, v73
	v_max3_u32 v62, v62, v74, v75
	v_max3_u32 v62, v62, v106, v108
	v_max3_u32 v62, v62, v109, v80
	v_max3_u32 v62, v62, v81, v104
	v_max3_u32 v62, v62, v107, v105
	v_max3_u32 v62, v62, v63, v110
	s_nop 1
	v_mov_b32_dpp v111, v62 quad_perm:[1,0,3,2] row_mask:0xf bank_mask:0xf
	s_waitcnt lgkmcnt(0)
	v_max_u32_e32 v62, v62, v111
	s_nop 1
	v_mov_b32_dpp v111, v62 quad_perm:[2,3,0,1] row_mask:0xf bank_mask:0xf
	s_waitcnt lgkmcnt(0)
	v_max_u32_e32 v62, v62, v111
	v_cmp_ne_u32_e32 vcc, v64, v62
	s_nop 1
	v_cndmask_b32_e32 v64, 0, v64, vcc
	v_cmp_ne_u32_e32 vcc, v65, v62
	s_nop 1
	v_cndmask_b32_e32 v65, 0, v65, vcc
	v_cmp_ne_u32_e32 vcc, v66, v62
	s_nop 1
	v_cndmask_b32_e32 v66, 0, v66, vcc
	v_cmp_ne_u32_e32 vcc, v67, v62
	s_nop 1
	v_cndmask_b32_e32 v67, 0, v67, vcc
	v_cmp_ne_u32_e32 vcc, v68, v62
	s_nop 1
	v_cndmask_b32_e32 v68, 0, v68, vcc
	v_cmp_ne_u32_e32 vcc, v69, v62
	s_nop 1
	v_cndmask_b32_e32 v69, 0, v69, vcc
	v_cmp_ne_u32_e32 vcc, v70, v62
	s_nop 1
	v_cndmask_b32_e32 v70, 0, v70, vcc
	v_cmp_ne_u32_e32 vcc, v72, v62
	s_nop 1
	v_cndmask_b32_e32 v72, 0, v72, vcc
	v_cmp_ne_u32_e32 vcc, v73, v62
	s_nop 1
	v_cndmask_b32_e32 v73, 0, v73, vcc
	v_cmp_ne_u32_e32 vcc, v74, v62
	s_nop 1
	v_cndmask_b32_e32 v74, 0, v74, vcc
	v_cmp_ne_u32_e32 vcc, v75, v62
	s_nop 1
	v_cndmask_b32_e32 v75, 0, v75, vcc
	v_cmp_ne_u32_e32 vcc, v106, v62
	s_nop 1
	v_cndmask_b32_e32 v106, 0, v106, vcc
	v_cmp_ne_u32_e32 vcc, v108, v62
	s_nop 1
	v_cndmask_b32_e32 v108, 0, v108, vcc
	v_cmp_ne_u32_e32 vcc, v109, v62
	s_nop 1
	v_cndmask_b32_e32 v109, 0, v109, vcc
	v_cmp_ne_u32_e32 vcc, v80, v62
	s_nop 1
	v_cndmask_b32_e32 v80, 0, v80, vcc
	v_cmp_ne_u32_e32 vcc, v81, v62
	s_nop 1
	v_cndmask_b32_e32 v81, 0, v81, vcc
	v_cmp_ne_u32_e32 vcc, v104, v62
	s_nop 1
	v_cndmask_b32_e32 v104, 0, v104, vcc
	v_cmp_ne_u32_e32 vcc, v107, v62
	s_nop 1
	v_cndmask_b32_e32 v107, 0, v107, vcc
	v_cmp_ne_u32_e32 vcc, v105, v62
	s_nop 1
	v_cndmask_b32_e32 v105, 0, v105, vcc
	v_cmp_ne_u32_e32 vcc, v63, v62
	s_nop 1
	v_cndmask_b32_e32 v111, 0, v63, vcc
	v_max3_u32 v63, v64, v65, v66
	v_max3_u32 v63, v63, v67, v68
	v_max3_u32 v63, v63, v69, v70
	v_max3_u32 v63, v63, v72, v73
	v_max3_u32 v63, v63, v74, v75
	v_max3_u32 v63, v63, v106, v108
	v_max3_u32 v63, v63, v109, v80
	v_cmp_ne_u32_e32 vcc, v110, v62
	v_max3_u32 v63, v63, v81, v104
	v_max3_u32 v63, v63, v107, v105
	v_cndmask_b32_e32 v110, 0, v110, vcc
	v_max3_u32 v63, v63, v111, v110
	s_nop 1
	v_mov_b32_dpp v112, v63 quad_perm:[1,0,3,2] row_mask:0xf bank_mask:0xf
	s_waitcnt lgkmcnt(0)
	v_max_u32_e32 v63, v63, v112
	s_nop 1
	v_mov_b32_dpp v112, v63 quad_perm:[2,3,0,1] row_mask:0xf bank_mask:0xf
	s_waitcnt lgkmcnt(0)
	v_max_u32_e32 v63, v63, v112
	v_cmp_ne_u32_e32 vcc, v64, v63
	s_nop 1
	v_cndmask_b32_e32 v112, 0, v64, vcc
	v_cmp_ne_u32_e32 vcc, v65, v63
	s_nop 1
	v_cndmask_b32_e32 v65, 0, v65, vcc
	v_cmp_ne_u32_e32 vcc, v66, v63
	s_nop 1
	v_cndmask_b32_e32 v66, 0, v66, vcc
	v_cmp_ne_u32_e32 vcc, v67, v63
	v_max3_u32 v64, v112, v65, v66
	s_nop 0
	v_cndmask_b32_e32 v67, 0, v67, vcc
	v_cmp_ne_u32_e32 vcc, v68, v63
	s_nop 1
	v_cndmask_b32_e32 v68, 0, v68, vcc
	v_cmp_ne_u32_e32 vcc, v69, v63
	v_max3_u32 v64, v64, v67, v68
	s_nop 0
	v_cndmask_b32_e32 v69, 0, v69, vcc
	v_cmp_ne_u32_e32 vcc, v70, v63
	s_nop 1
	v_cndmask_b32_e32 v70, 0, v70, vcc
	v_cmp_ne_u32_e32 vcc, v72, v63
	v_max3_u32 v64, v64, v69, v70
	s_nop 0
	v_cndmask_b32_e32 v72, 0, v72, vcc
	v_cmp_ne_u32_e32 vcc, v73, v63
	s_nop 1
	v_cndmask_b32_e32 v73, 0, v73, vcc
	v_cmp_ne_u32_e32 vcc, v74, v63
	v_max3_u32 v64, v64, v72, v73
	s_nop 0
	v_cndmask_b32_e32 v74, 0, v74, vcc
	v_cmp_ne_u32_e32 vcc, v75, v63
	s_nop 1
	v_cndmask_b32_e32 v75, 0, v75, vcc
	v_cmp_ne_u32_e32 vcc, v106, v63
	v_max3_u32 v64, v64, v74, v75
	s_nop 0
	v_cndmask_b32_e32 v106, 0, v106, vcc
	v_cmp_ne_u32_e32 vcc, v108, v63
	s_nop 1
	v_cndmask_b32_e32 v108, 0, v108, vcc
	v_cmp_ne_u32_e32 vcc, v109, v63
	v_max3_u32 v64, v64, v106, v108
	s_nop 0
	v_cndmask_b32_e32 v109, 0, v109, vcc
	v_cmp_ne_u32_e32 vcc, v80, v63
	s_nop 1
	v_cndmask_b32_e32 v80, 0, v80, vcc
	v_cmp_ne_u32_e32 vcc, v81, v63
	v_max3_u32 v64, v64, v109, v80
	s_nop 0
	v_cndmask_b32_e32 v81, 0, v81, vcc
	v_cmp_ne_u32_e32 vcc, v104, v63
	s_nop 1
	v_cndmask_b32_e32 v104, 0, v104, vcc
	v_cmp_ne_u32_e32 vcc, v107, v63
	v_max3_u32 v64, v64, v81, v104
	s_nop 0
	v_cndmask_b32_e32 v107, 0, v107, vcc
	v_cmp_ne_u32_e32 vcc, v105, v63
	s_nop 1
	v_cndmask_b32_e32 v105, 0, v105, vcc
	v_cmp_ne_u32_e32 vcc, v111, v63
	v_max3_u32 v64, v64, v107, v105
	s_nop 0
	v_cndmask_b32_e32 v111, 0, v111, vcc
	v_cmp_ne_u32_e32 vcc, v110, v63
	s_nop 1
	v_cndmask_b32_e32 v110, 0, v110, vcc
	v_max3_u32 v64, v64, v111, v110
	s_nop 1
	v_mov_b32_dpp v113, v64 quad_perm:[1,0,3,2] row_mask:0xf bank_mask:0xf
	s_waitcnt lgkmcnt(0)
	v_max_u32_e32 v64, v64, v113
	s_nop 1
	v_mov_b32_dpp v113, v64 quad_perm:[2,3,0,1] row_mask:0xf bank_mask:0xf
	s_waitcnt lgkmcnt(0)
	v_max_u32_e32 v64, v64, v113
	v_cmp_ne_u32_e32 vcc, v112, v64
	s_nop 1
	v_cndmask_b32_e32 v112, 0, v112, vcc
	v_cmp_ne_u32_e32 vcc, v65, v64
	s_nop 1
	v_cndmask_b32_e32 v113, 0, v65, vcc
	v_cmp_ne_u32_e32 vcc, v66, v64
	s_nop 1
	v_cndmask_b32_e32 v66, 0, v66, vcc
	v_cmp_ne_u32_e32 vcc, v67, v64
	v_max3_u32 v65, v112, v113, v66
	s_nop 0
	v_cndmask_b32_e32 v67, 0, v67, vcc
	v_cmp_ne_u32_e32 vcc, v68, v64
	s_nop 1
	v_cndmask_b32_e32 v68, 0, v68, vcc
	v_cmp_ne_u32_e32 vcc, v69, v64
	v_max3_u32 v65, v65, v67, v68
	s_nop 0
	v_cndmask_b32_e32 v69, 0, v69, vcc
	v_cmp_ne_u32_e32 vcc, v70, v64
	s_nop 1
	v_cndmask_b32_e32 v70, 0, v70, vcc
	v_cmp_ne_u32_e32 vcc, v72, v64
	v_max3_u32 v65, v65, v69, v70
	s_nop 0
	v_cndmask_b32_e32 v72, 0, v72, vcc
	v_cmp_ne_u32_e32 vcc, v73, v64
	s_nop 1
	v_cndmask_b32_e32 v73, 0, v73, vcc
	v_cmp_ne_u32_e32 vcc, v74, v64
	v_max3_u32 v65, v65, v72, v73
	s_nop 0
	v_cndmask_b32_e32 v74, 0, v74, vcc
	v_cmp_ne_u32_e32 vcc, v75, v64
	s_nop 1
	v_cndmask_b32_e32 v75, 0, v75, vcc
	v_cmp_ne_u32_e32 vcc, v106, v64
	v_max3_u32 v65, v65, v74, v75
	s_nop 0
	v_cndmask_b32_e32 v106, 0, v106, vcc
	v_cmp_ne_u32_e32 vcc, v108, v64
	s_nop 1
	v_cndmask_b32_e32 v108, 0, v108, vcc
	v_cmp_ne_u32_e32 vcc, v109, v64
	v_max3_u32 v65, v65, v106, v108
	s_nop 0
	v_cndmask_b32_e32 v109, 0, v109, vcc
	v_cmp_ne_u32_e32 vcc, v80, v64
	s_nop 1
	v_cndmask_b32_e32 v80, 0, v80, vcc
	v_cmp_ne_u32_e32 vcc, v81, v64
	v_max3_u32 v65, v65, v109, v80
	s_nop 0
	v_cndmask_b32_e32 v81, 0, v81, vcc
	v_cmp_ne_u32_e32 vcc, v104, v64
	s_nop 1
	v_cndmask_b32_e32 v104, 0, v104, vcc
	v_cmp_ne_u32_e32 vcc, v107, v64
	v_max3_u32 v65, v65, v81, v104
	s_nop 0
	v_cndmask_b32_e32 v107, 0, v107, vcc
	v_cmp_ne_u32_e32 vcc, v105, v64
	s_nop 1
	v_cndmask_b32_e32 v105, 0, v105, vcc
	v_cmp_ne_u32_e32 vcc, v111, v64
	v_max3_u32 v65, v65, v107, v105
	s_nop 0
	v_cndmask_b32_e32 v111, 0, v111, vcc
	v_cmp_ne_u32_e32 vcc, v110, v64
	s_nop 1
	v_cndmask_b32_e32 v110, 0, v110, vcc
	v_max3_u32 v65, v65, v111, v110
	s_nop 1
	v_mov_b32_dpp v114, v65 quad_perm:[1,0,3,2] row_mask:0xf bank_mask:0xf
	s_waitcnt lgkmcnt(0)
	v_max_u32_e32 v65, v65, v114
	s_nop 1
	v_mov_b32_dpp v114, v65 quad_perm:[2,3,0,1] row_mask:0xf bank_mask:0xf
	s_waitcnt lgkmcnt(0)
	v_max_u32_e32 v65, v65, v114
	v_cmp_ne_u32_e32 vcc, v112, v65
	s_nop 1
	v_cndmask_b32_e32 v112, 0, v112, vcc
	v_cmp_ne_u32_e32 vcc, v113, v65
	s_nop 1
	v_cndmask_b32_e32 v113, 0, v113, vcc
	v_cmp_ne_u32_e32 vcc, v66, v65
	s_nop 1
	v_cndmask_b32_e32 v114, 0, v66, vcc
	v_cmp_ne_u32_e32 vcc, v67, v65
	v_max3_u32 v66, v112, v113, v114
	s_nop 0
	v_cndmask_b32_e32 v67, 0, v67, vcc
	v_cmp_ne_u32_e32 vcc, v68, v65
	s_nop 1
	v_cndmask_b32_e32 v68, 0, v68, vcc
	v_cmp_ne_u32_e32 vcc, v69, v65
	v_max3_u32 v66, v66, v67, v68
	s_nop 0
	v_cndmask_b32_e32 v69, 0, v69, vcc
	v_cmp_ne_u32_e32 vcc, v70, v65
	s_nop 1
	v_cndmask_b32_e32 v70, 0, v70, vcc
	v_cmp_ne_u32_e32 vcc, v72, v65
	v_max3_u32 v66, v66, v69, v70
	s_nop 0
	v_cndmask_b32_e32 v72, 0, v72, vcc
	v_cmp_ne_u32_e32 vcc, v73, v65
	s_nop 1
	v_cndmask_b32_e32 v73, 0, v73, vcc
	v_cmp_ne_u32_e32 vcc, v74, v65
	v_max3_u32 v66, v66, v72, v73
	s_nop 0
	v_cndmask_b32_e32 v74, 0, v74, vcc
	v_cmp_ne_u32_e32 vcc, v75, v65
	s_nop 1
	v_cndmask_b32_e32 v75, 0, v75, vcc
	v_cmp_ne_u32_e32 vcc, v106, v65
	v_max3_u32 v66, v66, v74, v75
	s_nop 0
	v_cndmask_b32_e32 v106, 0, v106, vcc
	v_cmp_ne_u32_e32 vcc, v108, v65
	s_nop 1
	v_cndmask_b32_e32 v108, 0, v108, vcc
	v_cmp_ne_u32_e32 vcc, v109, v65
	v_max3_u32 v66, v66, v106, v108
	s_nop 0
	v_cndmask_b32_e32 v109, 0, v109, vcc
	v_cmp_ne_u32_e32 vcc, v80, v65
	s_nop 1
	v_cndmask_b32_e32 v80, 0, v80, vcc
	v_cmp_ne_u32_e32 vcc, v81, v65
	v_max3_u32 v66, v66, v109, v80
	s_nop 0
	v_cndmask_b32_e32 v81, 0, v81, vcc
	v_cmp_ne_u32_e32 vcc, v104, v65
	s_nop 1
	v_cndmask_b32_e32 v104, 0, v104, vcc
	v_cmp_ne_u32_e32 vcc, v107, v65
	v_max3_u32 v66, v66, v81, v104
	s_nop 0
	v_cndmask_b32_e32 v107, 0, v107, vcc
	v_cmp_ne_u32_e32 vcc, v105, v65
	s_nop 1
	v_cndmask_b32_e32 v105, 0, v105, vcc
	v_cmp_ne_u32_e32 vcc, v111, v65
	v_max3_u32 v66, v66, v107, v105
	s_nop 0
	v_cndmask_b32_e32 v111, 0, v111, vcc
	v_cmp_ne_u32_e32 vcc, v110, v65
	s_nop 1
	v_cndmask_b32_e32 v110, 0, v110, vcc
	v_max3_u32 v66, v66, v111, v110
	s_nop 1
	v_mov_b32_dpp v115, v66 quad_perm:[1,0,3,2] row_mask:0xf bank_mask:0xf
	s_waitcnt lgkmcnt(0)
	v_max_u32_e32 v66, v66, v115
	s_nop 1
	v_mov_b32_dpp v115, v66 quad_perm:[2,3,0,1] row_mask:0xf bank_mask:0xf
	s_waitcnt lgkmcnt(0)
	v_max_u32_e32 v66, v66, v115
	v_cmp_ne_u32_e32 vcc, v112, v66
	s_nop 1
	v_cndmask_b32_e32 v112, 0, v112, vcc
	v_cmp_ne_u32_e32 vcc, v113, v66
	s_nop 1
	v_cndmask_b32_e32 v113, 0, v113, vcc
	v_cmp_ne_u32_e32 vcc, v114, v66
	s_nop 1
	v_cndmask_b32_e32 v114, 0, v114, vcc
	v_cmp_ne_u32_e32 vcc, v67, v66
	s_nop 1
	v_cndmask_b32_e32 v115, 0, v67, vcc
	v_cmp_ne_u32_e32 vcc, v68, v66
	v_max3_u32 v67, v112, v113, v114
	s_nop 0
	v_cndmask_b32_e32 v68, 0, v68, vcc
	v_cmp_ne_u32_e32 vcc, v69, v66
	v_max3_u32 v67, v67, v115, v68
	s_nop 0
	v_cndmask_b32_e32 v69, 0, v69, vcc
	v_cmp_ne_u32_e32 vcc, v70, v66
	s_nop 1
	v_cndmask_b32_e32 v70, 0, v70, vcc
	v_cmp_ne_u32_e32 vcc, v72, v66
	v_max3_u32 v67, v67, v69, v70
	s_nop 0
	v_cndmask_b32_e32 v72, 0, v72, vcc
	v_cmp_ne_u32_e32 vcc, v73, v66
	s_nop 1
	v_cndmask_b32_e32 v73, 0, v73, vcc
	v_cmp_ne_u32_e32 vcc, v74, v66
	v_max3_u32 v67, v67, v72, v73
	s_nop 0
	v_cndmask_b32_e32 v74, 0, v74, vcc
	v_cmp_ne_u32_e32 vcc, v75, v66
	s_nop 1
	v_cndmask_b32_e32 v75, 0, v75, vcc
	v_cmp_ne_u32_e32 vcc, v106, v66
	v_max3_u32 v67, v67, v74, v75
	s_nop 0
	v_cndmask_b32_e32 v106, 0, v106, vcc
	v_cmp_ne_u32_e32 vcc, v108, v66
	s_nop 1
	v_cndmask_b32_e32 v108, 0, v108, vcc
	v_cmp_ne_u32_e32 vcc, v109, v66
	v_max3_u32 v67, v67, v106, v108
	s_nop 0
	v_cndmask_b32_e32 v109, 0, v109, vcc
	v_cmp_ne_u32_e32 vcc, v80, v66
	s_nop 1
	v_cndmask_b32_e32 v80, 0, v80, vcc
	v_cmp_ne_u32_e32 vcc, v81, v66
	v_max3_u32 v67, v67, v109, v80
	s_nop 0
	v_cndmask_b32_e32 v81, 0, v81, vcc
	v_cmp_ne_u32_e32 vcc, v104, v66
	s_nop 1
	v_cndmask_b32_e32 v104, 0, v104, vcc
	v_cmp_ne_u32_e32 vcc, v107, v66
	v_max3_u32 v67, v67, v81, v104
	s_nop 0
	v_cndmask_b32_e32 v107, 0, v107, vcc
	v_cmp_ne_u32_e32 vcc, v105, v66
	s_nop 1
	v_cndmask_b32_e32 v105, 0, v105, vcc
	v_cmp_ne_u32_e32 vcc, v111, v66
	v_max3_u32 v67, v67, v107, v105
	s_nop 0
	v_cndmask_b32_e32 v111, 0, v111, vcc
	v_cmp_ne_u32_e32 vcc, v110, v66
	s_nop 1
	v_cndmask_b32_e32 v110, 0, v110, vcc
	v_max3_u32 v67, v67, v111, v110
	s_nop 1
	v_mov_b32_dpp v116, v67 quad_perm:[1,0,3,2] row_mask:0xf bank_mask:0xf
	s_waitcnt lgkmcnt(0)
	v_max_u32_e32 v67, v67, v116
	s_nop 1
	v_mov_b32_dpp v116, v67 quad_perm:[2,3,0,1] row_mask:0xf bank_mask:0xf
	s_waitcnt lgkmcnt(0)
	v_max_u32_e32 v67, v67, v116
	v_cmp_ne_u32_e32 vcc, v112, v67
	s_nop 1
	v_cndmask_b32_e32 v112, 0, v112, vcc
	v_cmp_ne_u32_e32 vcc, v113, v67
	s_nop 1
	v_cndmask_b32_e32 v113, 0, v113, vcc
	v_cmp_ne_u32_e32 vcc, v114, v67
	s_nop 1
	v_cndmask_b32_e32 v114, 0, v114, vcc
	v_cmp_ne_u32_e32 vcc, v115, v67
	s_nop 1
	v_cndmask_b32_e32 v115, 0, v115, vcc
	v_cmp_ne_u32_e32 vcc, v68, v67
	s_nop 1
	v_cndmask_b32_e32 v116, 0, v68, vcc
	v_cmp_ne_u32_e32 vcc, v69, v67
	v_max3_u32 v68, v112, v113, v114
	v_max3_u32 v68, v68, v115, v116
	v_cndmask_b32_e32 v69, 0, v69, vcc
	v_cmp_ne_u32_e32 vcc, v70, v67
	s_nop 1
	v_cndmask_b32_e32 v70, 0, v70, vcc
	v_cmp_ne_u32_e32 vcc, v72, v67
	v_max3_u32 v68, v68, v69, v70
	s_nop 0
	v_cndmask_b32_e32 v72, 0, v72, vcc
	v_cmp_ne_u32_e32 vcc, v73, v67
	s_nop 1
	v_cndmask_b32_e32 v73, 0, v73, vcc
	v_cmp_ne_u32_e32 vcc, v74, v67
	v_max3_u32 v68, v68, v72, v73
	s_nop 0
	v_cndmask_b32_e32 v74, 0, v74, vcc
	v_cmp_ne_u32_e32 vcc, v75, v67
	s_nop 1
	v_cndmask_b32_e32 v75, 0, v75, vcc
	v_cmp_ne_u32_e32 vcc, v106, v67
	v_max3_u32 v68, v68, v74, v75
	s_nop 0
	v_cndmask_b32_e32 v106, 0, v106, vcc
	v_cmp_ne_u32_e32 vcc, v108, v67
	s_nop 1
	v_cndmask_b32_e32 v108, 0, v108, vcc
	v_cmp_ne_u32_e32 vcc, v109, v67
	v_max3_u32 v68, v68, v106, v108
	s_nop 0
	v_cndmask_b32_e32 v109, 0, v109, vcc
	v_cmp_ne_u32_e32 vcc, v80, v67
	s_nop 1
	v_cndmask_b32_e32 v80, 0, v80, vcc
	v_cmp_ne_u32_e32 vcc, v81, v67
	v_max3_u32 v68, v68, v109, v80
	s_nop 0
	v_cndmask_b32_e32 v81, 0, v81, vcc
	v_cmp_ne_u32_e32 vcc, v104, v67
	s_nop 1
	v_cndmask_b32_e32 v104, 0, v104, vcc
	v_cmp_ne_u32_e32 vcc, v107, v67
	v_max3_u32 v68, v68, v81, v104
	s_nop 0
	v_cndmask_b32_e32 v107, 0, v107, vcc
	v_cmp_ne_u32_e32 vcc, v105, v67
	s_nop 1
	v_cndmask_b32_e32 v105, 0, v105, vcc
	v_cmp_ne_u32_e32 vcc, v111, v67
	v_max3_u32 v68, v68, v107, v105
	s_nop 0
	v_cndmask_b32_e32 v111, 0, v111, vcc
	v_cmp_ne_u32_e32 vcc, v110, v67
	s_nop 1
	v_cndmask_b32_e32 v110, 0, v110, vcc
	v_max3_u32 v68, v68, v111, v110
	s_nop 1
	v_mov_b32_dpp v117, v68 quad_perm:[1,0,3,2] row_mask:0xf bank_mask:0xf
	s_waitcnt lgkmcnt(0)
	v_max_u32_e32 v68, v68, v117
	s_nop 1
	v_mov_b32_dpp v117, v68 quad_perm:[2,3,0,1] row_mask:0xf bank_mask:0xf
	s_waitcnt lgkmcnt(0)
	v_max_u32_e32 v68, v68, v117
	v_cmp_ne_u32_e32 vcc, v113, v68
	s_nop 1
	v_cndmask_b32_e32 v113, 0, v113, vcc
	v_max_u32_e32 v117, v112, v113
	v_cmp_eq_u32_e32 vcc, v112, v68
	s_nop 1
	v_cndmask_b32_e32 v112, v117, v113, vcc
	v_max_u32_e32 v113, v112, v114
	v_cmp_eq_u32_e32 vcc, v114, v68
	s_nop 1
	v_cndmask_b32_e32 v112, v113, v112, vcc
	v_max_u32_e32 v113, v112, v115
	v_cmp_eq_u32_e32 vcc, v115, v68
	s_nop 1
	v_cndmask_b32_e32 v112, v113, v112, vcc
	v_max_u32_e32 v113, v112, v116
	v_cmp_eq_u32_e32 vcc, v116, v68
	s_nop 1
	v_cndmask_b32_e32 v112, v113, v112, vcc
	v_max_u32_e32 v113, v112, v69
	v_cmp_eq_u32_e32 vcc, v69, v68
	s_nop 1
	v_cndmask_b32_e32 v69, v113, v112, vcc
	v_max_u32_e32 v112, v69, v70
	v_cmp_eq_u32_e32 vcc, v70, v68
	s_nop 1
	v_cndmask_b32_e32 v69, v112, v69, vcc
	v_max_u32_e32 v70, v69, v72
	v_cmp_eq_u32_e32 vcc, v72, v68
	s_nop 1
	v_cndmask_b32_e32 v69, v70, v69, vcc
	v_max_u32_e32 v70, v69, v73
	v_cmp_eq_u32_e32 vcc, v73, v68
	s_nop 1
	v_cndmask_b32_e32 v69, v70, v69, vcc
	v_max_u32_e32 v70, v69, v74
	v_cmp_eq_u32_e32 vcc, v74, v68
	s_nop 1
	v_cndmask_b32_e32 v69, v70, v69, vcc
	v_max_u32_e32 v70, v69, v75
	v_cmp_eq_u32_e32 vcc, v75, v68
	s_nop 1
	v_cndmask_b32_e32 v69, v70, v69, vcc
	v_max_u32_e32 v70, v69, v106
	v_cmp_eq_u32_e32 vcc, v106, v68
	s_nop 1
	v_cndmask_b32_e32 v69, v70, v69, vcc
	v_max_u32_e32 v70, v69, v108
	v_cmp_eq_u32_e32 vcc, v108, v68
	s_nop 1
	v_cndmask_b32_e32 v69, v70, v69, vcc
	v_max_u32_e32 v70, v69, v109
	v_cmp_eq_u32_e32 vcc, v109, v68
	s_nop 1
	v_cndmask_b32_e32 v69, v70, v69, vcc
	v_max_u32_e32 v70, v69, v80
	v_cmp_eq_u32_e32 vcc, v80, v68
	s_nop 1
	v_cndmask_b32_e32 v69, v70, v69, vcc
	v_max_u32_e32 v70, v69, v81
	v_cmp_eq_u32_e32 vcc, v81, v68
	s_nop 1
	v_cndmask_b32_e32 v69, v70, v69, vcc
	v_max_u32_e32 v70, v69, v104
	v_cmp_eq_u32_e32 vcc, v104, v68
	s_nop 1
	v_cndmask_b32_e32 v69, v70, v69, vcc
	v_max_u32_e32 v70, v69, v107
	v_cmp_eq_u32_e32 vcc, v107, v68
	v_bitop3_b32 v107, v63, 15, v63 bitop3:0xc
	v_add_u32_e32 v107, v86, v107
	v_cndmask_b32_e32 v69, v70, v69, vcc
	v_max_u32_e32 v70, v69, v105
	v_cmp_eq_u32_e32 vcc, v105, v68
	v_bitop3_b32 v105, v62, 15, v62 bitop3:0xc
	v_add_u32_e32 v105, v86, v105
	v_cndmask_b32_e32 v69, v70, v69, vcc
	v_max_u32_e32 v70, v69, v111
	v_cmp_eq_u32_e32 vcc, v111, v68
	s_nop 1
	v_cndmask_b32_e32 v69, v70, v69, vcc
	v_max_u32_e32 v70, v69, v110
	v_cmp_eq_u32_e32 vcc, v110, v68
	s_nop 1
	v_cndmask_b32_e32 v69, v70, v69, vcc
	v_cmp_lt_i32_e32 vcc, -1, v59
	s_nop 1
	v_mov_b32_dpp v70, v69 quad_perm:[1,0,3,2] row_mask:0xf bank_mask:0xf
	s_waitcnt lgkmcnt(0)
	v_max_u32_e32 v69, v69, v70
	v_cndmask_b32_e64 v72, v101, -1, vcc
	v_cmp_lt_i32_e32 vcc, -1, v61
	s_nop 1
	v_mov_b32_dpp v70, v69 quad_perm:[2,3,0,1] row_mask:0xf bank_mask:0xf
	v_bitop3_b32 v72, v72, v59, s58 bitop3:0x78
	v_cndmask_b32_e64 v73, v101, -1, vcc
	v_cmp_lt_i32_e32 vcc, -1, v102
	v_bitop3_b32 v73, v73, v61, s58 bitop3:0x78
	s_nop 0
	v_cndmask_b32_e64 v74, v101, -1, vcc
	v_cmp_lt_i32_e32 vcc, -1, v103
	v_bitop3_b32 v74, v74, v102, s58 bitop3:0x78
	s_nop 0
	v_cndmask_b32_e64 v75, v101, -1, vcc
	v_cmp_lt_i32_e32 vcc, -1, v76
	v_bitop3_b32 v75, v75, v103, s58 bitop3:0x78
	s_nop 0
	v_cndmask_b32_e64 v80, v101, -1, vcc
	v_cmp_lt_i32_e32 vcc, -1, v77
	v_bitop3_b32 v80, v80, v76, s58 bitop3:0x78
	s_nop 0
	v_cndmask_b32_e64 v81, v101, -1, vcc
	v_cmp_lt_i32_e32 vcc, -1, v78
	v_bitop3_b32 v81, v81, v77, s58 bitop3:0x78
	s_nop 0
	v_cndmask_b32_e64 v104, v101, -1, vcc
	v_cmp_lt_i32_e32 vcc, -1, v79
	v_bitop3_b32 v112, v104, v78, s58 bitop3:0x78
	s_nop 0
	v_cndmask_b32_e64 v104, v101, -1, vcc
	v_cmp_lt_i32_e32 vcc, -1, v62
	v_bitop3_b32 v113, v104, v79, s58 bitop3:0x78
	v_not_b32_e32 v104, v62
	v_cndmask_b32_e64 v106, v101, -1, vcc
	v_cmp_lt_i32_e32 vcc, -1, v63
	v_bitop3_b32 v62, v106, v62, s58 bitop3:0x78
	v_not_b32_e32 v106, v63
	v_cndmask_b32_e64 v108, v101, -1, vcc
	v_bitop3_b32 v63, v108, v63, s58 bitop3:0x78
	v_not_b32_e32 v108, v64
	v_bfe_u32 v108, v108, 4, 4
	v_add_u32_e32 v114, v86, v108
	v_bitop3_b32 v108, v64, 15, v64 bitop3:0xc
	v_cmp_lt_i32_e32 vcc, -1, v64
	v_add_u32_e32 v115, v86, v108
	v_bfe_u32 v104, v104, 4, 4
	v_cndmask_b32_e64 v108, v101, -1, vcc
	v_bitop3_b32 v64, v108, v64, s58 bitop3:0x78
	v_not_b32_e32 v108, v65
	v_bfe_u32 v106, v106, 4, 4
	v_bfe_u32 v108, v108, 4, 4
	v_add_u32_e32 v104, v86, v104
	v_add_u32_e32 v106, v86, v106
	v_add_u32_e32 v116, v86, v108
	v_bitop3_b32 v108, v65, 15, v65 bitop3:0xc
	v_cmp_lt_i32_e32 vcc, -1, v65
	v_add_u32_e32 v117, v86, v108
	ds_read_u8 v110, v104
	ds_read_u8 v111, v105 offset:16
	ds_read_u8 v108, v106
	ds_read_u8 v109, v107 offset:16
	ds_read_u8 v106, v114
	ds_read_u8 v107, v115 offset:16
	ds_read_u8 v104, v116
	ds_read_u8 v105, v117 offset:16
	v_cndmask_b32_e64 v114, v101, -1, vcc
	v_cmp_lt_i32_e32 vcc, -1, v66
	v_bitop3_b32 v65, v114, v65, s58 bitop3:0x78
	v_not_b32_e32 v114, v66
	v_cndmask_b32_e64 v116, v101, -1, vcc
	v_bitop3_b32 v115, v66, 15, v66 bitop3:0xc
	v_bitop3_b32 v116, v116, v66, s58 bitop3:0x78
	v_not_b32_e32 v66, v67
	v_bfe_u32 v66, v66, 4, 4
	v_add_u32_e32 v117, v86, v66
	v_bitop3_b32 v66, v67, 15, v67 bitop3:0xc
	v_cmp_lt_i32_e32 vcc, -1, v67
	v_add_u32_e32 v127, v86, v66
	v_sub_f32_e32 v62, v62, v72
	v_cndmask_b32_e64 v66, v101, -1, vcc
	v_bitop3_b32 v118, v66, v67, s58 bitop3:0x78
	v_not_b32_e32 v66, v68
	v_bfe_u32 v66, v66, 4, 4
	v_add_u32_e32 v128, v86, v66
	v_bitop3_b32 v66, v68, 15, v68 bitop3:0xc
	v_cmp_lt_i32_e32 vcc, -1, v68
	v_add_u32_e32 v129, v86, v66
	v_mul_f32_e32 v62, 0x3fb8aa3b, v62
	v_cndmask_b32_e64 v66, v101, -1, vcc
	v_bitop3_b32 v119, v66, v68, s58 bitop3:0x78
	s_waitcnt lgkmcnt(8)
	v_max_u32_e32 v66, v69, v70
	v_not_b32_e32 v67, v66
	v_bfe_u32 v67, v67, 4, 4
	v_add_u32_e32 v70, v86, v67
	v_bitop3_b32 v67, v66, 15, v66 bitop3:0xc
	v_cmp_lt_i32_e32 vcc, -1, v66
	v_add_u32_e32 v130, v86, v67
	v_bfe_u32 v114, v114, 4, 4
	v_cndmask_b32_e64 v67, v101, -1, vcc
	v_bitop3_b32 v131, v67, v66, s58 bitop3:0x78
	v_sub_f32_e32 v66, v72, v72
	v_mul_f32_e32 v66, 0x3fb8aa3b, v66
	v_exp_f32_e32 v124, v66
	v_sub_f32_e32 v66, v73, v72
	v_mul_f32_e32 v66, 0x3fb8aa3b, v66
	v_exp_f32_e32 v123, v66
	v_sub_f32_e32 v66, v74, v72
	v_sub_f32_e32 v67, v80, v72
	v_mul_f32_e32 v66, 0x3fb8aa3b, v66
	v_mul_f32_e32 v67, 0x3fb8aa3b, v67
	v_exp_f32_e32 v125, v66
	v_sub_f32_e32 v66, v75, v72
	v_exp_f32_e32 v80, v67
	v_sub_f32_e32 v67, v81, v72
	v_mul_f32_e32 v66, 0x3fb8aa3b, v66
	v_mul_f32_e32 v67, 0x3fb8aa3b, v67
	v_exp_f32_e32 v126, v66
	v_exp_f32_e32 v120, v67
	v_sub_f32_e32 v67, v112, v72
	v_add_f32_e32 v66, 0, v124
	v_mul_f32_e32 v67, 0x3fb8aa3b, v67
	v_add_f32_e32 v66, v66, v123
	v_exp_f32_e32 v121, v67
	v_sub_f32_e32 v67, v113, v72
	v_add_f32_e32 v66, v66, v125
	v_mul_f32_e32 v67, 0x3fb8aa3b, v67
	v_add_f32_e32 v66, v66, v126
	v_exp_f32_e32 v122, v67
	v_add_f32_e32 v66, v66, v80
	v_add_f32_e32 v66, v66, v120
	v_add_f32_e32 v66, v66, v121
	v_add_f32_e32 v73, v66, v122
	v_exp_f32_e32 v66, v62
	v_sub_f32_e32 v62, v63, v72
	v_mul_f32_e32 v62, 0x3fb8aa3b, v62
	v_exp_f32_e32 v67, v62
	v_sub_f32_e32 v62, v64, v72
	v_mul_f32_e32 v62, 0x3fb8aa3b, v62
	v_exp_f32_e32 v68, v62
	v_sub_f32_e32 v62, v65, v72
	v_mul_f32_e32 v62, 0x3fb8aa3b, v62
	v_exp_f32_e32 v69, v62
	v_add_f32_e32 v62, v73, v66
	v_add_f32_e32 v62, v62, v67
	v_add_f32_e32 v62, v62, v68
	v_add_f32_e32 v73, v62, v69
	v_sub_f32_e32 v62, v116, v72
	v_mul_f32_e32 v62, 0x3fb8aa3b, v62
	v_sub_f32_e32 v63, v118, v72
	v_exp_f32_e32 v62, v62
	v_mul_f32_e32 v63, 0x3fb8aa3b, v63
	v_sub_f32_e32 v64, v119, v72
	v_exp_f32_e32 v63, v63
	v_mul_f32_e32 v64, 0x3fb8aa3b, v64
	v_sub_f32_e32 v65, v131, v72
	v_exp_f32_e32 v64, v64
	v_mul_f32_e32 v65, 0x3fb8aa3b, v65
	v_exp_f32_e32 v65, v65
	v_add_f32_e32 v72, v73, v62
	v_add_f32_e32 v72, v72, v63
	v_add_f32_e32 v72, v72, v64
	v_add_f32_e32 v73, v72, v65
	v_div_scale_f32 v74, s[28:29], v73, v73, 1.0
	v_rcp_f32_e32 v75, v74
	v_add_u32_e32 v114, v86, v114
	v_add_u32_e32 v115, v86, v115
	ds_read_u8 v118, v114
	ds_read_u8 v119, v115 offset:16
	ds_read_u8 v116, v117
	ds_read_u8 v117, v127 offset:16
	ds_read_u8 v114, v128
	ds_read_u8 v115, v129 offset:16
	ds_read_u8 v112, v70
	ds_read_u8 v113, v130 offset:16
	v_fma_f32 v70, -v74, v75, 1.0
	v_fmac_f32_e32 v75, v70, v75
	v_div_scale_f32 v70, vcc, 1.0, v73, 1.0
	v_mul_f32_e32 v81, v70, v75
	v_fma_f32 v127, -v74, v81, v70
	v_fmac_f32_e32 v81, v127, v75
	v_fma_f32 v70, -v74, v81, v70
	v_add_u32_e32 v72, s34, v82
	v_div_fmas_f32 v70, v70, v75, v81
	v_div_fixup_f32 v70, v70, v73, 1.0
	v_ashrrev_i32_e32 v73, 31, v72
	v_lshlrev_b64 v[72:73], 9, v[72:73]
	v_lshl_add_u64 v[74:75], s[20:21], 0, v[72:73]
	v_lshl_add_u64 v[72:73], s[22:23], 0, v[72:73]
	v_lshl_add_u64 v[74:75], v[74:75], 0, s[24:25]
	v_lshl_add_u64 v[72:73], v[72:73], 0, s[24:25]
	v_cmp_lt_i32_e32 vcc, 0, v83
	s_mov_b64 s[28:29], 0
	s_and_saveexec_b64 s[30:31], vcc
	s_xor_b64 s[30:31], exec, s[30:31]
	s_cbranch_execz .LBB0_847
	v_cmp_eq_u32_e32 vcc, 1, v83
	s_and_saveexec_b64 s[34:35], vcc
	s_cbranch_execz .LBB0_846
	v_not_b32_e32 v59, v79
	v_not_b32_e32 v81, v77
	v_not_b32_e32 v102, v76
	v_bfe_u32 v59, v59, 4, 4
	v_bitop3_b32 v61, v79, 15, v79 bitop3:0xc
	v_not_b32_e32 v79, v78
	v_bitop3_b32 v78, v78, 15, v78 bitop3:0xc
	v_bfe_u32 v81, v81, 4, 4
	v_bitop3_b32 v77, v77, 15, v77 bitop3:0xc
	v_bfe_u32 v102, v102, 4, 4
	v_bitop3_b32 v76, v76, 15, v76 bitop3:0xc
	v_add_u32_e32 v59, v86, v59
	v_add_u32_e32 v61, v86, v61
	v_bfe_u32 v79, v79, 4, 4
	v_add_u32_e32 v78, v86, v78
	v_add_u32_e32 v81, v86, v81
	v_add_u32_e32 v77, v86, v77
	v_add_u32_e32 v102, v86, v102
	v_add_u32_e32 v76, v86, v76
	v_add_u32_e32 v79, v86, v79
	ds_read_u8 v59, v59
	ds_read_u8 v61, v61 offset:16
	ds_read_u8 v103, v79
	ds_read_u8 v78, v78 offset:16
	ds_read_u8 v81, v81
	ds_read_u8 v77, v77 offset:16
	ds_read_u8 v102, v102
	ds_read_u8 v76, v76 offset:16
	s_waitcnt lgkmcnt(6)
	v_lshl_add_u32 v79, v59, 7, v61
	s_waitcnt lgkmcnt(4)
	v_lshl_add_u32 v78, v103, 7, v78
	s_waitcnt lgkmcnt(2)
	v_lshl_add_u32 v77, v81, 7, v77
	v_mul_f32_e32 v59, v80, v70
	s_waitcnt lgkmcnt(0)
	v_lshl_add_u32 v76, v102, 7, v76
	s_mov_b64 s[28:29], exec
	global_store_dwordx4 v[74:75], v[76:79], off offset:16
	global_store_dword v[72:73], v59, off offset:16
